# adds: P5/P9 residual epilogues rewritten (all loads up front, counted waits, atomics last) in plain/write-through twin form; P4 gate section loads hoisted; XCC table check latency hidden behind P5 K-l
# speedup vs baseline: 1.0170x; 1.0026x over previous
; #define LAS __attribute__((address_space(3)))
; __device__ __forceinline__ float log_sigmoid(float x) { return -log1pf(expf(-x)); }
; __device__ __forceinline__ void ret_unit(LAS unsigned char* lds, int u, const bf16* PROJ, const int* pos, const float* dec_f, const float* dec_b, const bf16* ST,
;                                          const float* gn_w, const float* gn_b, bf16* MIX, int tid, const WsRef& wsr) {
;     ...
;     const int bh = u >> 6, c = u & 63, b = bh >> 2, h = bh & 3;
;     const size_t row0 = (size_t)b * SEQ + (size_t)c * 128;
;     LAS bf16* Qs = (LAS bf16*)lds; LAS bf16* Ks = (LAS bf16*)(lds + TILE_B); LAS bf16* VT = (LAS bf16*)(lds + 2 * TILE_B);
;     const float lgf2 = log_sigmoid(dec_f[h]) * LOG2E, lgb2 = log_sigmoid(dec_b[h]) * LOG2E;
.LBB0_438:
	s_ashr_i32 s0, s73, 6
	s_and_b32 s80, s0, 3
	s_lshl_b32 s1, s80, 2
	v_mov_b32_e32 v16, s1
	global_load_dword v0, v16, s[18:19]
	s_mov_b32 s1, 0x42ce8ed0
	s_mov_b32 s83, 0xc2b17218
	s_mov_b32 s11, 0x3f2aaaab
	s_mov_b32 s88, 0x7f800000
	s_mov_b32 s8, 0x33800000
	s_and_b32 s82, s73, 63
	s_ashr_i32 s4, s73, 8
	s_ashr_i32 s5, s4, 31
	s_lshl_b32 s81, s82, 7
	s_waitcnt vmcnt(0)
	v_mul_f32_e32 v1, 0xbfb8aa3b, v0
	v_fma_f32 v2, v0, s41, -v1
	v_rndne_f32_e32 v3, v1
	v_fmac_f32_e32 v2, 0xb2a5705f, v0
	v_sub_f32_e32 v1, v1, v3
	v_add_f32_e32 v1, v1, v2
	v_exp_f32_e32 v1, v1
	v_cvt_i32_f32_e32 v2, v3
	v_cmp_nlt_f32_e64 s[68:69], s1, v0
	v_ldexp_f32 v1, v1, v2
	s_nop 0
	v_cndmask_b32_e64 v1, 0, v1, s[68:69]
	v_cmp_ngt_f32_e64 s[68:69], s83, v0
	s_nop 1
	v_cndmask_b32_e64 v17, v228, v1, s[68:69]
	v_add_f32_e32 v2, 1.0, v17
	v_add_f32_e32 v0, -1.0, v2
	v_sub_f32_e32 v1, v0, v2
	v_add_f32_e32 v1, 1.0, v1
	v_sub_f32_e32 v0, v17, v0
	v_add_f32_e32 v3, v0, v1
	v_frexp_mant_f32_e32 v0, v2
	v_cmp_gt_f32_e64 s[68:69], s11, v0
	v_cvt_f64_f32_e32 v[0:1], v2
	v_frexp_exp_i32_f64_e32 v0, v[0:1]
	v_subbrev_co_u32_e64 v8, s[68:69], 0, v0, s[68:69]
	v_sub_u32_e32 v0, 0, v8
	v_ldexp_f32 v1, v2, v0
	v_add_f32_e32 v2, -1.0, v1
	v_add_f32_e32 v4, 1.0, v1
	v_ldexp_f32 v0, v3, v0
	v_add_f32_e32 v3, 1.0, v2
	v_add_f32_e32 v5, -1.0, v4
	v_sub_f32_e32 v3, v1, v3
	v_sub_f32_e32 v1, v1, v5
	v_add_f32_e32 v3, v0, v3
	v_add_f32_e32 v0, v0, v1
	v_add_f32_e32 v9, v4, v0
	v_rcp_f32_e32 v11, v9
	v_sub_f32_e32 v1, v4, v9
	v_add_f32_e32 v10, v0, v1
	v_add_f32_e32 v1, v2, v3
	v_mul_f32_e32 v13, v1, v11
	v_sub_f32_e32 v0, v2, v1
	v_mul_f32_e32 v2, v9, v13
	v_fma_f32 v4, v13, v9, -v2
	v_fmac_f32_e32 v4, v13, v10
	v_add_f32_e32 v12, v3, v0
	v_add_f32_e32 v0, v2, v4
	v_sub_f32_e32 v3, v1, v0
	v_pk_add_f32 v[6:7], v[0:1], v[2:3] neg_lo:[0,1] neg_hi:[0,1]
	v_mov_b32_e32 v5, v0
	v_pk_add_f32 v[0:1], v[6:7], v[4:5] neg_lo:[0,1] neg_hi:[0,1]
	v_cmp_neq_f32_e64 s[68:69], s88, v17
	v_add_f32_e32 v1, v12, v1
	v_add_f32_e32 v0, v0, v1
	v_add_f32_e32 v1, v3, v0
	v_mul_f32_e32 v12, v11, v1
	v_mul_f32_e32 v2, v9, v12
	v_fma_f32 v4, v12, v9, -v2
	v_fmac_f32_e32 v4, v12, v10
	v_sub_f32_e32 v3, v3, v1
	v_add_f32_e32 v9, v0, v3
	v_add_f32_e32 v0, v2, v4
	v_sub_f32_e32 v3, v1, v0
	v_pk_add_f32 v[6:7], v[0:1], v[2:3] neg_lo:[0,1] neg_hi:[0,1]
	v_mov_b32_e32 v5, v0
	v_pk_add_f32 v[0:1], v[6:7], v[4:5] neg_lo:[0,1] neg_hi:[0,1]
	s_nop 0
	v_add_f32_e32 v1, v9, v1
	v_add_f32_e32 v0, v0, v1
	v_add_f32_e32 v1, v13, v12
	v_add_f32_e32 v0, v3, v0
	v_sub_f32_e32 v2, v1, v13
	v_mul_f32_e32 v0, v11, v0
	v_sub_f32_e32 v2, v12, v2
	v_add_f32_e32 v2, v2, v0
	v_add_f32_e32 v4, v1, v2
	v_mul_f32_e32 v5, v4, v4
	v_fmamk_f32 v0, v5, 0x3e9b6dac, v223
	v_fmaak_f32 v105, v5, v0, 0x3f2aaada
	v_cvt_f32_i32_e32 v0, v8
	v_sub_f32_e32 v1, v4, v1
	v_sub_f32_e32 v1, v2, v1
	v_ldexp_f32 v6, v1, 1
	v_mul_f32_e32 v1, v4, v5
	v_ldexp_f32 v3, v4, 1
	v_pk_mul_f32 v[4:5], v[0:1], v[104:105]
	s_nop 0
	v_fma_f32 v2, v0, s33, -v4
	v_fmac_f32_e32 v2, 0xb102e308, v0
	v_pk_add_f32 v[0:1], v[4:5], v[2:3]
	s_nop 0
	v_sub_f32_e32 v3, v1, v3
	v_sub_f32_e32 v3, v5, v3
	v_add_f32_e32 v7, v6, v3
	v_mov_b32_e32 v6, v4
	v_pk_add_f32 v[4:5], v[0:1], v[4:5] neg_lo:[0,1] neg_hi:[0,1]
	v_pk_add_f32 v[8:9], v[0:1], v[6:7]
	v_mov_b32_e32 v3, v0
	v_mov_b32_e32 v5, v9
	v_pk_add_f32 v[10:11], v[2:3], v[4:5] neg_lo:[0,1] neg_hi:[0,1]
	v_pk_add_f32 v[2:3], v[2:3], v[4:5]
	v_mov_b32_e32 v14, v1
	v_pk_add_f32 v[4:5], v[2:3], v[0:1] op_sel:[1,0] op_sel_hi:[0,1] neg_lo:[0,1] neg_hi:[0,1]
	v_pk_add_f32 v[12:13], v[8:9], v[4:5] op_sel_hi:[1,0] neg_lo:[0,1] neg_hi:[0,1]
	v_mov_b32_e32 v8, v9
	v_mov_b32_e32 v9, v3
	v_mov_b32_e32 v15, v4
	v_pk_add_f32 v[4:5], v[8:9], v[14:15] neg_lo:[0,1] neg_hi:[0,1]
	v_mov_b32_e32 v6, v7
	v_mov_b32_e32 v7, v0
	v_pk_add_f32 v[0:1], v[6:7], v[4:5] neg_lo:[0,1] neg_hi:[0,1]
	v_mov_b32_e32 v12, v10
	v_pk_add_f32 v[4:5], v[12:13], v[0:1]
	v_mov_b32_e32 v11, v3
	v_pk_add_f32 v[6:7], v[4:5], v[4:5] op_sel:[0,1] op_sel_hi:[1,0]
	s_nop 0
	v_pk_add_f32 v[2:3], v[2:3], v[6:7] op_sel:[1,0] op_sel_hi:[0,1]
	v_mov_b32_e32 v5, v2
	v_pk_add_f32 v[8:9], v[4:5], v[10:11] neg_lo:[0,1] neg_hi:[0,1]
	v_mov_b32_e32 v1, v6
	v_sub_f32_e32 v3, v4, v8
	v_pk_add_f32 v[0:1], v[0:1], v[8:9] neg_lo:[0,1] neg_hi:[0,1]
	v_sub_f32_e32 v3, v10, v3
	v_add_f32_e32 v0, v0, v3
	v_add_f32_e32 v0, v0, v1
	global_load_dword v1, v16, s[20:21]
	v_add_f32_e32 v0, v2, v0
	v_cndmask_b32_e64 v0, v228, v0, s[68:69]
	v_cmp_lt_f32_e64 s[68:69], |v17|, s8
	s_waitcnt vmcnt(0)
; __device__ __forceinline__ u32x4 ws_load16(const WsRef& w, unsigned byte_off) { return __builtin_bit_cast(u32x4, __builtin_amdgcn_raw_buffer_load_b128(w.r, byte_off, 0, 0)); }
; __device__ __forceinline__ float log_sigmoid(float x) { return -log1pf(expf(-x)); }
; __device__ __forceinline__ void ret_unit(LAS unsigned char* lds, int u, const bf16* PROJ, const int* pos, const float* dec_f, const float* dec_b, const bf16* ST,
;                                          const float* gn_w, const float* gn_b, bf16* MIX, int tid, const WsRef& wsr) {
;     ...
;     const float lgf2 = log_sigmoid(dec_f[h]) * LOG2E, lgb2 = log_sigmoid(dec_b[h]) * LOG2E;
;     const u32x4* sfp = (const u32x4*)(ST + ((size_t)bh * 64 + c) * 16384); const u32x4* sbp = (const u32x4*)(ST + ((size_t)(8 + bh) * 64 + c) * 16384);
;     u32x4 sf[4], sb[4];
; #pragma unroll
;     for (int i = 0; i < 4; ++i) { sf[i] = sfp[tid + 512 * i]; sb[i] = sbp[tid + 512 * i]; }
;     u32x4 rq1[2], rq2[2], rk1[2], rk2[2], rv[4]; float rp[2];
; #pragma unroll
;     for (int ii = 0; ii < 2; ++ii) { const int it = tid + 512 * ii, dc = it & 7, j = it >> 3; const unsigned qo = (unsigned)WS_PROJ + (unsigned)(((unsigned)(row0 + j) * INC + h * 128 + dc * 8) * 2u);
;         rq1[ii] = ws_load16(wsr, qo); rq2[ii] = ws_load16(wsr, qo + 128u); rk1[ii] = ws_load16(wsr, qo + 1024u); rk2[ii] = ws_load16(wsr, qo + 1152u); rp[ii] = (float)pos[row0 + j]; }
	v_mul_f32_e32 v2, 0xbfb8aa3b, v1
	v_fma_f32 v3, v1, s41, -v2
	v_rndne_f32_e32 v4, v2
	v_fmac_f32_e32 v3, 0xb2a5705f, v1
	v_sub_f32_e32 v2, v2, v4
	v_add_f32_e32 v2, v2, v3
	v_exp_f32_e32 v2, v2
	v_cvt_i32_f32_e32 v3, v4
	v_cndmask_b32_e64 v0, v0, v17, s[68:69]
	v_cmp_nlt_f32_e64 s[68:69], s1, v1
	s_ashr_i32 s1, s0, 31
	v_ldexp_f32 v2, v2, v3
	v_cndmask_b32_e64 v2, 0, v2, s[68:69]
	v_cmp_ngt_f32_e64 s[68:69], s83, v1
	s_lshl_b64 s[0:1], s[0:1], 21
	s_add_u32 s0, s54, s0
	v_cndmask_b32_e64 v1, v228, v2, s[68:69]
	v_add_f32_e32 v4, 1.0, v1
	v_add_f32_e32 v2, -1.0, v4
	v_sub_f32_e32 v3, v2, v4
	v_add_f32_e32 v3, 1.0, v3
	v_sub_f32_e32 v2, v1, v2
	v_add_f32_e32 v5, v2, v3
	v_frexp_mant_f32_e32 v2, v4
	v_cmp_gt_f32_e64 s[68:69], s11, v2
	v_cvt_f64_f32_e32 v[2:3], v4
	v_frexp_exp_i32_f64_e32 v2, v[2:3]
	v_subbrev_co_u32_e64 v10, s[68:69], 0, v2, s[68:69]
	v_sub_u32_e32 v2, 0, v10
	v_ldexp_f32 v3, v4, v2
	v_add_f32_e32 v4, -1.0, v3
	v_add_f32_e32 v6, 1.0, v3
	v_ldexp_f32 v2, v5, v2
	v_add_f32_e32 v5, 1.0, v4
	v_add_f32_e32 v7, -1.0, v6
	v_sub_f32_e32 v5, v3, v5
	v_sub_f32_e32 v3, v3, v7
	v_add_f32_e32 v5, v2, v5
	v_add_f32_e32 v2, v2, v3
	v_add_f32_e32 v11, v6, v2
	v_rcp_f32_e32 v13, v11
	v_sub_f32_e32 v3, v6, v11
	v_add_f32_e32 v12, v2, v3
	v_add_f32_e32 v3, v4, v5
	v_mul_f32_e32 v15, v3, v13
	v_sub_f32_e32 v2, v4, v3
	v_mul_f32_e32 v4, v11, v15
	v_fma_f32 v6, v15, v11, -v4
	v_fmac_f32_e32 v6, v15, v12
	v_add_f32_e32 v14, v5, v2
	v_add_f32_e32 v2, v4, v6
	v_sub_f32_e32 v5, v3, v2
	v_pk_add_f32 v[8:9], v[2:3], v[4:5] neg_lo:[0,1] neg_hi:[0,1]
	v_mov_b32_e32 v7, v2
	v_pk_add_f32 v[2:3], v[8:9], v[6:7] neg_lo:[0,1] neg_hi:[0,1]
	v_cmp_neq_f32_e64 s[68:69], s88, v1
	v_add_f32_e32 v3, v14, v3
	v_add_f32_e32 v2, v2, v3
	v_add_f32_e32 v3, v5, v2
	v_mul_f32_e32 v14, v13, v3
	v_mul_f32_e32 v4, v11, v14
	v_fma_f32 v6, v14, v11, -v4
	v_fmac_f32_e32 v6, v14, v12
	v_sub_f32_e32 v5, v5, v3
	v_add_f32_e32 v11, v2, v5
	v_add_f32_e32 v2, v4, v6
	v_sub_f32_e32 v5, v3, v2
	v_pk_add_f32 v[8:9], v[2:3], v[4:5] neg_lo:[0,1] neg_hi:[0,1]
	v_mov_b32_e32 v7, v2
	v_pk_add_f32 v[2:3], v[8:9], v[6:7] neg_lo:[0,1] neg_hi:[0,1]
	s_addc_u32 s1, s55, s1
	v_add_f32_e32 v3, v11, v3
	v_add_f32_e32 v2, v2, v3
	v_add_f32_e32 v3, v15, v14
	v_add_f32_e32 v2, v5, v2
	v_sub_f32_e32 v4, v3, v15
	v_mul_f32_e32 v2, v13, v2
	v_sub_f32_e32 v4, v14, v4
	v_add_f32_e32 v4, v4, v2
	v_add_f32_e32 v6, v3, v4
	v_mul_f32_e32 v7, v6, v6
	v_fmamk_f32 v2, v7, 0x3e9b6dac, v223
	v_fmaak_f32 v105, v7, v2, 0x3f2aaada
	v_cvt_f32_i32_e32 v2, v10
	v_sub_f32_e32 v3, v6, v3
	v_sub_f32_e32 v3, v4, v3
	v_ldexp_f32 v8, v3, 1
	v_mul_f32_e32 v3, v6, v7
	v_ldexp_f32 v5, v6, 1
	v_pk_mul_f32 v[6:7], v[2:3], v[104:105]
	v_mul_f32_e32 v105, 0xbfb8aa3b, v0
	v_fma_f32 v4, v2, s33, -v6
	v_fmac_f32_e32 v4, 0xb102e308, v2
	v_pk_add_f32 v[2:3], v[6:7], v[4:5]
	s_mov_b32 s88, s84
	v_sub_f32_e32 v5, v3, v5
	v_sub_f32_e32 v5, v7, v5
	v_add_f32_e32 v9, v8, v5
	v_mov_b32_e32 v8, v6
	v_pk_add_f32 v[6:7], v[2:3], v[6:7] neg_lo:[0,1] neg_hi:[0,1]
	v_pk_add_f32 v[10:11], v[2:3], v[8:9]
	v_mov_b32_e32 v5, v2
	v_mov_b32_e32 v7, v11
	v_pk_add_f32 v[12:13], v[4:5], v[6:7] neg_lo:[0,1] neg_hi:[0,1]
	v_pk_add_f32 v[4:5], v[4:5], v[6:7]
	v_mov_b32_e32 v16, v3
	v_pk_add_f32 v[6:7], v[4:5], v[2:3] op_sel:[1,0] op_sel_hi:[0,1] neg_lo:[0,1] neg_hi:[0,1]
	v_pk_add_f32 v[14:15], v[10:11], v[6:7] op_sel_hi:[1,0] neg_lo:[0,1] neg_hi:[0,1]
	v_mov_b32_e32 v10, v11
	v_mov_b32_e32 v11, v5
	v_mov_b32_e32 v17, v6
	v_pk_add_f32 v[6:7], v[10:11], v[16:17] neg_lo:[0,1] neg_hi:[0,1]
	v_mov_b32_e32 v8, v9
	v_mov_b32_e32 v9, v2
	v_pk_add_f32 v[2:3], v[8:9], v[6:7] neg_lo:[0,1] neg_hi:[0,1]
	v_mov_b32_e32 v14, v12
	v_pk_add_f32 v[6:7], v[14:15], v[2:3]
	v_mov_b32_e32 v13, v5
	v_pk_add_f32 v[8:9], v[6:7], v[6:7] op_sel:[0,1] op_sel_hi:[1,0]
	s_nop 0
	v_pk_add_f32 v[4:5], v[4:5], v[8:9] op_sel:[1,0] op_sel_hi:[0,1]
	v_mov_b32_e32 v7, v4
	v_pk_add_f32 v[10:11], v[6:7], v[12:13] neg_lo:[0,1] neg_hi:[0,1]
	v_mov_b32_e32 v3, v8
	v_sub_f32_e32 v5, v6, v10
	v_pk_add_f32 v[2:3], v[2:3], v[10:11] neg_lo:[0,1] neg_hi:[0,1]
	v_sub_f32_e32 v5, v12, v5
	v_add_f32_e32 v2, v2, v5
	v_add_f32_e32 v2, v2, v3
	v_add_f32_e32 v2, v4, v2
	v_cndmask_b32_e64 v2, v228, v2, s[68:69]
	v_cmp_lt_f32_e64 s[68:69], |v1|, s8
	s_movk_i32 s8, 0x2000
	s_nop 0
	v_cndmask_b32_e64 v48, v2, v1, s[68:69]
	s_lshl_b32 s68, s82, 15
	s_add_u32 s0, s0, s68
	s_addc_u32 s1, s1, 0
	s_add_u32 s82, s0, 0x1000000
	v_lshl_add_u64 v[2:3], s[0:1], 0, v[96:97]
	s_addc_u32 s83, s1, 0
	v_add_co_u32_e64 v8, s[68:69], s8, v2
	v_lshl_add_u64 v[28:29], s[82:83], 0, v[96:97]
	s_nop 0
	v_addc_co_u32_e64 v9, s[68:69], 0, v3, s[68:69]
	v_add_co_u32_e64 v16, s[68:69], s8, v28
	global_load_dwordx4 v[4:7], v96, s[0:1]
	global_load_dwordx4 v[12:15], v96, s[82:83]
	v_addc_co_u32_e64 v17, s[68:69], 0, v29, s[68:69]
	global_load_dwordx4 v[8:11], v[8:9], off
	s_nop 0
	global_load_dwordx4 v[16:19], v[16:17], off
	s_nop 0
	global_load_dwordx4 v[24:27], v224, s[0:1]
	global_load_dwordx4 v[20:23], v224, s[82:83]
	s_movk_i32 s0, 0x6000
	v_add_co_u32_e64 v2, s[68:69], s0, v2
	s_lshl_b64 s[4:5], s[4:5], 13
	s_nop 0
	v_addc_co_u32_e64 v3, s[68:69], 0, v3, s[68:69]
	global_load_dwordx4 v[32:35], v[2:3], off
	v_add_co_u32_e64 v2, s[68:69], s0, v28
	s_or_b32 s4, s4, s81
	s_nop 0
	v_addc_co_u32_e64 v3, s[68:69], 0, v29, s[68:69]
	s_lshl_b32 s0, s80, 7
	v_or_b32_e32 v0, s4, v98
	global_load_dwordx4 v[36:39], v[2:3], off
	v_or_b32_e32 v2, s0, v106
	v_mul_lo_u32 v3, v0, s9
	v_mov_b32_e32 v1, s5
	v_or_b32_e32 v3, v3, v2
	v_lshl_add_u32 v3, v3, 1, v229
	v_lshl_add_u64 v[0:1], v[0:1], 2, s[12:13]
	buffer_load_dwordx4 v[50:53], v3, s[88:91], 0 offen
; __device__ __forceinline__ u32x4 ws_load16(const WsRef& w, unsigned byte_off) { return __builtin_bit_cast(u32x4, __builtin_amdgcn_raw_buffer_load_b128(w.r, byte_off, 0, 0)); }
; __device__ __forceinline__ float fexp2(float x) { return __builtin_amdgcn_exp2f(x); }
; __device__ __forceinline__ void ret_unit(LAS unsigned char* lds, int u, const bf16* PROJ, const int* pos, const float* dec_f, const float* dec_b, const bf16* ST,
;                                          const float* gn_w, const float* gn_b, bf16* MIX, int tid, const WsRef& wsr) {
;     ...
;     for (int ii = 0; ii < 2; ++ii) { const int it = tid + 512 * ii, dc = it & 7, j = it >> 3; const unsigned qo = (unsigned)WS_PROJ + (unsigned)(((unsigned)(row0 + j) * INC + h * 128 + dc * 8) * 2u);
;         rq1[ii] = ws_load16(wsr, qo); rq2[ii] = ws_load16(wsr, qo + 128u); rk1[ii] = ws_load16(wsr, qo + 1024u); rk2[ii] = ws_load16(wsr, qo + 1152u); rp[ii] = (float)pos[row0 + j]; }
; #pragma unroll
;     for (int ii = 0; ii < 2; ++ii) { const int it = tid + 512 * ii, dc = it & 7, j = it >> 3;
;         const u32x4 q1 = rq1[ii], q2 = rq2[ii], k1 = rk1[ii], k2 = rk2[ii];
;         const float p = rp[ii];
;         float sn[8], cs[8];
; #pragma unroll
;         for (int e = 0; e < 8; ++e) { const int i = dc * 8 + e; const float inv = fexp2(-(float)i * 0.20762050593046015f); fast_sincos(p * inv, sn[e], cs[e]); }
;     ...
;         for (int r = 0; r < 4; ++r) { const int key = n * 16 + 4 * fq + r; const int df = q - key; const float f = df >= 0 ? fexp2(lgf2 * (float)df) : fexp2(lgb2 * (float)(-df)); s[n][r] *= f; } }
	buffer_load_dwordx4 v[54:57], v3, s[88:91], 0 offen offset:128
	buffer_load_dwordx4 v[58:61], v3, s[88:91], 0 offen offset:1024
	buffer_load_dwordx4 v[62:65], v3, s[88:91], 0 offen offset:1152
	v_lshl_add_u64 v[66:67], s[4:5], 0, v[100:101]
	global_load_dword v0, v[0:1], off
	v_mul_f32_e32 v230, 0xbfb8aa3b, v48
	v_cndmask_b32_e64 v89, v105, v230, s[30:31]
	v_cndmask_b32_e64 v94, v105, v230, s[56:57]
	v_cndmask_b32_e64 v95, v105, v230, s[58:59]
	v_mul_f32_e32 v89, v89, v137
	v_cndmask_b32_e64 v92, v105, v230, s[74:75]
	v_cndmask_b32_e64 v93, v105, v230, s[76:77]
	v_mul_f32_e32 v94, v94, v142
	v_mul_f32_e32 v95, v95, v143
	v_exp_f32_e32 v89, v89
	v_mul_f32_e32 v92, v92, v140
	v_mul_f32_e32 v93, v93, v141
	v_exp_f32_e32 v94, v94
	v_exp_f32_e32 v95, v95
	v_exp_f32_e32 v92, v92
	v_exp_f32_e32 v93, v93
	v_cndmask_b32_e64 v130, v105, v230, s[60:61]
	v_cndmask_b32_e64 v131, v105, v230, s[62:63]
	v_cndmask_b32_e64 v48, v105, v230, s[42:43]
	v_mul_f32_e32 v130, v130, v144
	v_mul_f32_e32 v131, v131, v145
	v_mul_f32_e32 v48, v48, v127
	v_exp_f32_e32 v130, v130
	v_exp_f32_e32 v131, v131
	v_exp_f32_e32 v48, v48
	v_cndmask_b32_e64 v90, v105, v230, s[34:35]
	v_cndmask_b32_e64 v91, v105, v230, s[38:39]
	v_mul_f32_e32 v90, v90, v138
	v_mul_f32_e32 v91, v91, v139
	v_exp_f32_e32 v90, v90
	v_exp_f32_e32 v91, v91
	v_cndmask_b32_e64 v238, v105, v230, s[94:95]
	v_mul_f32_e32 v238, v238, v154
	v_exp_f32_e32 v238, v238
	v_cndmask_b32_e64 v234, v105, v230, s[78:79]
	v_cndmask_b32_e64 v235, v105, v230, s[2:3]
	v_cndmask_b32_e64 v236, v105, v230, s[92:93]
	v_cndmask_b32_e32 v237, v105, v230, vcc
	v_mul_f32_e32 v234, v234, v150
	v_mul_f32_e32 v235, v235, v151
	v_mul_f32_e32 v236, v236, v152
	v_mul_f32_e32 v237, v237, v153
	v_exp_f32_e32 v234, v234
	v_exp_f32_e32 v235, v235
	v_exp_f32_e32 v236, v236
	v_exp_f32_e32 v237, v237
	v_cndmask_b32_e64 v132, v105, v230, s[64:65]
	v_cndmask_b32_e64 v133, v105, v230, s[14:15]
	v_cndmask_b32_e64 v232, v105, v230, s[16:17]
	v_cndmask_b32_e64 v233, v105, v230, s[24:25]
	v_mul_f32_e32 v132, v132, v146
	v_mul_f32_e32 v133, v133, v147
	v_mul_f32_e32 v232, v232, v148
	v_mul_f32_e32 v233, v233, v149
	v_exp_f32_e32 v132, v132
	v_exp_f32_e32 v133, v133
	v_exp_f32_e32 v232, v232
	v_exp_f32_e32 v233, v233
	s_mov_b32 s1, 0x800000
	s_add_i32 s73, s73, s40
	s_cmpk_lt_i32 s73, 0x200
	s_waitcnt vmcnt(4)
	v_lshlrev_b32_e32 v82, 16, v50
	s_waitcnt vmcnt(3)
	v_lshlrev_b32_e32 v84, 16, v54
	v_and_b32_e32 v85, 0xffff0000, v54
	v_and_b32_e32 v83, 0xffff0000, v50
	s_waitcnt vmcnt(0)
	v_cvt_f32_i32_e32 v49, v0
	v_mul_lo_u32 v0, v66, s9
	v_or_b32_e32 v0, v0, v2
	v_lshl_add_u32 v0, v0, 1, v229
	v_lshl_add_u64 v[66:67], v[66:67], 2, s[12:13]
	buffer_load_dwordx4 v[44:47], v0, s[88:91], 0 offen
	buffer_load_dwordx4 v[40:43], v0, s[88:91], 0 offen offset:128
	buffer_load_dwordx4 v[28:31], v0, s[88:91], 0 offen offset:1024
	s_nop 0
	buffer_load_dwordx4 v[0:3], v0, s[88:91], 0 offen offset:1152
	v_mul_f32_e32 v70, v109, v49
	global_load_dword v66, v[66:67], off
	v_mul_f32_e32 v71, 0.15915494, v70
	v_rndne_f32_e32 v71, v71
	v_fmac_f32_e32 v70, 0xc0c90000, v71
	v_fmac_f32_e32 v70, 0xbafdaa22, v71
	v_mul_f32_e32 v71, 0.15915494, v70
	v_sin_f32_e32 v70, v71
	v_cos_f32_e32 v72, v71
	v_mul_f32_e32 v71, v110, v49
	v_mul_f32_e32 v73, 0.15915494, v71
	v_mul_f32_e32 v74, v111, v49
	v_rndne_f32_e32 v73, v73
	v_mul_f32_e32 v75, 0.15915494, v74
	v_fmac_f32_e32 v71, 0xc0c90000, v73
	v_rndne_f32_e32 v75, v75
	v_fmac_f32_e32 v71, 0xbafdaa22, v73
	v_fmac_f32_e32 v74, 0xc0c90000, v75
	v_mul_f32_e32 v73, 0.15915494, v71
	v_fmac_f32_e32 v74, 0xbafdaa22, v75
	v_sin_f32_e32 v71, v73
	v_mul_f32_e32 v75, 0.15915494, v74
	v_cos_f32_e32 v73, v73
	v_sin_f32_e32 v74, v75
	v_cos_f32_e32 v76, v75
	v_mul_f32_e32 v75, v112, v49
	v_mul_f32_e32 v77, 0.15915494, v75
	v_rndne_f32_e32 v77, v77
	v_mul_f32_e32 v78, v113, v49
	v_fmac_f32_e32 v75, 0xc0c90000, v77
	v_mul_f32_e32 v79, 0.15915494, v78
	v_fmac_f32_e32 v75, 0xbafdaa22, v77
	v_rndne_f32_e32 v79, v79
	v_mul_f32_e32 v77, 0.15915494, v75
	v_fmac_f32_e32 v78, 0xc0c90000, v79
	v_sin_f32_e32 v75, v77
	v_fmac_f32_e32 v78, 0xbafdaa22, v79
	v_cos_f32_e32 v77, v77
	v_mul_f32_e32 v79, 0.15915494, v78
	v_sin_f32_e32 v78, v79
	v_cos_f32_e32 v80, v79
	s_waitcnt vmcnt(0)
; #define LAS __attribute__((address_space(3)))
; __device__ __forceinline__ unsigned pk2(float lo, float hi) { return pg8::cvt_pk_bf16(lo, hi); }
; __device__ __forceinline__ float bflo(unsigned w) { return __uint_as_float(w << 16); }
; __device__ __forceinline__ float bfhi(unsigned w) { return __uint_as_float(w & 0xffff0000u); }
; __device__ __forceinline__ float fexp2(float x) { return __builtin_amdgcn_exp2f(x); }
; __device__ __forceinline__ void ret_unit(LAS unsigned char* lds, int u, const bf16* PROJ, const int* pos, const float* dec_f, const float* dec_b, const bf16* ST,
;                                          const float* gn_w, const float* gn_b, bf16* MIX, int tid, const WsRef& wsr) {
;     ...
;     for (int ii = 0; ii < 2; ++ii) { const int it = tid + 512 * ii, dc = it & 7, j = it >> 3;
;         const u32x4 q1 = rq1[ii], q2 = rq2[ii], k1 = rk1[ii], k2 = rk2[ii];
;         const float p = rp[ii];
;         float sn[8], cs[8];
; #pragma unroll
;         for (int e = 0; e < 8; ++e) { const int i = dc * 8 + e; const float inv = fexp2(-(float)i * 0.20762050593046015f); fast_sincos(p * inv, sn[e], cs[e]); }
;         u32x4 oq1, oq2, ok1, ok2;
; #pragma unroll
;         for (int e = 0; e < 4; ++e) { const int e0 = 2 * e, e1 = 2 * e + 1;
;             const float a0 = bflo(q1[e]), a1 = bfhi(q1[e]), b0 = bflo(q2[e]), b1 = bfhi(q2[e]);
;             oq1[e] = pk2(a0 * cs[e0] - b0 * sn[e0], a1 * cs[e1] - b1 * sn[e1]); oq2[e] = pk2(b0 * cs[e0] + a0 * sn[e0], b1 * cs[e1] + a1 * sn[e1]);
;             const float c0 = bflo(k1[e]) * 0.08838834764831845f, c1 = bfhi(k1[e]) * 0.08838834764831845f, d0 = bflo(k2[e]) * 0.08838834764831845f, d1 = bfhi(k2[e]) * 0.08838834764831845f;
;             ok1[e] = pk2(c0 * cs[e0] - d0 * sn[e0], c1 * cs[e1] - d1 * sn[e1]); ok2[e] = pk2(d0 * cs[e0] + c0 * sn[e0], d1 * cs[e1] + c1 * sn[e1]); }
;         *(LAS u32x4*)(Qs + j * LDT + dc * 8) = oq1; *(LAS u32x4*)(Qs + j * LDT + 64 + dc * 8) = oq2;
;         *(LAS u32x4*)(Ks + j * LDT + dc * 8) = ok1; *(LAS u32x4*)(Ks + j * LDT + 64 + dc * 8) = ok2; }
	v_cvt_f32_i32_e32 v88, v66
	v_mul_f32_e32 v66, v107, v49
	v_mul_f32_e32 v67, 0.15915494, v66
	v_rndne_f32_e32 v67, v67
	v_fmac_f32_e32 v66, 0xc0c90000, v67
	v_fmac_f32_e32 v66, 0xbafdaa22, v67
	v_mul_f32_e32 v67, 0.15915494, v66
	v_sin_f32_e32 v66, v67
	v_cos_f32_e32 v68, v67
	v_mul_f32_e32 v67, v108, v49
	v_mul_f32_e32 v69, 0.15915494, v67
	v_rndne_f32_e32 v69, v69
	v_fmac_f32_e32 v67, 0xc0c90000, v69
	v_fmac_f32_e32 v67, 0xbafdaa22, v69
	v_mul_f32_e32 v69, 0.15915494, v67
	v_sin_f32_e32 v67, v69
	v_cos_f32_e32 v69, v69
	v_mul_f32_e32 v49, v114, v49
	v_mul_f32_e32 v79, 0.15915494, v49
	v_pk_mul_f32 v[86:87], v[66:67], v[84:85]
	v_rndne_f32_e32 v79, v79
	v_pk_fma_f32 v[86:87], v[68:69], v[82:83], v[86:87] neg_lo:[0,0,1] neg_hi:[0,0,1]
	v_pk_mul_f32 v[82:83], v[66:67], v[82:83]
	v_cvt_pk_bf16_f32 v50, v86, v87
	v_pk_fma_f32 v[82:83], v[68:69], v[84:85], v[82:83]
	v_lshlrev_b32_e32 v84, 16, v62
	v_cvt_pk_bf16_f32 v54, v82, v83
	v_lshlrev_b32_e32 v82, 16, v58
	v_and_b32_e32 v83, 0xffff0000, v58
	v_and_b32_e32 v85, 0xffff0000, v62
	v_pk_mul_f32 v[82:83], v[82:83], s[10:11] op_sel_hi:[1,0]
	v_pk_mul_f32 v[84:85], v[84:85], s[10:11] op_sel_hi:[1,0]
	v_fmac_f32_e32 v49, 0xc0c90000, v79
	v_pk_mul_f32 v[86:87], v[84:85], v[66:67]
	v_pk_mul_f32 v[66:67], v[82:83], v[66:67]
	v_pk_fma_f32 v[86:87], v[82:83], v[68:69], v[86:87] neg_lo:[0,0,1] neg_hi:[0,0,1]
	v_pk_fma_f32 v[66:67], v[84:85], v[68:69], v[66:67]
	v_lshlrev_b32_e32 v68, 16, v55
	v_and_b32_e32 v69, 0xffff0000, v55
	v_cvt_pk_bf16_f32 v62, v66, v67
	v_lshlrev_b32_e32 v66, 16, v51
	v_and_b32_e32 v67, 0xffff0000, v51
	v_pk_mul_f32 v[82:83], v[70:71], v[68:69]
	v_fmac_f32_e32 v49, 0xbafdaa22, v79
	v_pk_fma_f32 v[82:83], v[72:73], v[66:67], v[82:83] neg_lo:[0,0,1] neg_hi:[0,0,1]
	v_pk_mul_f32 v[66:67], v[70:71], v[66:67]
	v_cvt_pk_bf16_f32 v51, v82, v83
	v_pk_fma_f32 v[66:67], v[72:73], v[68:69], v[66:67]
	v_lshlrev_b32_e32 v68, 16, v63
	v_and_b32_e32 v69, 0xffff0000, v63
	v_cvt_pk_bf16_f32 v55, v66, v67
	v_lshlrev_b32_e32 v66, 16, v59
	v_and_b32_e32 v67, 0xffff0000, v59
	v_pk_mul_f32 v[68:69], v[68:69], s[10:11] op_sel_hi:[1,0]
	v_pk_mul_f32 v[66:67], v[66:67], s[10:11] op_sel_hi:[1,0]
	v_pk_mul_f32 v[82:83], v[68:69], v[70:71]
	v_mul_f32_e32 v49, 0.15915494, v49
	v_pk_fma_f32 v[82:83], v[66:67], v[72:73], v[82:83] neg_lo:[0,0,1] neg_hi:[0,0,1]
	v_pk_mul_f32 v[66:67], v[66:67], v[70:71]
	v_sin_f32_e32 v79, v49
	v_pk_fma_f32 v[66:67], v[68:69], v[72:73], v[66:67]
	v_lshlrev_b32_e32 v68, 16, v56
	v_and_b32_e32 v69, 0xffff0000, v56
	v_cvt_pk_bf16_f32 v63, v66, v67
	v_lshlrev_b32_e32 v66, 16, v52
	v_and_b32_e32 v67, 0xffff0000, v52
	v_pk_mul_f32 v[70:71], v[74:75], v[68:69]
	v_cos_f32_e32 v81, v49
	v_pk_fma_f32 v[70:71], v[76:77], v[66:67], v[70:71] neg_lo:[0,0,1] neg_hi:[0,0,1]
	v_pk_mul_f32 v[66:67], v[74:75], v[66:67]
	v_cvt_pk_bf16_f32 v52, v70, v71
	v_pk_fma_f32 v[66:67], v[76:77], v[68:69], v[66:67]
	v_lshlrev_b32_e32 v68, 16, v64
	v_and_b32_e32 v69, 0xffff0000, v64
	v_cvt_pk_bf16_f32 v56, v66, v67
	v_lshlrev_b32_e32 v66, 16, v60
	v_and_b32_e32 v67, 0xffff0000, v60
	v_pk_mul_f32 v[68:69], v[68:69], s[10:11] op_sel_hi:[1,0]
	v_pk_mul_f32 v[66:67], v[66:67], s[10:11] op_sel_hi:[1,0]
	v_pk_mul_f32 v[70:71], v[68:69], v[74:75]
	v_mul_f32_e32 v49, v107, v88
	v_pk_fma_f32 v[70:71], v[66:67], v[76:77], v[70:71] neg_lo:[0,0,1] neg_hi:[0,0,1]
	v_pk_mul_f32 v[66:67], v[66:67], v[74:75]
	v_cvt_pk_bf16_f32 v60, v70, v71
	v_pk_fma_f32 v[66:67], v[68:69], v[76:77], v[66:67]
	v_lshlrev_b32_e32 v68, 16, v57
	v_and_b32_e32 v69, 0xffff0000, v57
	v_cvt_pk_bf16_f32 v64, v66, v67
	v_lshlrev_b32_e32 v66, 16, v53
	v_and_b32_e32 v67, 0xffff0000, v53
	v_pk_mul_f32 v[70:71], v[78:79], v[68:69]
	v_cvt_pk_bf16_f32 v58, v86, v87
	v_pk_fma_f32 v[70:71], v[80:81], v[66:67], v[70:71] neg_lo:[0,0,1] neg_hi:[0,0,1]
	v_pk_mul_f32 v[66:67], v[78:79], v[66:67]
	v_cvt_pk_bf16_f32 v53, v70, v71
	v_pk_fma_f32 v[66:67], v[80:81], v[68:69], v[66:67]
	v_lshlrev_b32_e32 v68, 16, v65
	v_and_b32_e32 v69, 0xffff0000, v65
	v_cvt_pk_bf16_f32 v57, v66, v67
	v_lshlrev_b32_e32 v66, 16, v61
	v_and_b32_e32 v67, 0xffff0000, v61
	v_pk_mul_f32 v[68:69], v[68:69], s[10:11] op_sel_hi:[1,0]
	v_pk_mul_f32 v[66:67], v[66:67], s[10:11] op_sel_hi:[1,0]
	v_pk_mul_f32 v[70:71], v[68:69], v[78:79]
	v_cvt_pk_bf16_f32 v59, v82, v83
	v_pk_fma_f32 v[70:71], v[66:67], v[80:81], v[70:71] neg_lo:[0,0,1] neg_hi:[0,0,1]
	v_pk_mul_f32 v[66:67], v[66:67], v[78:79]
	v_cvt_pk_bf16_f32 v61, v70, v71
	v_pk_fma_f32 v[66:67], v[68:69], v[80:81], v[66:67]
	v_lshlrev_b32_e32 v68, 16, v40
	v_cvt_pk_bf16_f32 v65, v66, v67
	ds_write_b128 v115, v[50:53]
	ds_write_b128 v115, v[54:57] offset:128
	ds_write_b128 v115, v[58:61] offset:34816
	ds_write_b128 v115, v[62:65] offset:34944
	v_mul_f32_e32 v50, 0.15915494, v49
	v_rndne_f32_e32 v50, v50
	v_fmac_f32_e32 v49, 0xc0c90000, v50
	v_fmac_f32_e32 v49, 0xbafdaa22, v50
	v_mul_f32_e32 v49, 0.15915494, v49
	v_sin_f32_e32 v50, v49
	v_cos_f32_e32 v52, v49
	v_mul_f32_e32 v49, v108, v88
	v_mul_f32_e32 v51, 0.15915494, v49
	v_rndne_f32_e32 v51, v51
	v_fmac_f32_e32 v49, 0xc0c90000, v51
	v_fmac_f32_e32 v49, 0xbafdaa22, v51
	v_mul_f32_e32 v49, 0.15915494, v49
	v_sin_f32_e32 v51, v49
	v_cos_f32_e32 v53, v49
	v_mul_f32_e32 v49, v109, v88
	v_mul_f32_e32 v54, 0.15915494, v49
	v_rndne_f32_e32 v54, v54
	v_fmac_f32_e32 v49, 0xc0c90000, v54
	v_fmac_f32_e32 v49, 0xbafdaa22, v54
	v_mul_f32_e32 v49, 0.15915494, v49
	v_sin_f32_e32 v54, v49
	v_cos_f32_e32 v56, v49
	v_mul_f32_e32 v49, v110, v88
	v_mul_f32_e32 v55, 0.15915494, v49
	v_rndne_f32_e32 v55, v55
	v_fmac_f32_e32 v49, 0xc0c90000, v55
	v_fmac_f32_e32 v49, 0xbafdaa22, v55
	v_mul_f32_e32 v49, 0.15915494, v49
; #define LAS __attribute__((address_space(3)))
; __device__ __forceinline__ unsigned pk2(float lo, float hi) { return pg8::cvt_pk_bf16(lo, hi); }
; __device__ __forceinline__ float bflo(unsigned w) { return __uint_as_float(w << 16); }
; __device__ __forceinline__ float bfhi(unsigned w) { return __uint_as_float(w & 0xffff0000u); }
; __device__ __forceinline__ u32x4 ws_load16(const WsRef& w, unsigned byte_off) { return __builtin_bit_cast(u32x4, __builtin_amdgcn_raw_buffer_load_b128(w.r, byte_off, 0, 0)); }
; __device__ __forceinline__ void ret_unit(LAS unsigned char* lds, int u, const bf16* PROJ, const int* pos, const float* dec_f, const float* dec_b, const bf16* ST,
;                                          const float* gn_w, const float* gn_b, bf16* MIX, int tid, const WsRef& wsr) {
;     ...
;     for (int ii = 0; ii < 2; ++ii) { const int it = tid + 512 * ii, dc = it & 7, j = it >> 3;
;         const u32x4 q1 = rq1[ii], q2 = rq2[ii], k1 = rk1[ii], k2 = rk2[ii];
;         const float p = rp[ii];
;         float sn[8], cs[8];
; #pragma unroll
;         for (int e = 0; e < 8; ++e) { const int i = dc * 8 + e; const float inv = fexp2(-(float)i * 0.20762050593046015f); fast_sincos(p * inv, sn[e], cs[e]); }
;         u32x4 oq1, oq2, ok1, ok2;
; #pragma unroll
;         for (int e = 0; e < 4; ++e) { const int e0 = 2 * e, e1 = 2 * e + 1;
;             const float a0 = bflo(q1[e]), a1 = bfhi(q1[e]), b0 = bflo(q2[e]), b1 = bfhi(q2[e]);
;             oq1[e] = pk2(a0 * cs[e0] - b0 * sn[e0], a1 * cs[e1] - b1 * sn[e1]); oq2[e] = pk2(b0 * cs[e0] + a0 * sn[e0], b1 * cs[e1] + a1 * sn[e1]);
;             const float c0 = bflo(k1[e]) * 0.08838834764831845f, c1 = bfhi(k1[e]) * 0.08838834764831845f, d0 = bflo(k2[e]) * 0.08838834764831845f, d1 = bfhi(k2[e]) * 0.08838834764831845f;
;             ok1[e] = pk2(c0 * cs[e0] - d0 * sn[e0], c1 * cs[e1] - d1 * sn[e1]); ok2[e] = pk2(d0 * cs[e0] + c0 * sn[e0], d1 * cs[e1] + c1 * sn[e1]); }
;         *(LAS u32x4*)(Qs + j * LDT + dc * 8) = oq1; *(LAS u32x4*)(Qs + j * LDT + 64 + dc * 8) = oq2;
;         *(LAS u32x4*)(Ks + j * LDT + dc * 8) = ok1; *(LAS u32x4*)(Ks + j * LDT + 64 + dc * 8) = ok2; }
; #pragma unroll
;     for (int ii = 0; ii < 4; ++ii) { const int it = tid + 512 * ii, ec = it & 15, j = it >> 4; rv[ii] = ws_load16(wsr, (unsigned)WS_PROJ + (unsigned)(((unsigned)(row0 + j) * INC + 1024 + h * 128 + ec * 8) * 2u)); }
	v_sin_f32_e32 v55, v49
	v_cos_f32_e32 v57, v49
	v_mul_f32_e32 v49, v111, v88
	v_mul_f32_e32 v58, 0.15915494, v49
	v_rndne_f32_e32 v58, v58
	v_fmac_f32_e32 v49, 0xc0c90000, v58
	v_fmac_f32_e32 v49, 0xbafdaa22, v58
	v_mul_f32_e32 v49, 0.15915494, v49
	v_sin_f32_e32 v58, v49
	v_cos_f32_e32 v60, v49
	v_mul_f32_e32 v49, v112, v88
	v_and_b32_e32 v69, 0xffff0000, v40
	v_mul_f32_e32 v59, 0.15915494, v49
	v_lshlrev_b32_e32 v66, 16, v44
	v_and_b32_e32 v67, 0xffff0000, v44
	v_pk_mul_f32 v[70:71], v[50:51], v[68:69]
	v_rndne_f32_e32 v59, v59
	v_pk_fma_f32 v[70:71], v[52:53], v[66:67], v[70:71] neg_lo:[0,0,1] neg_hi:[0,0,1]
	v_pk_mul_f32 v[66:67], v[50:51], v[66:67]
	v_fmac_f32_e32 v49, 0xc0c90000, v59
	v_pk_fma_f32 v[66:67], v[52:53], v[68:69], v[66:67]
	v_fmac_f32_e32 v49, 0xbafdaa22, v59
	v_cvt_pk_bf16_f32 v44, v66, v67
	v_lshlrev_b32_e32 v66, 16, v28
	v_and_b32_e32 v67, 0xffff0000, v28
	v_lshlrev_b32_e32 v68, 16, v0
	v_and_b32_e32 v69, 0xffff0000, v0
	v_mul_f32_e32 v49, 0.15915494, v49
	v_pk_mul_f32 v[66:67], v[66:67], s[10:11] op_sel_hi:[1,0]
	v_pk_mul_f32 v[68:69], v[68:69], s[10:11] op_sel_hi:[1,0]
	v_sin_f32_e32 v59, v49
	v_cos_f32_e32 v61, v49
	v_mul_f32_e32 v49, v113, v88
	v_cvt_pk_bf16_f32 v40, v70, v71
	v_pk_mul_f32 v[70:71], v[68:69], v[50:51]
	v_pk_mul_f32 v[50:51], v[66:67], v[50:51]
	v_mul_f32_e32 v62, 0.15915494, v49
	v_pk_fma_f32 v[70:71], v[66:67], v[52:53], v[70:71] neg_lo:[0,0,1] neg_hi:[0,0,1]
	v_pk_fma_f32 v[50:51], v[68:69], v[52:53], v[50:51]
	v_lshlrev_b32_e32 v52, 16, v41
	v_and_b32_e32 v53, 0xffff0000, v41
	v_rndne_f32_e32 v62, v62
	v_cvt_pk_bf16_f32 v28, v50, v51
	v_lshlrev_b32_e32 v50, 16, v45
	v_and_b32_e32 v51, 0xffff0000, v45
	v_pk_mul_f32 v[66:67], v[54:55], v[52:53]
	v_fmac_f32_e32 v49, 0xc0c90000, v62
	v_pk_fma_f32 v[66:67], v[56:57], v[50:51], v[66:67] neg_lo:[0,0,1] neg_hi:[0,0,1]
	v_pk_mul_f32 v[50:51], v[54:55], v[50:51]
	v_fmac_f32_e32 v49, 0xbafdaa22, v62
	v_pk_fma_f32 v[50:51], v[56:57], v[52:53], v[50:51]
	v_lshlrev_b32_e32 v52, 16, v1
	v_and_b32_e32 v53, 0xffff0000, v1
	v_mul_f32_e32 v49, 0.15915494, v49
	v_cvt_pk_bf16_f32 v45, v50, v51
	v_lshlrev_b32_e32 v50, 16, v29
	v_and_b32_e32 v51, 0xffff0000, v29
	v_pk_mul_f32 v[52:53], v[52:53], s[10:11] op_sel_hi:[1,0]
	v_sin_f32_e32 v62, v49
	v_cos_f32_e32 v64, v49
	v_mul_f32_e32 v49, v114, v88
	v_cvt_pk_bf16_f32 v41, v66, v67
	v_pk_mul_f32 v[50:51], v[50:51], s[10:11] op_sel_hi:[1,0]
	v_pk_mul_f32 v[66:67], v[52:53], v[54:55]
	v_mul_f32_e32 v63, 0.15915494, v49
	v_pk_fma_f32 v[66:67], v[50:51], v[56:57], v[66:67] neg_lo:[0,0,1] neg_hi:[0,0,1]
	v_pk_mul_f32 v[50:51], v[50:51], v[54:55]
	v_rndne_f32_e32 v63, v63
	v_pk_fma_f32 v[50:51], v[52:53], v[56:57], v[50:51]
	v_lshlrev_b32_e32 v52, 16, v42
	v_and_b32_e32 v53, 0xffff0000, v42
	v_fmac_f32_e32 v49, 0xc0c90000, v63
	v_cvt_pk_bf16_f32 v29, v50, v51
	v_lshlrev_b32_e32 v50, 16, v46
	v_and_b32_e32 v51, 0xffff0000, v46
	v_pk_mul_f32 v[54:55], v[58:59], v[52:53]
	v_fmac_f32_e32 v49, 0xbafdaa22, v63
	v_pk_fma_f32 v[54:55], v[60:61], v[50:51], v[54:55] neg_lo:[0,0,1] neg_hi:[0,0,1]
	v_pk_mul_f32 v[50:51], v[58:59], v[50:51]
	v_mul_f32_e32 v49, 0.15915494, v49
	v_pk_fma_f32 v[50:51], v[60:61], v[52:53], v[50:51]
	v_lshlrev_b32_e32 v52, 16, v2
	v_and_b32_e32 v53, 0xffff0000, v2
	v_sin_f32_e32 v63, v49
	v_cvt_pk_bf16_f32 v46, v50, v51
	v_lshlrev_b32_e32 v50, 16, v30
	v_and_b32_e32 v51, 0xffff0000, v30
	v_pk_mul_f32 v[52:53], v[52:53], s[10:11] op_sel_hi:[1,0]
	v_cos_f32_e32 v65, v49
	v_cvt_pk_bf16_f32 v42, v54, v55
	v_pk_mul_f32 v[50:51], v[50:51], s[10:11] op_sel_hi:[1,0]
	v_pk_mul_f32 v[54:55], v[52:53], v[58:59]
	v_cvt_pk_bf16_f32 v0, v70, v71
	v_pk_fma_f32 v[54:55], v[50:51], v[60:61], v[54:55] neg_lo:[0,0,1] neg_hi:[0,0,1]
	v_pk_mul_f32 v[50:51], v[50:51], v[58:59]
	v_cvt_pk_bf16_f32 v2, v54, v55
	v_pk_fma_f32 v[50:51], v[52:53], v[60:61], v[50:51]
	v_lshlrev_b32_e32 v52, 16, v43
	v_and_b32_e32 v53, 0xffff0000, v43
	v_cvt_pk_bf16_f32 v30, v50, v51
	v_lshlrev_b32_e32 v50, 16, v47
	v_and_b32_e32 v51, 0xffff0000, v47
	v_pk_mul_f32 v[54:55], v[62:63], v[52:53]
	v_cvt_pk_bf16_f32 v1, v66, v67
	v_pk_fma_f32 v[54:55], v[64:65], v[50:51], v[54:55] neg_lo:[0,0,1] neg_hi:[0,0,1]
	v_pk_mul_f32 v[50:51], v[62:63], v[50:51]
	v_cvt_pk_bf16_f32 v43, v54, v55
	v_pk_fma_f32 v[50:51], v[64:65], v[52:53], v[50:51]
	v_lshlrev_b32_e32 v52, 16, v3
	v_and_b32_e32 v53, 0xffff0000, v3
	v_cvt_pk_bf16_f32 v47, v50, v51
	v_lshlrev_b32_e32 v50, 16, v31
	v_and_b32_e32 v51, 0xffff0000, v31
	v_pk_mul_f32 v[52:53], v[52:53], s[10:11] op_sel_hi:[1,0]
	v_pk_mul_f32 v[50:51], v[50:51], s[10:11] op_sel_hi:[1,0]
	v_pk_mul_f32 v[54:55], v[52:53], v[62:63]
	v_add_u32_e32 v49, v124, v125
	v_pk_fma_f32 v[54:55], v[50:51], v[64:65], v[54:55] neg_lo:[0,0,1] neg_hi:[0,0,1]
	v_pk_mul_f32 v[50:51], v[50:51], v[62:63]
	v_cvt_pk_bf16_f32 v3, v54, v55
	v_pk_fma_f32 v[50:51], v[52:53], v[64:65], v[50:51]
	v_cndmask_b32_e64 v86, v105, v230, s[66:67]
	v_cvt_pk_bf16_f32 v31, v50, v51
	ds_write_b128 v116, v[40:43]
	ds_write_b128 v116, v[44:47] offset:128
	ds_write_b128 v116, v[0:3] offset:34816
	ds_write_b128 v116, v[28:31] offset:34944
	v_or_b32_e32 v44, s0, v222
	v_or_b32_e32 v0, s4, v99
	v_mad_u64_u32 v[0:1], s[68:69], v0, s9, v[44:45]
	v_lshl_add_u32 v0, v0, 1, v229
	buffer_load_dwordx4 v[0:3], v0, s[88:91], 0 offen
	v_or_b32_e32 v28, s4, v117
	v_mad_u64_u32 v[28:29], s[68:69], v28, s9, v[44:45]
	v_lshl_add_u32 v28, v28, 1, v229
	buffer_load_dwordx4 v[28:31], v28, s[88:91], 0 offen
	v_or_b32_e32 v40, s4, v118
	v_mad_u64_u32 v[40:41], s[68:69], v40, s9, v[44:45]
	v_lshl_add_u32 v40, v40, 1, v229
	buffer_load_dwordx4 v[40:43], v40, s[88:91], 0 offen
	v_add_u32_e32 v45, s4, v119
	v_mad_u64_u32 v[44:45], s[68:69], v45, s9, v[44:45]
	v_lshl_add_u32 v44, v44, 1, v229
	buffer_load_dwordx4 v[44:47], v44, s[88:91], 0 offen
	s_waitcnt vmcnt(3)
; #define LAS __attribute__((address_space(3)))
; #define MFMA16(a, b, c) __builtin_amdgcn_mfma_f32_16x16x32_bf16((a), (b), (c), 0, 0, 0)
; __device__ __forceinline__ void ret_unit(LAS unsigned char* lds, int u, const bf16* PROJ, const int* pos, const float* dec_f, const float* dec_b, const bf16* ST,
;                                          const float* gn_w, const float* gn_b, bf16* MIX, int tid, const WsRef& wsr) {
;     ...
;     for (int ii = 0; ii < 4; ++ii) { const int it = tid + 512 * ii, ec = it & 15, j = it >> 4; const u32x4 w = rv[ii];
;         const int jsw = (((j >> 3) ^ (ec & 7)) << 3) | (j & 7);
; #pragma unroll
;         for (int e = 0; e < 4; ++e) { VT[(ec * 8 + 2 * e) * LDT + jsw] = (bf16)(w[e] & 0xffffu); VT[(ec * 8 + 2 * e + 1) * LDT + jsw] = (bf16)(w[e] >> 16); } }
;     __syncthreads();
;     const int q = wave * 16 + fr;
;     bf16x8 qf[4];
; #pragma unroll
;     for (int kk = 0; kk < 4; ++kk) qf[kk] = *(const LAS bf16x8*)(Qs + q * LDT + kk * 32 + fq * 8);
;     f32x4 s[8];
; #pragma unroll
;     for (int n = 0; n < 8; ++n) s[n] = (f32x4){0.f, 0.f, 0.f, 0.f};
; #pragma unroll
;     for (int kk = 0; kk < 4; ++kk)
; #pragma unroll
;         for (int n = 0; n < 8; ++n) { const bf16x8 kf = *(const LAS bf16x8*)(Ks + (n * 16 + fr) * LDT + kk * 32 + fq * 8); s[n] = MFMA16(kf, qf[kk], s[n]); }
	ds_write_b16 v120, v0
	ds_write_b16_d16_hi v120, v0 offset:272
	ds_write_b16 v120, v1 offset:544
	ds_write_b16_d16_hi v120, v1 offset:816
	ds_write_b16 v120, v2 offset:1088
	ds_write_b16_d16_hi v120, v2 offset:1360
	ds_write_b16 v120, v3 offset:1632
	ds_write_b16_d16_hi v120, v3 offset:1904
	s_waitcnt vmcnt(2)
	ds_write_b16 v121, v28
	ds_write_b16_d16_hi v121, v28 offset:272
	ds_write_b16 v121, v29 offset:544
	ds_write_b16_d16_hi v121, v29 offset:816
	ds_write_b16 v121, v30 offset:1088
	ds_write_b16_d16_hi v121, v30 offset:1360
	ds_write_b16 v121, v31 offset:1632
	ds_write_b16_d16_hi v121, v31 offset:1904
	s_waitcnt vmcnt(1)
	ds_write_b16 v122, v40
	ds_write_b16_d16_hi v122, v40 offset:272
	ds_write_b16 v122, v41 offset:544
	ds_write_b16_d16_hi v122, v41 offset:816
	ds_write_b16 v122, v42 offset:1088
	ds_write_b16_d16_hi v122, v42 offset:1360
	ds_write_b16 v122, v43 offset:1632
	ds_write_b16_d16_hi v122, v43 offset:1904
	s_waitcnt vmcnt(0)
	ds_write_b16 v123, v44
	ds_write_b16_d16_hi v123, v44 offset:272
	ds_write_b16 v123, v45 offset:544
	ds_write_b16_d16_hi v123, v45 offset:816
	ds_write_b16 v123, v46 offset:1088
	ds_write_b16_d16_hi v123, v46 offset:1360
	ds_write_b16 v123, v47 offset:1632
	ds_write_b16_d16_hi v123, v47 offset:1904
	s_waitcnt lgkmcnt(0)
	s_barrier
	ds_read_b128 v[44:47], v225
	ds_read_b128 v[40:43], v225 offset:64
	ds_read_b128 v[28:31], v225 offset:128
	ds_read_b128 v[0:3], v225 offset:192
	ds_read_b128 v[50:53], v226 offset:34816
	ds_read_b128 v[54:57], v226 offset:39168
	ds_read_b128 v[82:85], v226 offset:34880
	s_waitcnt lgkmcnt(2)
	v_mfma_f32_16x16x32_bf16 v[50:53], v[50:53], v[44:47], 0
	ds_read_b128 v[58:61], v226 offset:43520
	ds_read_b128 v[62:65], v226 offset:47872
	ds_read_b128 v[66:69], v226 offset:52224
	s_waitcnt lgkmcnt(3)
	v_mfma_f32_16x16x32_bf16 v[50:53], v[82:85], v[40:43], v[50:53]
	ds_read_b128 v[82:85], v226 offset:39232
	ds_read_b128 v[70:73], v49 offset:34816
	ds_read_b128 v[74:77], v49 offset:39168
	v_mfma_f32_16x16x32_bf16 v[54:57], v[54:57], v[44:47], 0
	ds_read_b128 v[78:81], v49 offset:43520
	v_cndmask_b32_e64 v87, v105, v230, s[26:27]
	v_cndmask_b32_e64 v88, v105, v230, s[28:29]
	s_waitcnt lgkmcnt(3)
	v_mfma_f32_16x16x32_bf16 v[54:57], v[82:85], v[40:43], v[54:57]
	ds_read_b128 v[82:85], v226 offset:43584
	v_mul_f32_e32 v86, v86, v134
	v_mul_f32_e32 v87, v87, v135
	v_mfma_f32_16x16x32_bf16 v[58:61], v[58:61], v[44:47], 0
	v_mul_f32_e32 v88, v88, v136
	v_exp_f32_e32 v86, v86
	v_exp_f32_e32 v87, v87
	s_waitcnt lgkmcnt(0)
	v_mfma_f32_16x16x32_bf16 v[58:61], v[82:85], v[40:43], v[58:61]
	ds_read_b128 v[82:85], v226 offset:47936
	v_exp_f32_e32 v88, v88
	v_readlane_b32 s68, v255, 4
	v_mfma_f32_16x16x32_bf16 v[62:65], v[62:65], v[44:47], 0
	v_readlane_b32 s69, v255, 5
	s_waitcnt lgkmcnt(0)
	v_mfma_f32_16x16x32_bf16 v[62:65], v[82:85], v[40:43], v[62:65]
	ds_read_b128 v[82:85], v226 offset:52288
	v_cndmask_b32_e64 v239, v105, v230, s[68:69]
	v_readlane_b32 s68, v255, 50
	v_mfma_f32_16x16x32_bf16 v[66:69], v[66:69], v[44:47], 0
	v_readlane_b32 s69, v255, 51
	v_mul_f32_e32 v239, v239, v155
	v_exp_f32_e32 v239, v239
	s_waitcnt lgkmcnt(0)
	v_mfma_f32_16x16x32_bf16 v[66:69], v[82:85], v[40:43], v[66:69]
	ds_read_b128 v[82:85], v49 offset:34880
	v_cndmask_b32_e64 v240, v105, v230, s[68:69]
	v_readlane_b32 s68, v255, 52
	v_mfma_f32_16x16x32_bf16 v[70:73], v[70:73], v[44:47], 0
	v_readlane_b32 s69, v255, 53
	v_mul_f32_e32 v240, v240, v156
	v_exp_f32_e32 v240, v240
	s_waitcnt lgkmcnt(0)
	v_mfma_f32_16x16x32_bf16 v[70:73], v[82:85], v[40:43], v[70:73]
	ds_read_b128 v[82:85], v49 offset:39232
	v_cndmask_b32_e64 v241, v105, v230, s[68:69]
	v_readlane_b32 s68, v255, 54
	v_mfma_f32_16x16x32_bf16 v[74:77], v[74:77], v[44:47], 0
	v_readlane_b32 s69, v255, 55
	v_mul_f32_e32 v241, v241, v157
	v_exp_f32_e32 v241, v241
	s_waitcnt lgkmcnt(0)
	v_mfma_f32_16x16x32_bf16 v[74:77], v[82:85], v[40:43], v[74:77]
	ds_read_b128 v[82:85], v49 offset:43584
	v_cndmask_b32_e64 v242, v105, v230, s[68:69]
	v_readlane_b32 s68, v255, 56
	v_mfma_f32_16x16x32_bf16 v[78:81], v[78:81], v[44:47], 0
	v_readlane_b32 s69, v255, 57
	v_mul_f32_e32 v242, v242, v158
	v_exp_f32_e32 v242, v242
	s_waitcnt lgkmcnt(0)
	v_mfma_f32_16x16x32_bf16 v[78:81], v[82:85], v[40:43], v[78:81]
	ds_read_b128 v[82:85], v226 offset:34944
	v_cndmask_b32_e64 v243, v105, v230, s[68:69]
	v_mul_f32_e32 v243, v243, v159
	s_waitcnt lgkmcnt(0)
	v_mfma_f32_16x16x32_bf16 v[50:53], v[82:85], v[28:31], v[50:53]
	ds_read_b128 v[82:85], v226 offset:39296
	v_exp_f32_e32 v243, v243
	s_waitcnt lgkmcnt(0)
	v_mfma_f32_16x16x32_bf16 v[54:57], v[82:85], v[28:31], v[54:57]
	ds_read_b128 v[82:85], v226 offset:43648
	s_waitcnt lgkmcnt(0)
	v_mfma_f32_16x16x32_bf16 v[58:61], v[82:85], v[28:31], v[58:61]
	ds_read_b128 v[82:85], v226 offset:48000
	s_waitcnt lgkmcnt(0)
	v_mfma_f32_16x16x32_bf16 v[62:65], v[82:85], v[28:31], v[62:65]
	ds_read_b128 v[82:85], v226 offset:52352
	s_waitcnt lgkmcnt(0)
	v_mfma_f32_16x16x32_bf16 v[66:69], v[82:85], v[28:31], v[66:69]
	ds_read_b128 v[82:85], v49 offset:34944
	s_waitcnt lgkmcnt(0)
	v_mfma_f32_16x16x32_bf16 v[70:73], v[82:85], v[28:31], v[70:73]
	ds_read_b128 v[82:85], v49 offset:39296
	s_waitcnt lgkmcnt(0)
	v_mfma_f32_16x16x32_bf16 v[74:77], v[82:85], v[28:31], v[74:77]
	ds_read_b128 v[82:85], v49 offset:43648
	s_waitcnt lgkmcnt(0)
	v_mfma_f32_16x16x32_bf16 v[78:81], v[82:85], v[28:31], v[78:81]
	ds_read_b128 v[82:85], v226 offset:35008
	s_waitcnt lgkmcnt(0)
	v_mfma_f32_16x16x32_bf16 v[50:53], v[82:85], v[0:3], v[50:53]
	ds_read_b128 v[82:85], v226 offset:39360
	s_waitcnt lgkmcnt(0)
; #define LAS __attribute__((address_space(3)))
; __device__ __forceinline__ unsigned pk2(float lo, float hi) { return pg8::cvt_pk_bf16(lo, hi); }
; __device__ __forceinline__ float fexp2(float x) { return __builtin_amdgcn_exp2f(x); }
; #define MFMA16(a, b, c) __builtin_amdgcn_mfma_f32_16x16x32_bf16((a), (b), (c), 0, 0, 0)
; __device__ __forceinline__ void ret_unit(LAS unsigned char* lds, int u, const bf16* PROJ, const int* pos, const float* dec_f, const float* dec_b, const bf16* ST,
;                                          const float* gn_w, const float* gn_b, bf16* MIX, int tid, const WsRef& wsr) {
;     ...
;     bf16x8 pf[4];
; #pragma unroll
;     for (int n = 0; n < 8; ++n) {
; #pragma unroll
;         for (int r = 0; r < 4; ++r) { const int key = n * 16 + 4 * fq + r; const int df = q - key; const float f = df >= 0 ? fexp2(lgf2 * (float)df) : fexp2(lgb2 * (float)(-df)); s[n][r] *= f; } }
; #pragma unroll
;     for (int kk = 0; kk < 4; ++kk) { u32x4 w; w.x = pk2(s[2 * kk][0], s[2 * kk][1]); w.y = pk2(s[2 * kk][2], s[2 * kk][3]); w.z = pk2(s[2 * kk + 1][0], s[2 * kk + 1][1]); w.w = pk2(s[2 * kk + 1][2], s[2 * kk + 1][3]);
;         pf[kk] = __builtin_bit_cast(bf16x8, w); }
;     f32x4 o[8];
; #pragma unroll
;     for (int n = 0; n < 8; ++n) o[n] = (f32x4){0.f, 0.f, 0.f, 0.f};
; #pragma unroll
;     for (int kk = 0; kk < 4; ++kk)
; #pragma unroll
;         for (int n = 0; n < 8; ++n) { const int sw = (2 * n + (fr >> 3)) & 7, jc = kk * 4 + (fq >> 1); const LAS bf16* vr = VT + (n * 16 + fr) * LDT + 4 * (fq & 1);
;             const u32x2 lo = *(const LAS u32x2*)(vr + ((jc ^ sw) << 3)), hi = *(const LAS u32x2*)(vr + (((jc + 2) ^ sw) << 3)); u32x4 w; w.x = lo.x; w.y = lo.y; w.z = hi.x; w.w = hi.y;
;             o[n] = MFMA16(__builtin_bit_cast(bf16x8, w), pf[kk], o[n]); }
	v_mfma_f32_16x16x32_bf16 v[54:57], v[82:85], v[0:3], v[54:57]
	ds_read_b128 v[82:85], v226 offset:43712
	s_nop 6
	v_pk_mul_f32 v[56:57], v[86:87], v[56:57]
	s_waitcnt lgkmcnt(0)
	v_mfma_f32_16x16x32_bf16 v[58:61], v[82:85], v[0:3], v[58:61]
	ds_read_b128 v[82:85], v226 offset:48064
	s_nop 6
	v_pk_mul_f32 v[58:59], v[88:89], v[58:59]
	s_waitcnt lgkmcnt(0)
	v_mfma_f32_16x16x32_bf16 v[62:65], v[82:85], v[0:3], v[62:65]
	ds_read_b128 v[82:85], v226 offset:52416
	v_pk_mul_f32 v[88:89], v[90:91], v[60:61]
	s_nop 5
	v_pk_mul_f32 v[64:65], v[94:95], v[64:65]
	s_waitcnt lgkmcnt(0)
	v_mfma_f32_16x16x32_bf16 v[66:69], v[82:85], v[0:3], v[66:69]
	ds_read_b128 v[82:85], v49 offset:35008
	v_pk_mul_f32 v[92:93], v[92:93], v[62:63]
	v_cvt_pk_bf16_f32 v63, v56, v57
	v_cvt_pk_bf16_f32 v56, v58, v59
	v_cvt_pk_bf16_f32 v59, v64, v65
	v_add_u32_e32 v64, v160, v161
	ds_read_b64 v[64:65], v64
	s_waitcnt lgkmcnt(1)
	v_mfma_f32_16x16x32_bf16 v[70:73], v[82:85], v[0:3], v[70:73]
	ds_read_b128 v[82:85], v49 offset:39360
	v_cvt_pk_bf16_f32 v58, v92, v93
	v_add_u32_e32 v92, v175, v170
	ds_read_b64 v[92:93], v92
	s_waitcnt lgkmcnt(1)
	v_mfma_f32_16x16x32_bf16 v[74:77], v[82:85], v[0:3], v[74:77]
	ds_read_b128 v[82:85], v49 offset:43712
	v_add_u32_e32 v94, v175, v171
	ds_read_b64 v[94:95], v94
	s_waitcnt lgkmcnt(1)
	v_mfma_f32_16x16x32_bf16 v[78:81], v[82:85], v[0:3], v[78:81]
	v_cndmask_b32_e64 v49, v105, v230, s[44:45]
	v_cndmask_b32_e64 v82, v105, v230, s[46:47]
	v_cndmask_b32_e64 v83, v105, v230, s[48:49]
	v_mul_f32_e32 v49, v49, v129
	v_mul_f32_e32 v82, v82, v231
	v_mul_f32_e32 v83, v83, v252
	v_exp_f32_e32 v49, v49
	v_exp_f32_e32 v82, v82
	v_exp_f32_e32 v83, v83
	v_pk_mul_f32 v[66:67], v[130:131], v[66:67]
	v_pk_mul_f32 v[48:49], v[48:49], v[50:51]
	v_cndmask_b32_e64 v84, v105, v230, s[50:51]
	v_pk_mul_f32 v[50:51], v[82:83], v[52:53]
	v_cvt_pk_bf16_f32 v52, v66, v67
	v_add_u32_e32 v66, v160, v162
	ds_read_b64 v[66:67], v66
	v_cndmask_b32_e64 v85, v105, v230, s[52:53]
	v_mul_f32_e32 v84, v84, v253
	v_mul_f32_e32 v85, v85, v254
	v_exp_f32_e32 v84, v84
	v_exp_f32_e32 v85, v85
	v_cvt_pk_bf16_f32 v60, v48, v49
	v_cvt_pk_bf16_f32 v61, v50, v51
	v_pk_mul_f32 v[80:81], v[242:243], v[80:81]
	v_pk_mul_f32 v[54:55], v[84:85], v[54:55]
	v_cvt_pk_bf16_f32 v51, v80, v81
	v_cvt_pk_bf16_f32 v62, v54, v55
	v_cvt_pk_bf16_f32 v57, v88, v89
	v_pk_mul_f32 v[78:79], v[240:241], v[78:79]
	s_waitcnt lgkmcnt(0)
	v_mfma_f32_16x16x32_bf16 v[84:87], v[64:67], v[60:63], 0
	v_add_u32_e32 v64, v163, v164
	v_add_u32_e32 v66, v163, v165
	ds_read_b64 v[64:65], v64
	ds_read_b64 v[66:67], v66
	s_waitcnt lgkmcnt(0)
	v_mfma_f32_16x16x32_bf16 v[80:83], v[64:67], v[60:63], 0
	v_add_u32_e32 v64, v166, v167
	v_add_u32_e32 v66, v166, v168
	ds_read_b64 v[64:65], v64
	ds_read_b64 v[66:67], v66
	s_waitcnt lgkmcnt(0)
	v_mfma_f32_16x16x32_bf16 v[88:91], v[64:67], v[60:63], 0
	v_add_u32_e32 v64, v169, v170
	v_add_u32_e32 v66, v169, v171
	ds_read_b64 v[64:65], v64
	ds_read_b64 v[66:67], v66
	v_pk_mul_f32 v[76:77], v[238:239], v[76:77]
	v_cvt_pk_bf16_f32 v50, v78, v79
	v_cvt_pk_bf16_f32 v49, v76, v77
	s_waitcnt lgkmcnt(0)
	v_mfma_f32_16x16x32_bf16 v[76:79], v[64:67], v[60:63], 0
	v_add_u32_e32 v64, v172, v161
	v_add_u32_e32 v66, v172, v162
	ds_read_b64 v[64:65], v64
	ds_read_b64 v[66:67], v66
	v_pk_mul_f32 v[74:75], v[236:237], v[74:75]
	v_pk_mul_f32 v[72:73], v[234:235], v[72:73]
	v_cvt_pk_bf16_f32 v48, v74, v75
	v_cvt_pk_bf16_f32 v55, v72, v73
	s_waitcnt lgkmcnt(0)
	v_mfma_f32_16x16x32_bf16 v[72:75], v[64:67], v[60:63], 0
	v_add_u32_e32 v64, v173, v164
	v_add_u32_e32 v66, v173, v165
	ds_read_b64 v[64:65], v64
	ds_read_b64 v[66:67], v66
	v_pk_mul_f32 v[70:71], v[232:233], v[70:71]
	v_pk_mul_f32 v[68:69], v[132:133], v[68:69]
	v_cvt_pk_bf16_f32 v54, v70, v71
	v_cvt_pk_bf16_f32 v53, v68, v69
	s_waitcnt lgkmcnt(0)
	v_mfma_f32_16x16x32_bf16 v[68:71], v[64:67], v[60:63], 0
	v_add_u32_e32 v64, v174, v167
	v_add_u32_e32 v66, v174, v168
	ds_read_b64 v[64:65], v64
	ds_read_b64 v[66:67], v66
	s_waitcnt lgkmcnt(0)
	v_mfma_f32_16x16x32_bf16 v[64:67], v[64:67], v[60:63], 0
	v_mfma_f32_16x16x32_bf16 v[60:63], v[92:95], v[60:63], 0
	v_add_u32_e32 v92, v160, v176
	v_add_u32_e32 v94, v160, v177
	ds_read_b64 v[92:93], v92
	ds_read_b64 v[94:95], v94
	s_waitcnt lgkmcnt(0)
	v_mfma_f32_16x16x32_bf16 v[84:87], v[92:95], v[56:59], v[84:87]
	v_add_u32_e32 v92, v163, v178
	v_add_u32_e32 v94, v163, v179
	ds_read_b64 v[92:93], v92
	ds_read_b64 v[94:95], v94
	s_waitcnt lgkmcnt(0)
	v_mfma_f32_16x16x32_bf16 v[80:83], v[92:95], v[56:59], v[80:83]
	v_add_u32_e32 v92, v166, v180
	v_add_u32_e32 v94, v166, v181
	ds_read_b64 v[92:93], v92
	ds_read_b64 v[94:95], v94
	s_waitcnt lgkmcnt(0)
	v_mfma_f32_16x16x32_bf16 v[88:91], v[92:95], v[56:59], v[88:91]
	v_add_u32_e32 v92, v169, v182
	v_add_u32_e32 v94, v169, v183
	ds_read_b64 v[92:93], v92
	ds_read_b64 v[94:95], v94
	s_waitcnt lgkmcnt(0)
	v_mfma_f32_16x16x32_bf16 v[92:95], v[92:95], v[56:59], v[76:79]
	s_nop 2
	v_add_u32_e32 v76, v172, v176
	v_add_u32_e32 v78, v172, v177
	ds_read_b64 v[76:77], v76
	ds_read_b64 v[78:79], v78
	s_waitcnt lgkmcnt(0)
	v_mfma_f32_16x16x32_bf16 v[72:75], v[76:79], v[56:59], v[72:75]
	v_add_u32_e32 v76, v173, v178
	v_add_u32_e32 v78, v173, v179
	ds_read_b64 v[76:77], v76
	ds_read_b64 v[78:79], v78
	s_waitcnt lgkmcnt(0)
	v_mfma_f32_16x16x32_bf16 v[68:71], v[76:79], v[56:59], v[68:71]
	v_add_u32_e32 v76, v174, v180
	v_add_u32_e32 v78, v174, v181
	ds_read_b64 v[76:77], v76
	ds_read_b64 v[78:79], v78
	s_waitcnt lgkmcnt(0)
	v_mfma_f32_16x16x32_bf16 v[64:67], v[76:79], v[56:59], v[64:67]
	v_add_u32_e32 v76, v175, v182
	v_add_u32_e32 v78, v175, v183
	ds_read_b64 v[76:77], v76
	ds_read_b64 v[78:79], v78
	s_waitcnt lgkmcnt(0)
; #define LAS __attribute__((address_space(3)))
; #define MFMA16(a, b, c) __builtin_amdgcn_mfma_f32_16x16x32_bf16((a), (b), (c), 0, 0, 0)
; __device__ __forceinline__ void ret_unit(LAS unsigned char* lds, int u, const bf16* PROJ, const int* pos, const float* dec_f, const float* dec_b, const bf16* ST,
;                                          const float* gn_w, const float* gn_b, bf16* MIX, int tid, const WsRef& wsr) {
;     ...
;     for (int kk = 0; kk < 4; ++kk)
; #pragma unroll
;         for (int n = 0; n < 8; ++n) { const int sw = (2 * n + (fr >> 3)) & 7, jc = kk * 4 + (fq >> 1); const LAS bf16* vr = VT + (n * 16 + fr) * LDT + 4 * (fq & 1);
;             const u32x2 lo = *(const LAS u32x2*)(vr + ((jc ^ sw) << 3)), hi = *(const LAS u32x2*)(vr + (((jc + 2) ^ sw) << 3)); u32x4 w; w.x = lo.x; w.y = lo.y; w.z = hi.x; w.w = hi.y;
;             o[n] = MFMA16(__builtin_bit_cast(bf16x8, w), pf[kk], o[n]); }
;     __syncthreads();
; #pragma unroll
;     for (int i = 0; i < 4; ++i) { const int id = tid + 512 * i, e = id >> 4, dch = id & 15;
;         *(LAS u32x4*)(Ks + e * LDT + dch * 8) = sf[i]; *(LAS u32x4*)(VT + e * LDT + dch * 8) = sb[i]; }
;     __syncthreads();
;     {
;         f32x4 tf[8], tb[8];
; #pragma unroll
;         for (int n = 0; n < 8; ++n) { tf[n] = (f32x4){0.f, 0.f, 0.f, 0.f}; tb[n] = (f32x4){0.f, 0.f, 0.f, 0.f}; }
; #pragma unroll
;         for (int kk = 0; kk < 4; ++kk)
; #pragma unroll
;             for (int n = 0; n < 8; ++n) { const bf16x8 yf = *(const LAS bf16x8*)(Ks + (n * 16 + fr) * LDT + kk * 32 + fq * 8); const bf16x8 yb = *(const LAS bf16x8*)(VT + (n * 16 + fr) * LDT + kk * 32 + fq * 8);
;                 tf[n] = MFMA16(yf, qf[kk], tf[n]); tb[n] = MFMA16(yb, qf[kk], tb[n]); }
	v_mfma_f32_16x16x32_bf16 v[56:59], v[76:79], v[56:59], v[60:63]
	v_add_u32_e32 v76, v163, v186
	v_add_u32_e32 v78, v163, v187
	ds_read_b64 v[76:77], v76
	ds_read_b64 v[78:79], v78
	s_waitcnt lgkmcnt(0)
	v_mfma_f32_16x16x32_bf16 v[76:79], v[76:79], v[52:55], v[80:83]
	s_nop 2
	v_add_u32_e32 v80, v166, v188
	v_add_u32_e32 v82, v166, v189
	ds_read_b64 v[80:81], v80
	ds_read_b64 v[82:83], v82
	s_waitcnt lgkmcnt(0)
	v_mfma_f32_16x16x32_bf16 v[80:83], v[80:83], v[52:55], v[88:91]
	s_nop 2
	v_add_u32_e32 v88, v172, v184
	v_add_u32_e32 v90, v172, v185
	ds_read_b64 v[88:89], v88
	ds_read_b64 v[90:91], v90
	s_waitcnt lgkmcnt(0)
	v_mfma_f32_16x16x32_bf16 v[72:75], v[88:91], v[52:55], v[72:75]
	v_add_u32_e32 v88, v173, v186
	v_add_u32_e32 v90, v173, v187
	v_add_u32_e32 v60, v160, v184
	v_add_u32_e32 v62, v160, v185
	ds_read_b64 v[88:89], v88
	ds_read_b64 v[90:91], v90
	ds_read_b64 v[60:61], v60
	ds_read_b64 v[62:63], v62
	s_waitcnt lgkmcnt(2)
	v_mfma_f32_16x16x32_bf16 v[88:91], v[88:91], v[52:55], v[68:71]
	s_nop 2
	v_add_u32_e32 v68, v174, v188
	v_add_u32_e32 v70, v174, v189
	ds_read_b64 v[68:69], v68
	ds_read_b64 v[70:71], v70
	s_waitcnt lgkmcnt(2)
	v_mfma_f32_16x16x32_bf16 v[60:63], v[60:63], v[52:55], v[84:87]
	s_nop 2
	v_add_u32_e32 v84, v169, v190
	v_add_u32_e32 v86, v169, v191
	ds_read_b64 v[84:85], v84
	ds_read_b64 v[86:87], v86
	s_waitcnt lgkmcnt(0)
	v_mfma_f32_16x16x32_bf16 v[84:87], v[84:87], v[52:55], v[92:95]
	v_mfma_f32_16x16x32_bf16 v[92:95], v[68:71], v[52:55], v[64:67]
	v_add_u32_e32 v68, v172, v192
	v_add_u32_e32 v70, v172, v193
	ds_read_b64 v[68:69], v68
	ds_read_b64 v[70:71], v70
	v_add_u32_e32 v64, v175, v190
	v_add_u32_e32 v66, v175, v191
	ds_read_b64 v[64:65], v64
	ds_read_b64 v[66:67], v66
	s_waitcnt lgkmcnt(0)
	v_mfma_f32_16x16x32_bf16 v[232:235], v[64:67], v[52:55], v[56:59]
	v_add_u32_e32 v52, v160, v192
	v_add_u32_e32 v54, v160, v193
	ds_read_b64 v[52:53], v52
	ds_read_b64 v[54:55], v54
	v_add_u32_e32 v56, v163, v194
	v_add_u32_e32 v58, v163, v195
	ds_read_b64 v[56:57], v56
	ds_read_b64 v[58:59], v58
	s_waitcnt lgkmcnt(2)
	v_mfma_f32_16x16x32_bf16 v[52:55], v[52:55], v[48:51], v[60:63]
	s_nop 2
	v_add_u32_e32 v60, v166, v196
	v_add_u32_e32 v62, v166, v197
	ds_read_b64 v[60:61], v60
	ds_read_b64 v[62:63], v62
	v_add_u32_e32 v64, v169, v198
	v_add_u32_e32 v66, v169, v199
	s_waitcnt lgkmcnt(2)
	v_mfma_f32_16x16x32_bf16 v[56:59], v[56:59], v[48:51], v[76:79]
	ds_read_b64 v[64:65], v64
	ds_read_b64 v[66:67], v66
	s_waitcnt lgkmcnt(2)
	v_mfma_f32_16x16x32_bf16 v[60:63], v[60:63], v[48:51], v[80:83]
	v_add_u32_e32 v76, v174, v196
	v_add_u32_e32 v78, v174, v197
	s_nop 0
	v_add_u32_e32 v80, v175, v198
	v_mfma_f32_16x16x32_bf16 v[68:71], v[68:71], v[48:51], v[72:75]
	v_add_u32_e32 v82, v175, v199
	ds_read_b64 v[76:77], v76
	ds_read_b64 v[78:79], v78
	v_add_u32_e32 v72, v173, v194
	v_add_u32_e32 v74, v173, v195
	ds_read_b64 v[72:73], v72
	ds_read_b64 v[74:75], v74
	ds_read_b64 v[80:81], v80
	ds_read_b64 v[82:83], v82
	s_waitcnt lgkmcnt(0)
	s_barrier
	ds_write_b128 v200, v[4:7] offset:34816
	ds_write_b128 v201, v[12:15]
	ds_write_b128 v202, v[8:11] offset:34816
	ds_write_b128 v203, v[16:19]
	ds_write_b128 v205, v[24:27] offset:34816
	ds_write_b128 v206, v[20:23]
	ds_write_b128 v207, v[32:35] offset:34816
	ds_write_b128 v208, v[36:39]
	s_waitcnt lgkmcnt(0)
	s_barrier
	ds_read_b128 v[4:7], v209 offset:34816
	ds_read_b128 v[8:11], v210
	s_waitcnt lgkmcnt(1)
	v_mfma_f32_16x16x32_bf16 v[12:15], v[4:7], v[44:47], 0
	s_waitcnt lgkmcnt(0)
	v_mfma_f32_16x16x32_bf16 v[16:19], v[8:11], v[44:47], 0
	ds_read_b128 v[4:7], v209 offset:39168
	ds_read_b128 v[8:11], v211
	s_waitcnt lgkmcnt(1)
	v_mfma_f32_16x16x32_bf16 v[32:35], v[4:7], v[44:47], 0
	s_waitcnt lgkmcnt(0)
	v_mfma_f32_16x16x32_bf16 v[36:39], v[8:11], v[44:47], 0
	ds_read_b128 v[4:7], v209 offset:43520
	ds_read_b128 v[8:11], v212
	v_mfma_f32_16x16x32_bf16 v[72:75], v[72:75], v[48:51], v[88:91]
	v_mfma_f32_16x16x32_bf16 v[76:79], v[76:79], v[48:51], v[92:95]
	s_waitcnt lgkmcnt(1)
	v_mfma_f32_16x16x32_bf16 v[88:91], v[4:7], v[44:47], 0
	s_waitcnt lgkmcnt(0)
	v_mfma_f32_16x16x32_bf16 v[92:95], v[8:11], v[44:47], 0
	ds_read_b128 v[4:7], v209 offset:47872
	ds_read_b128 v[8:11], v213
	v_mfma_f32_16x16x32_bf16 v[64:67], v[64:67], v[48:51], v[84:87]
	v_mfma_f32_16x16x32_bf16 v[48:51], v[80:83], v[48:51], v[232:235]
	s_waitcnt lgkmcnt(1)
	v_mfma_f32_16x16x32_bf16 v[232:235], v[4:7], v[44:47], 0
	s_waitcnt lgkmcnt(0)
	v_mfma_f32_16x16x32_bf16 v[236:239], v[8:11], v[44:47], 0
	ds_read_b128 v[4:7], v209 offset:52224
	ds_read_b128 v[8:11], v214
	s_waitcnt lgkmcnt(1)
	v_mfma_f32_16x16x32_bf16 v[240:243], v[4:7], v[44:47], 0
	s_waitcnt lgkmcnt(0)
	v_mfma_f32_16x16x32_bf16 v[244:247], v[8:11], v[44:47], 0
	ds_read_b128 v[4:7], v209 offset:56576
	ds_read_b128 v[8:11], v215
	s_waitcnt lgkmcnt(1)
	v_mfma_f32_16x16x32_bf16 v[80:83], v[4:7], v[44:47], 0
	s_waitcnt lgkmcnt(0)
	v_mfma_f32_16x16x32_bf16 v[84:87], v[8:11], v[44:47], 0
	ds_read_b128 v[4:7], v209 offset:60928
	ds_read_b128 v[8:11], v216
	s_waitcnt lgkmcnt(1)
	v_mfma_f32_16x16x32_bf16 v[20:23], v[4:7], v[44:47], 0
	ds_read_b128 v[4:7], v209 offset:65280
	ds_read_b128 v[248:251], v217
	s_waitcnt lgkmcnt(2)
	v_mfma_f32_16x16x32_bf16 v[24:27], v[8:11], v[44:47], 0
	s_waitcnt lgkmcnt(1)
	v_mfma_f32_16x16x32_bf16 v[8:11], v[4:7], v[44:47], 0
	s_waitcnt lgkmcnt(0)
	v_mfma_f32_16x16x32_bf16 v[4:7], v[248:251], v[44:47], 0
	ds_read_b128 v[44:47], v209 offset:34880
	ds_read_b128 v[248:251], v210 offset:64
	s_waitcnt lgkmcnt(1)
	v_mfma_f32_16x16x32_bf16 v[12:15], v[44:47], v[40:43], v[12:15]
	s_waitcnt lgkmcnt(0)
; #define LAS __attribute__((address_space(3)))
; #define MFMA16(a, b, c) __builtin_amdgcn_mfma_f32_16x16x32_bf16((a), (b), (c), 0, 0, 0)
; __device__ __forceinline__ void ret_unit(LAS unsigned char* lds, int u, const bf16* PROJ, const int* pos, const float* dec_f, const float* dec_b, const bf16* ST,
;                                          const float* gn_w, const float* gn_b, bf16* MIX, int tid, const WsRef& wsr) {
;     ...
; #pragma unroll
;         for (int kk = 0; kk < 4; ++kk)
; #pragma unroll
;             for (int n = 0; n < 8; ++n) { const bf16x8 yf = *(const LAS bf16x8*)(Ks + (n * 16 + fr) * LDT + kk * 32 + fq * 8); const bf16x8 yb = *(const LAS bf16x8*)(VT + (n * 16 + fr) * LDT + kk * 32 + fq * 8);
;                 tf[n] = MFMA16(yf, qf[kk], tf[n]); tb[n] = MFMA16(yb, qf[kk], tb[n]); }
	v_mfma_f32_16x16x32_bf16 v[16:19], v[248:251], v[40:43], v[16:19]
	ds_read_b128 v[44:47], v209 offset:39232
	ds_read_b128 v[248:251], v211 offset:64
	s_waitcnt lgkmcnt(1)
	v_mfma_f32_16x16x32_bf16 v[32:35], v[44:47], v[40:43], v[32:35]
	s_waitcnt lgkmcnt(0)
	v_mfma_f32_16x16x32_bf16 v[36:39], v[248:251], v[40:43], v[36:39]
	ds_read_b128 v[44:47], v209 offset:43584
	ds_read_b128 v[248:251], v212 offset:64
	s_waitcnt lgkmcnt(1)
	v_mfma_f32_16x16x32_bf16 v[44:47], v[44:47], v[40:43], v[88:91]
	s_waitcnt lgkmcnt(0)
	v_mfma_f32_16x16x32_bf16 v[88:91], v[248:251], v[40:43], v[92:95]
	s_nop 2
	ds_read_b128 v[92:95], v209 offset:47936
	ds_read_b128 v[248:251], v213 offset:64
	s_waitcnt lgkmcnt(1)
	v_mfma_f32_16x16x32_bf16 v[92:95], v[92:95], v[40:43], v[232:235]
	s_waitcnt lgkmcnt(0)
	v_mfma_f32_16x16x32_bf16 v[232:235], v[248:251], v[40:43], v[236:239]
	s_nop 2
	ds_read_b128 v[236:239], v209 offset:52288
	ds_read_b128 v[248:251], v214 offset:64
	s_waitcnt lgkmcnt(1)
	v_mfma_f32_16x16x32_bf16 v[236:239], v[236:239], v[40:43], v[240:243]
	s_waitcnt lgkmcnt(0)
	v_mfma_f32_16x16x32_bf16 v[240:243], v[248:251], v[40:43], v[244:247]
	s_nop 2
	ds_read_b128 v[244:247], v209 offset:56640
	ds_read_b128 v[248:251], v215 offset:64
	s_waitcnt lgkmcnt(1)
	v_mfma_f32_16x16x32_bf16 v[80:83], v[244:247], v[40:43], v[80:83]
	s_waitcnt lgkmcnt(0)
	v_mfma_f32_16x16x32_bf16 v[84:87], v[248:251], v[40:43], v[84:87]
	ds_read_b128 v[244:247], v209 offset:60992
	ds_read_b128 v[248:251], v216 offset:64
	s_waitcnt lgkmcnt(1)
	v_mfma_f32_16x16x32_bf16 v[244:247], v[244:247], v[40:43], v[20:23]
	s_waitcnt lgkmcnt(0)
	v_mfma_f32_16x16x32_bf16 v[248:251], v[248:251], v[40:43], v[24:27]
	s_nop 0
	ds_read_b128 v[20:23], v209 offset:65344
	s_nop 0
	ds_read_b128 v[24:27], v217 offset:64
	s_waitcnt lgkmcnt(1)
	v_mfma_f32_16x16x32_bf16 v[8:11], v[20:23], v[40:43], v[8:11]
	s_waitcnt lgkmcnt(0)
	v_mfma_f32_16x16x32_bf16 v[4:7], v[24:27], v[40:43], v[4:7]
	ds_read_b128 v[20:23], v209 offset:34944
	ds_read_b128 v[24:27], v210 offset:128
	s_waitcnt lgkmcnt(1)
	v_mfma_f32_16x16x32_bf16 v[40:43], v[20:23], v[28:31], v[12:15]
	s_waitcnt lgkmcnt(0)
	v_mfma_f32_16x16x32_bf16 v[130:133], v[24:27], v[28:31], v[16:19]
	s_nop 0
	ds_read_b128 v[12:15], v209 offset:39296
	s_nop 0
	ds_read_b128 v[16:19], v211 offset:128
	s_waitcnt lgkmcnt(1)
	v_mfma_f32_16x16x32_bf16 v[32:35], v[12:15], v[28:31], v[32:35]
	s_waitcnt lgkmcnt(0)
	v_mfma_f32_16x16x32_bf16 v[36:39], v[16:19], v[28:31], v[36:39]
	ds_read_b128 v[12:15], v209 offset:43648
	ds_read_b128 v[16:19], v212 offset:128
	s_waitcnt lgkmcnt(1)
	v_mfma_f32_16x16x32_bf16 v[44:47], v[12:15], v[28:31], v[44:47]
	s_waitcnt lgkmcnt(0)
	v_mfma_f32_16x16x32_bf16 v[88:91], v[16:19], v[28:31], v[88:91]
	ds_read_b128 v[12:15], v209 offset:48000
	ds_read_b128 v[16:19], v213 offset:128
	s_waitcnt lgkmcnt(1)
	v_mfma_f32_16x16x32_bf16 v[92:95], v[12:15], v[28:31], v[92:95]
	s_waitcnt lgkmcnt(0)
	v_mfma_f32_16x16x32_bf16 v[232:235], v[16:19], v[28:31], v[232:235]
	ds_read_b128 v[12:15], v209 offset:52352
	ds_read_b128 v[16:19], v214 offset:128
	s_waitcnt lgkmcnt(1)
	v_mfma_f32_16x16x32_bf16 v[236:239], v[12:15], v[28:31], v[236:239]
	s_waitcnt lgkmcnt(0)
	v_mfma_f32_16x16x32_bf16 v[240:243], v[16:19], v[28:31], v[240:243]
	ds_read_b128 v[12:15], v209 offset:56704
	ds_read_b128 v[16:19], v215 offset:128
	s_waitcnt lgkmcnt(1)
	v_mfma_f32_16x16x32_bf16 v[20:23], v[12:15], v[28:31], v[80:83]
	s_waitcnt lgkmcnt(0)
	v_mfma_f32_16x16x32_bf16 v[24:27], v[16:19], v[28:31], v[84:87]
	ds_read_b128 v[12:15], v209 offset:61056
	ds_read_b128 v[16:19], v216 offset:128
	ds_read_b128 v[80:83], v209 offset:65408
	ds_read_b128 v[84:87], v217 offset:128
	s_waitcnt lgkmcnt(3)
	v_mfma_f32_16x16x32_bf16 v[12:15], v[12:15], v[28:31], v[244:247]
	s_waitcnt lgkmcnt(2)
	v_mfma_f32_16x16x32_bf16 v[16:19], v[16:19], v[28:31], v[248:251]
	s_waitcnt lgkmcnt(1)
	v_mfma_f32_16x16x32_bf16 v[8:11], v[80:83], v[28:31], v[8:11]
	s_waitcnt lgkmcnt(0)
	v_mfma_f32_16x16x32_bf16 v[4:7], v[84:87], v[28:31], v[4:7]
	ds_read_b128 v[28:31], v209 offset:35008
	ds_read_b128 v[80:83], v210 offset:192
	s_waitcnt lgkmcnt(1)
	v_mfma_f32_16x16x32_bf16 v[28:31], v[28:31], v[0:3], v[40:43]
	s_waitcnt lgkmcnt(0)
	v_mfma_f32_16x16x32_bf16 v[40:43], v[80:83], v[0:3], v[130:133]
	ds_read_b128 v[80:83], v209 offset:39360
	ds_read_b128 v[84:87], v211 offset:192
	s_waitcnt lgkmcnt(1)
	v_mfma_f32_16x16x32_bf16 v[80:83], v[80:83], v[0:3], v[32:35]
	s_waitcnt lgkmcnt(0)
	v_mfma_f32_16x16x32_bf16 v[34:37], v[84:87], v[0:3], v[36:39]
	ds_read_b128 v[84:87], v209 offset:43712
	ds_read_b128 v[130:133], v212 offset:192
	s_waitcnt lgkmcnt(1)
	v_mfma_f32_16x16x32_bf16 v[44:47], v[84:87], v[0:3], v[44:47]
	s_waitcnt lgkmcnt(0)
	v_mfma_f32_16x16x32_bf16 v[84:87], v[130:133], v[0:3], v[88:91]
	s_nop 2
	ds_read_b128 v[88:91], v209 offset:48064
	ds_read_b128 v[130:133], v213 offset:192
	s_waitcnt lgkmcnt(1)
	v_mfma_f32_16x16x32_bf16 v[88:91], v[88:91], v[0:3], v[92:95]
	s_waitcnt lgkmcnt(0)
	v_mfma_f32_16x16x32_bf16 v[92:95], v[130:133], v[0:3], v[232:235]
	ds_read_b128 v[130:133], v209 offset:52416
	s_nop 1
	ds_read_b128 v[232:235], v214 offset:192
	s_waitcnt lgkmcnt(1)
	v_mfma_f32_16x16x32_bf16 v[130:133], v[130:133], v[0:3], v[236:239]
	s_waitcnt lgkmcnt(0)
	v_mfma_f32_16x16x32_bf16 v[232:235], v[232:235], v[0:3], v[240:243]
	s_nop 0
	ds_read_b128 v[236:239], v209 offset:56768
	s_nop 0
	ds_read_b128 v[240:243], v215 offset:192
	s_waitcnt lgkmcnt(1)
	v_mfma_f32_16x16x32_bf16 v[236:239], v[236:239], v[0:3], v[20:23]
	s_waitcnt lgkmcnt(0)
	v_mfma_f32_16x16x32_bf16 v[240:243], v[240:243], v[0:3], v[24:27]
	s_nop 0
	ds_read_b128 v[20:23], v209 offset:61120
	s_nop 0
	ds_read_b128 v[24:27], v216 offset:192
	s_waitcnt lgkmcnt(1)
; __device__ __forceinline__ float fexp2(float x) { return __builtin_amdgcn_exp2f(x); }
; #define MFMA16(a, b, c) __builtin_amdgcn_mfma_f32_16x16x32_bf16((a), (b), (c), 0, 0, 0)
; __device__ __forceinline__ void ret_unit(LAS unsigned char* lds, int u, const bf16* PROJ, const int* pos, const float* dec_f, const float* dec_b, const bf16* ST,
;                                          const float* gn_w, const float* gn_b, bf16* MIX, int tid, const WsRef& wsr) {
;     ...
;                 tf[n] = MFMA16(yf, qf[kk], tf[n]); tb[n] = MFMA16(yb, qf[kk], tb[n]); }
;         const float xif = fexp2(lgf2 * (float)(q + 1)), xib = fexp2(lgb2 * (float)(128 - q));
; #pragma unroll
;         for (int n = 0; n < 8; ++n) o[n] = o[n] + tf[n] * xif + tb[n] * xib;
;     }
;     float sm = 0.f;
; #pragma unroll
;     for (int n = 0; n < 8; ++n) sm += (o[n][0] + o[n][1]) + (o[n][2] + o[n][3]);
;     sm += __shfl_xor(sm, 16); sm += __shfl_xor(sm, 32);
	v_mfma_f32_16x16x32_bf16 v[12:15], v[20:23], v[0:3], v[12:15]
	s_waitcnt lgkmcnt(0)
	v_mfma_f32_16x16x32_bf16 v[244:247], v[24:27], v[0:3], v[16:19]
	s_nop 2
	ds_read_b128 v[16:19], v209 offset:65472
	ds_read_b128 v[20:23], v217 offset:192
	s_waitcnt lgkmcnt(1)
	v_mfma_f32_16x16x32_bf16 v[8:11], v[16:19], v[0:3], v[8:11]
	s_waitcnt lgkmcnt(0)
	v_mfma_f32_16x16x32_bf16 v[248:251], v[20:23], v[0:3], v[4:7]
	v_mul_f32_e32 v0, v105, v218
	v_exp_f32_e32 v38, v0
	v_mul_f32_e32 v0, v230, v219
	v_exp_f32_e32 v230, v0
	v_pk_fma_f32 v[2:3], v[38:39], v[28:29], v[52:53] op_sel_hi:[0,1,1]
	v_pk_fma_f32 v[16:17], v[38:39], v[132:133], v[70:71] op_sel_hi:[0,1,1]
	v_pk_fma_f32 v[0:1], v[38:39], v[30:31], v[54:55] op_sel_hi:[0,1,1]
	v_pk_fma_f32 v[32:33], v[230:231], v[40:41], v[2:3] op_sel_hi:[0,1,1]
	v_pk_fma_f32 v[2:3], v[38:39], v[80:81], v[56:57] op_sel_hi:[0,1,1]
	v_pk_fma_f32 v[18:19], v[38:39], v[130:131], v[68:69] op_sel_hi:[0,1,1]
	v_pk_fma_f32 v[22:23], v[230:231], v[234:235], v[16:17] op_sel_hi:[0,1,1]
	v_pk_fma_f32 v[16:17], v[38:39], v[238:239], v[74:75] op_sel_hi:[0,1,1]
	v_pk_fma_f32 v[12:13], v[38:39], v[12:13], v[76:77] op_sel_hi:[0,1,1]
	v_pk_fma_f32 v[30:31], v[230:231], v[42:43], v[0:1] op_sel_hi:[0,1,1]
	v_pk_fma_f32 v[0:1], v[38:39], v[82:83], v[58:59] op_sel_hi:[0,1,1]
	v_pk_fma_f32 v[28:29], v[230:231], v[34:35], v[2:3] op_sel_hi:[0,1,1]
	v_pk_fma_f32 v[24:25], v[230:231], v[232:233], v[18:19] op_sel_hi:[0,1,1]
	v_pk_fma_f32 v[18:19], v[230:231], v[242:243], v[16:17] op_sel_hi:[0,1,1]
	v_pk_fma_f32 v[16:17], v[230:231], v[244:245], v[12:13] op_sel_hi:[0,1,1]
	v_pk_fma_f32 v[10:11], v[38:39], v[10:11], v[50:51] op_sel_hi:[0,1,1]
	v_pk_fma_f32 v[12:13], v[38:39], v[8:9], v[48:49] op_sel_hi:[0,1,1]
	v_pk_fma_f32 v[26:27], v[230:231], v[36:37], v[0:1] op_sel_hi:[0,1,1]
	v_pk_fma_f32 v[8:9], v[230:231], v[250:251], v[10:11] op_sel_hi:[0,1,1]
	v_pk_fma_f32 v[10:11], v[230:231], v[248:249], v[12:13] op_sel_hi:[0,1,1]
	v_mov_b32_e32 v12, v32
	v_mov_b32_e32 v13, v28
	v_mov_b32_e32 v34, v33
	v_mov_b32_e32 v35, v29
	v_pk_fma_f32 v[0:1], v[38:39], v[46:47], v[62:63] op_sel_hi:[0,1,1]
	v_pk_fma_f32 v[2:3], v[38:39], v[44:45], v[60:61] op_sel_hi:[0,1,1]
	v_pk_add_f32 v[12:13], v[12:13], v[34:35]
	v_mov_b32_e32 v34, v30
	v_mov_b32_e32 v35, v26
	v_mov_b32_e32 v36, v31
	v_mov_b32_e32 v37, v27
	v_pk_fma_f32 v[4:5], v[230:231], v[86:87], v[0:1] op_sel_hi:[0,1,1]
	v_pk_fma_f32 v[6:7], v[230:231], v[84:85], v[2:3] op_sel_hi:[0,1,1]
	v_pk_add_f32 v[34:35], v[34:35], v[36:37]
	v_mov_b32_e32 v36, v6
	v_pk_add_f32 v[12:13], v[12:13], v[34:35]
	v_pk_mov_b32 v[34:35], v[6:7], v[4:5] op_sel:[1,0]
	v_mov_b32_e32 v37, v5
	v_pk_fma_f32 v[0:1], v[38:39], v[90:91], v[66:67] op_sel_hi:[0,1,1]
	v_pk_fma_f32 v[2:3], v[38:39], v[88:89], v[64:65] op_sel_hi:[0,1,1]
	v_pk_add_f32 v[34:35], v[34:35], v[36:37]
	v_pk_fma_f32 v[0:1], v[230:231], v[94:95], v[0:1] op_sel_hi:[0,1,1]
	v_pk_fma_f32 v[2:3], v[230:231], v[92:93], v[2:3] op_sel_hi:[0,1,1]
	v_add_f32_e32 v12, 0, v12
	v_pk_add_f32 v[34:35], v[34:35], v[34:35] op_sel:[0,1] op_sel_hi:[1,0]
	v_pk_fma_f32 v[20:21], v[38:39], v[236:237], v[72:73] op_sel_hi:[0,1,1]
	v_pk_fma_f32 v[14:15], v[38:39], v[14:15], v[78:79] op_sel_hi:[0,1,1]
	v_add_f32_e32 v12, v12, v13
	v_add_f32_e32 v36, v2, v3
	v_add_f32_e32 v38, v0, v1
	v_mov_b32_e32 v13, v24
	v_mov_b32_e32 v35, v25
	v_mov_b32_e32 v37, v22
	v_mov_b32_e32 v39, v23
	v_pk_fma_f32 v[20:21], v[230:231], v[240:241], v[20:21] op_sel_hi:[0,1,1]
	v_pk_add_f32 v[12:13], v[12:13], v[34:35]
	v_pk_add_f32 v[34:35], v[36:37], v[38:39]
	v_mov_b32_e32 v36, v20
	v_pk_add_f32 v[12:13], v[12:13], v[34:35]
	v_pk_mov_b32 v[34:35], v[20:21], v[18:19] op_sel:[1,0]
	v_mov_b32_e32 v37, v19
	v_pk_add_f32 v[34:35], v[34:35], v[36:37]
	v_pk_fma_f32 v[14:15], v[230:231], v[246:247], v[14:15] op_sel_hi:[0,1,1]
	v_pk_add_f32 v[12:13], v[12:13], v[12:13] op_sel:[0,1] op_sel_hi:[1,0]
	v_pk_add_f32 v[34:35], v[34:35], v[34:35] op_sel:[0,1] op_sel_hi:[1,0]
	v_add_f32_e32 v36, v16, v17
	v_add_f32_e32 v38, v14, v15
	v_mov_b32_e32 v13, v10
	v_mov_b32_e32 v35, v11
	v_mov_b32_e32 v37, v8
	v_mov_b32_e32 v39, v9
	v_pk_add_f32 v[12:13], v[12:13], v[34:35]
	v_pk_add_f32 v[34:35], v[36:37], v[38:39]
	v_or_b32_e32 v48, s0, v126
	v_pk_add_f32 v[12:13], v[12:13], v[34:35]
	v_mov_b32_e32 v49, v97
	v_add_f32_e32 v12, v12, v13
	ds_bpermute_b32 v13, v220, v12
	s_waitcnt lgkmcnt(0)
	v_add_f32_e32 v12, v12, v13
	ds_bpermute_b32 v13, v221, v12
	s_waitcnt lgkmcnt(0)
; __device__ __forceinline__ float bflo(unsigned w) { return __uint_as_float(w << 16); }
; __device__ __forceinline__ float bfhi(unsigned w) { return __uint_as_float(w & 0xffff0000u); }
; __device__ __forceinline__ void ret_unit(LAS unsigned char* lds, int u, const bf16* PROJ, const int* pos, const float* dec_f, const float* dec_b, const bf16* ST,
;                                          const float* gn_w, const float* gn_b, bf16* MIX, int tid, const WsRef& wsr) {
;     ...
;     const float mu = sm * (1.f / 128.f);
;     float vq = 0.f;
; #pragma unroll
;     for (int n = 0; n < 8; ++n) { const f32x4 d = o[n] - mu; vq += (d[0] * d[0] + d[1] * d[1]) + (d[2] * d[2] + d[3] * d[3]); }
;     vq += __shfl_xor(vq, 16); vq += __shfl_xor(vq, 32);
;     const float rstd = rsqrtf(vq * (1.f / 128.f) + EPS);
;     const size_t row = row0 + q;
; #pragma unroll
;     for (int n = 0; n < 8; ++n) { const int col = h * 128 + n * 16 + 4 * fq;
;         const f32x4 gw = *(const f32x4*)(gn_w + col), gb = *(const f32x4*)(gn_b + col);
;         const u32x2 gg = *(const u32x2*)(PROJ + row * INC + 1536 + col);
;         const f32x4 g = (f32x4){bflo(gg.x), bfhi(gg.x), bflo(gg.y), bfhi(gg.y)};
;         f32x4 y = (o[n] - mu) * rstd * gw + gb;
	v_add_f32_e32 v40, v12, v13
	v_fmamk_f32 v33, v40, 0xbc000000, v33
	v_fmamk_f32 v29, v40, 0xbc000000, v29
	v_fmamk_f32 v31, v40, 0xbc000000, v31
	v_fmac_f32_e32 v32, 0xbc000000, v40
	v_fmamk_f32 v27, v40, 0xbc000000, v27
	v_fmac_f32_e32 v28, 0xbc000000, v40
	v_mov_b32_e32 v34, v33
	v_mov_b32_e32 v35, v29
	v_fmac_f32_e32 v30, 0xbc000000, v40
	v_fmac_f32_e32 v26, 0xbc000000, v40
	v_mov_b32_e32 v12, v32
	v_mov_b32_e32 v13, v28
	v_pk_mul_f32 v[34:35], v[34:35], v[34:35]
	v_mov_b32_e32 v36, v31
	v_mov_b32_e32 v37, v27
	v_pk_fma_f32 v[12:13], v[12:13], v[12:13], v[34:35]
	v_mov_b32_e32 v34, v30
	v_mov_b32_e32 v35, v26
	v_pk_mul_f32 v[36:37], v[36:37], v[36:37]
	v_fmamk_f32 v7, v40, 0xbc000000, v7
	v_pk_fma_f32 v[34:35], v[34:35], v[34:35], v[36:37]
	v_fmac_f32_e32 v6, 0xbc000000, v40
	v_pk_add_f32 v[12:13], v[12:13], v[34:35]
	v_fmamk_f32 v5, v40, 0xbc000000, v5
	v_fmac_f32_e32 v4, 0xbc000000, v40
	v_pk_add_f32 v[12:13], v[12:13], v[12:13] op_sel_hi:[0,1]
	v_pk_mul_f32 v[34:35], v[4:5], v[4:5]
	v_pk_mul_f32 v[36:37], v[6:7], v[6:7]
	v_fmac_f32_e32 v2, 0xbc000000, v40
	v_pk_mov_b32 v[38:39], v[36:37], v[34:35] op_sel:[1,0]
	v_mov_b32_e32 v37, v35
	v_fmamk_f32 v3, v40, 0xbc000000, v3
	v_fmac_f32_e32 v0, 0xbc000000, v40
	v_mul_f32_e32 v12, v2, v2
	v_pk_add_f32 v[34:35], v[38:39], v[36:37]
	v_fmamk_f32 v1, v40, 0xbc000000, v1
	v_pk_fma_f32 v[36:37], v[2:3], v[2:3], v[12:13] op_sel_hi:[1,1,0]
	v_mul_f32_e32 v12, v0, v0
	v_pk_add_f32 v[34:35], v[34:35], v[34:35] op_sel_hi:[0,1]
	v_pk_fma_f32 v[38:39], v[0:1], v[0:1], v[12:13] op_sel_hi:[1,1,0]
	v_fmamk_f32 v23, v40, 0xbc000000, v23
	v_fmac_f32_e32 v22, 0xbc000000, v40
	v_fmamk_f32 v25, v40, 0xbc000000, v25
	v_fmac_f32_e32 v24, 0xbc000000, v40
	v_mul_f32_e32 v36, v24, v24
	v_mul_f32_e32 v38, v25, v25
	v_mul_f32_e32 v34, v22, v22
	v_mul_f32_e32 v12, v23, v23
	v_pk_add_f32 v[36:37], v[36:37], v[38:39]
	v_pk_add_f32 v[12:13], v[34:35], v[12:13]
	v_fmamk_f32 v21, v40, 0xbc000000, v21
	v_pk_add_f32 v[12:13], v[36:37], v[12:13]
	v_fmac_f32_e32 v20, 0xbc000000, v40
	v_fmamk_f32 v19, v40, 0xbc000000, v19
	v_fmac_f32_e32 v18, 0xbc000000, v40
	v_pk_add_f32 v[12:13], v[12:13], v[12:13] op_sel_hi:[0,1]
	v_pk_mul_f32 v[34:35], v[18:19], v[18:19]
	v_pk_mul_f32 v[36:37], v[20:21], v[20:21]
	v_fmac_f32_e32 v16, 0xbc000000, v40
	v_pk_mov_b32 v[38:39], v[36:37], v[34:35] op_sel:[1,0]
	v_mov_b32_e32 v37, v35
	v_fmamk_f32 v17, v40, 0xbc000000, v17
	v_fmac_f32_e32 v14, 0xbc000000, v40
	v_mul_f32_e32 v12, v16, v16
	v_pk_add_f32 v[34:35], v[38:39], v[36:37]
	v_fmamk_f32 v15, v40, 0xbc000000, v15
	v_pk_fma_f32 v[36:37], v[16:17], v[16:17], v[12:13] op_sel_hi:[1,1,0]
	v_mul_f32_e32 v12, v14, v14
	v_pk_add_f32 v[34:35], v[34:35], v[34:35] op_sel_hi:[0,1]
	v_pk_fma_f32 v[38:39], v[14:15], v[14:15], v[12:13] op_sel_hi:[1,1,0]
	v_fmamk_f32 v9, v40, 0xbc000000, v9
	v_fmac_f32_e32 v8, 0xbc000000, v40
	v_fmamk_f32 v11, v40, 0xbc000000, v11
	v_fmac_f32_e32 v10, 0xbc000000, v40
	v_mul_f32_e32 v36, v10, v10
	v_mul_f32_e32 v38, v11, v11
	v_mul_f32_e32 v34, v8, v8
	v_mul_f32_e32 v12, v9, v9
	v_pk_add_f32 v[36:37], v[36:37], v[38:39]
	v_pk_add_f32 v[12:13], v[34:35], v[12:13]
	v_lshl_add_u64 v[34:35], s[4:5], 0, v[102:103]
	v_pk_add_f32 v[12:13], v[36:37], v[12:13]
	v_mov_b64_e32 v[36:37], s[6:7]
	v_add_f32_e32 v12, v12, v13
	ds_bpermute_b32 v13, v220, v12
	s_waitcnt lgkmcnt(0)
	v_add_f32_e32 v12, v12, v13
	ds_bpermute_b32 v13, v221, v12
	s_waitcnt lgkmcnt(0)
	v_add_f32_e32 v12, v12, v13
	v_fmamk_f32 v12, v12, 0x3c000000, v227
	v_cmp_gt_f32_e64 s[68:69], s1, v12
	v_mul_f32_e32 v13, 0x4b800000, v12
	v_mad_u64_u32 v[44:45], s[0:1], v34, s72, v[36:37]
	v_cndmask_b32_e64 v12, v12, v13, s[68:69]
	v_rsq_f32_e32 v12, v12
	v_mad_i32_i24 v45, v35, s72, v45
	v_lshlrev_b64 v[34:35], 11, v[34:35]
	v_lshl_add_u64 v[46:47], s[70:71], 0, v[34:35]
	v_mul_f32_e32 v13, 0x45800000, v12
	v_cndmask_b32_e64 v12, v12, v13, s[68:69]
	v_lshlrev_b32_e32 v13, 2, v48
	v_lshlrev_b32_e32 v48, 1, v48
	v_lshl_add_u64 v[34:35], v[44:45], 0, v[48:49]
	v_lshl_add_u64 v[46:47], v[46:47], 0, v[48:49]
	global_load_dwordx2 v[36:37], v[34:35], off offset:3072
	global_load_dwordx2 v[38:39], v[34:35], off offset:3104
	global_load_dwordx2 v[40:41], v[34:35], off offset:3136
	global_load_dwordx2 v[42:43], v[34:35], off offset:3168
	global_load_dwordx2 v[44:45], v[34:35], off offset:3200
	global_load_dwordx2 v[50:51], v[34:35], off offset:3232
	global_load_dwordx2 v[52:53], v[34:35], off offset:3264
	global_load_dwordx2 v[54:55], v[34:35], off offset:3296
	global_load_dwordx4 v[56:59], v13, s[22:23]
	global_load_dwordx4 v[60:63], v13, s[36:37]
	global_load_dwordx4 v[64:67], v13, s[22:23] offset:64
	global_load_dwordx4 v[68:71], v13, s[36:37] offset:64
	global_load_dwordx4 v[72:75], v13, s[22:23] offset:128
	global_load_dwordx4 v[76:79], v13, s[36:37] offset:128
	global_load_dwordx4 v[80:83], v13, s[22:23] offset:192
	global_load_dwordx4 v[84:87], v13, s[36:37] offset:192
	global_load_dwordx4 v[88:91], v13, s[22:23] offset:256
	global_load_dwordx4 v[92:95], v13, s[36:37] offset:256
	global_load_dwordx4 v[232:235], v13, s[22:23] offset:320
	global_load_dwordx4 v[236:239], v13, s[36:37] offset:320
	global_load_dwordx4 v[240:243], v13, s[22:23] offset:384
	global_load_dwordx4 v[248:251], v13, s[36:37] offset:384
	v_pk_mul_f32 v[32:33], v[32:33], v[12:13] op_sel_hi:[1,0]
	v_pk_mul_f32 v[30:31], v[30:31], v[12:13] op_sel_hi:[1,0]
	v_pk_mul_f32 v[28:29], v[28:29], v[12:13] op_sel_hi:[1,0]
	v_pk_mul_f32 v[26:27], v[26:27], v[12:13] op_sel_hi:[1,0]
	v_pk_mul_f32 v[6:7], v[6:7], v[12:13] op_sel_hi:[1,0]
	v_pk_mul_f32 v[4:5], v[4:5], v[12:13] op_sel_hi:[1,0]
	v_pk_mul_f32 v[2:3], v[2:3], v[12:13] op_sel_hi:[1,0]
	v_pk_mul_f32 v[0:1], v[0:1], v[12:13] op_sel_hi:[1,0]
	v_pk_mul_f32 v[24:25], v[24:25], v[12:13] op_sel_hi:[1,0]
	v_pk_mul_f32 v[22:23], v[22:23], v[12:13] op_sel_hi:[1,0]
	v_pk_mul_f32 v[20:21], v[20:21], v[12:13] op_sel_hi:[1,0]
	v_pk_mul_f32 v[18:19], v[18:19], v[12:13] op_sel_hi:[1,0]
	v_pk_mul_f32 v[16:17], v[16:17], v[12:13] op_sel_hi:[1,0]
	v_pk_mul_f32 v[14:15], v[14:15], v[12:13] op_sel_hi:[1,0]
	v_pk_mul_f32 v[10:11], v[10:11], v[12:13] op_sel_hi:[1,0]
	v_pk_mul_f32 v[8:9], v[8:9], v[12:13] op_sel_hi:[1,0]
	s_waitcnt vmcnt(12)
; __device__ __forceinline__ unsigned pk2(float lo, float hi) { return pg8::cvt_pk_bf16(lo, hi); }
; __device__ __forceinline__ float bflo(unsigned w) { return __uint_as_float(w << 16); }
; __device__ __forceinline__ float bfhi(unsigned w) { return __uint_as_float(w & 0xffff0000u); }
; __device__ __forceinline__ void ret_unit(LAS unsigned char* lds, int u, const bf16* PROJ, const int* pos, const float* dec_f, const float* dec_b, const bf16* ST,
;                                          const float* gn_w, const float* gn_b, bf16* MIX, int tid, const WsRef& wsr) {
;     ...
;     const size_t row = row0 + q;
; #pragma unroll
;     for (int n = 0; n < 8; ++n) { const int col = h * 128 + n * 16 + 4 * fq;
;         const f32x4 gw = *(const f32x4*)(gn_w + col), gb = *(const f32x4*)(gn_b + col);
;         const u32x2 gg = *(const u32x2*)(PROJ + row * INC + 1536 + col);
;         const f32x4 g = (f32x4){bflo(gg.x), bfhi(gg.x), bflo(gg.y), bfhi(gg.y)};
;         f32x4 y = (o[n] - mu) * rstd * gw + gb;
; #pragma unroll
;         for (int r = 0; r < 4; ++r) y[r] = y[r] * g[r] * __builtin_amdgcn_rcpf(1.f + __expf(-g[r]));
;         u32x2 w; w.x = pk2(y[0], y[1]); w.y = pk2(y[2], y[3]); *(u32x2*)(MIX + row * D + col) = w; }
	v_lshlrev_b32_e32 v130, 16, v36
	v_and_b32_e32 v131, 0xffff0000, v36
	v_lshlrev_b32_e32 v132, 16, v37
	v_and_b32_e32 v133, 0xffff0000, v37
	v_pk_fma_f32 v[32:33], v[56:57], v[32:33], v[60:61]
	v_pk_fma_f32 v[30:31], v[58:59], v[30:31], v[62:63]
	global_load_dwordx4 v[56:59], v13, s[22:23] offset:448
	global_load_dwordx4 v[60:63], v13, s[36:37] offset:448
	v_mul_f32_e32 v36, 0xbfb8aa3b, v130
	v_mul_f32_e32 v37, 0xbfb8aa3b, v131
	v_exp_f32_e32 v36, v36
	v_exp_f32_e32 v37, v37
	v_pk_mul_f32 v[32:33], v[32:33], v[130:131]
	v_mul_f32_e32 v130, 0xbfb8aa3b, v132
	v_mul_f32_e32 v131, 0xbfb8aa3b, v133
	v_add_f32_e32 v36, 1.0, v36
	v_add_f32_e32 v37, 1.0, v37
	v_rcp_f32_e32 v36, v36
	v_rcp_f32_e32 v37, v37
	v_exp_f32_e32 v130, v130
	v_exp_f32_e32 v131, v131
	v_pk_mul_f32 v[30:31], v[30:31], v[132:133]
	v_pk_mul_f32 v[32:33], v[36:37], v[32:33]
	v_add_f32_e32 v130, 1.0, v130
	v_add_f32_e32 v131, 1.0, v131
	v_rcp_f32_e32 v130, v130
	v_rcp_f32_e32 v131, v131
	v_cvt_pk_bf16_f32 v32, v32, v33
	s_nop 0
	v_pk_mul_f32 v[30:31], v[130:131], v[30:31]
	s_nop 0
	v_cvt_pk_bf16_f32 v33, v30, v31
	global_store_dwordx2 v[46:47], v[32:33], off
	s_waitcnt vmcnt(13)
	v_lshlrev_b32_e32 v130, 16, v38
	v_and_b32_e32 v131, 0xffff0000, v38
	v_lshlrev_b32_e32 v132, 16, v39
	v_and_b32_e32 v133, 0xffff0000, v39
	v_pk_fma_f32 v[28:29], v[64:65], v[28:29], v[68:69]
	v_pk_fma_f32 v[26:27], v[66:67], v[26:27], v[70:71]
	v_mul_f32_e32 v38, 0xbfb8aa3b, v130
	v_mul_f32_e32 v39, 0xbfb8aa3b, v131
	v_exp_f32_e32 v38, v38
	v_exp_f32_e32 v39, v39
	v_pk_mul_f32 v[28:29], v[28:29], v[130:131]
	v_mul_f32_e32 v130, 0xbfb8aa3b, v132
	v_mul_f32_e32 v131, 0xbfb8aa3b, v133
	v_add_f32_e32 v38, 1.0, v38
	v_add_f32_e32 v39, 1.0, v39
	v_rcp_f32_e32 v38, v38
	v_rcp_f32_e32 v39, v39
	v_exp_f32_e32 v130, v130
	v_exp_f32_e32 v131, v131
	v_pk_mul_f32 v[26:27], v[26:27], v[132:133]
	v_pk_mul_f32 v[28:29], v[38:39], v[28:29]
	v_add_f32_e32 v130, 1.0, v130
	v_add_f32_e32 v131, 1.0, v131
	v_rcp_f32_e32 v130, v130
	v_rcp_f32_e32 v131, v131
	v_cvt_pk_bf16_f32 v28, v28, v29
	s_nop 0
	v_pk_mul_f32 v[26:27], v[130:131], v[26:27]
	s_nop 0
	v_cvt_pk_bf16_f32 v29, v26, v27
	global_store_dwordx2 v[46:47], v[28:29], off offset:32
	s_waitcnt vmcnt(12)
	v_lshlrev_b32_e32 v130, 16, v40
	v_and_b32_e32 v131, 0xffff0000, v40
	v_lshlrev_b32_e32 v132, 16, v41
	v_and_b32_e32 v133, 0xffff0000, v41
	v_pk_fma_f32 v[6:7], v[72:73], v[6:7], v[76:77]
	v_pk_fma_f32 v[4:5], v[74:75], v[4:5], v[78:79]
	v_mul_f32_e32 v40, 0xbfb8aa3b, v130
	v_mul_f32_e32 v41, 0xbfb8aa3b, v131
	v_exp_f32_e32 v40, v40
	v_exp_f32_e32 v41, v41
	v_pk_mul_f32 v[6:7], v[6:7], v[130:131]
	v_mul_f32_e32 v130, 0xbfb8aa3b, v132
	v_mul_f32_e32 v131, 0xbfb8aa3b, v133
	v_add_f32_e32 v40, 1.0, v40
	v_add_f32_e32 v41, 1.0, v41
	v_rcp_f32_e32 v40, v40
	v_rcp_f32_e32 v41, v41
	v_exp_f32_e32 v130, v130
	v_exp_f32_e32 v131, v131
	v_pk_mul_f32 v[4:5], v[4:5], v[132:133]
	v_pk_mul_f32 v[6:7], v[40:41], v[6:7]
	v_add_f32_e32 v130, 1.0, v130
	v_add_f32_e32 v131, 1.0, v131
	v_rcp_f32_e32 v130, v130
	v_rcp_f32_e32 v131, v131
	v_cvt_pk_bf16_f32 v6, v6, v7
	s_nop 0
	v_pk_mul_f32 v[4:5], v[130:131], v[4:5]
	s_nop 0
	v_cvt_pk_bf16_f32 v7, v4, v5
	global_store_dwordx2 v[46:47], v[6:7], off offset:64
	s_waitcnt vmcnt(11)
	v_lshlrev_b32_e32 v130, 16, v42
	v_and_b32_e32 v131, 0xffff0000, v42
	v_lshlrev_b32_e32 v132, 16, v43
	v_and_b32_e32 v133, 0xffff0000, v43
	v_pk_fma_f32 v[2:3], v[80:81], v[2:3], v[84:85]
	v_pk_fma_f32 v[0:1], v[82:83], v[0:1], v[86:87]
	v_mul_f32_e32 v42, 0xbfb8aa3b, v130
	v_mul_f32_e32 v43, 0xbfb8aa3b, v131
	v_exp_f32_e32 v42, v42
	v_exp_f32_e32 v43, v43
	v_pk_mul_f32 v[2:3], v[2:3], v[130:131]
	v_mul_f32_e32 v130, 0xbfb8aa3b, v132
	v_mul_f32_e32 v131, 0xbfb8aa3b, v133
	v_add_f32_e32 v42, 1.0, v42
	v_add_f32_e32 v43, 1.0, v43
	v_rcp_f32_e32 v42, v42
	v_rcp_f32_e32 v43, v43
	v_exp_f32_e32 v130, v130
	v_exp_f32_e32 v131, v131
	v_pk_mul_f32 v[0:1], v[0:1], v[132:133]
	v_pk_mul_f32 v[2:3], v[42:43], v[2:3]
	v_add_f32_e32 v130, 1.0, v130
	v_add_f32_e32 v131, 1.0, v131
	v_rcp_f32_e32 v130, v130
	v_rcp_f32_e32 v131, v131
	v_cvt_pk_bf16_f32 v2, v2, v3
	s_nop 0
	v_pk_mul_f32 v[0:1], v[130:131], v[0:1]
	s_nop 0
	v_cvt_pk_bf16_f32 v3, v0, v1
	global_store_dwordx2 v[46:47], v[2:3], off offset:96
	s_waitcnt vmcnt(10)
; __device__ __forceinline__ unsigned pk2(float lo, float hi) { return pg8::cvt_pk_bf16(lo, hi); }
; __device__ __forceinline__ float bflo(unsigned w) { return __uint_as_float(w << 16); }
; __device__ __forceinline__ float bfhi(unsigned w) { return __uint_as_float(w & 0xffff0000u); }
; __device__ __forceinline__ void ret_unit(LAS unsigned char* lds, int u, const bf16* PROJ, const int* pos, const float* dec_f, const float* dec_b, const bf16* ST,
;                                          const float* gn_w, const float* gn_b, bf16* MIX, int tid, const WsRef& wsr) {
;     ...
;     const size_t row = row0 + q;
; #pragma unroll
;     for (int n = 0; n < 8; ++n) { const int col = h * 128 + n * 16 + 4 * fq;
;         const f32x4 gw = *(const f32x4*)(gn_w + col), gb = *(const f32x4*)(gn_b + col);
;         const u32x2 gg = *(const u32x2*)(PROJ + row * INC + 1536 + col);
;         const f32x4 g = (f32x4){bflo(gg.x), bfhi(gg.x), bflo(gg.y), bfhi(gg.y)};
;         f32x4 y = (o[n] - mu) * rstd * gw + gb;
; #pragma unroll
;         for (int r = 0; r < 4; ++r) y[r] = y[r] * g[r] * __builtin_amdgcn_rcpf(1.f + __expf(-g[r]));
;         u32x2 w; w.x = pk2(y[0], y[1]); w.y = pk2(y[2], y[3]); *(u32x2*)(MIX + row * D + col) = w; }
;     __syncthreads();
	v_lshlrev_b32_e32 v130, 16, v44
	v_and_b32_e32 v131, 0xffff0000, v44
	v_lshlrev_b32_e32 v132, 16, v45
	v_and_b32_e32 v133, 0xffff0000, v45
	v_pk_fma_f32 v[24:25], v[88:89], v[24:25], v[92:93]
	v_pk_fma_f32 v[22:23], v[90:91], v[22:23], v[94:95]
	v_mul_f32_e32 v44, 0xbfb8aa3b, v130
	v_mul_f32_e32 v45, 0xbfb8aa3b, v131
	v_exp_f32_e32 v44, v44
	v_exp_f32_e32 v45, v45
	v_pk_mul_f32 v[24:25], v[24:25], v[130:131]
	v_mul_f32_e32 v130, 0xbfb8aa3b, v132
	v_mul_f32_e32 v131, 0xbfb8aa3b, v133
	v_add_f32_e32 v44, 1.0, v44
	v_add_f32_e32 v45, 1.0, v45
	v_rcp_f32_e32 v44, v44
	v_rcp_f32_e32 v45, v45
	v_exp_f32_e32 v130, v130
	v_exp_f32_e32 v131, v131
	v_pk_mul_f32 v[22:23], v[22:23], v[132:133]
	v_pk_mul_f32 v[24:25], v[44:45], v[24:25]
	v_add_f32_e32 v130, 1.0, v130
	v_add_f32_e32 v131, 1.0, v131
	v_rcp_f32_e32 v130, v130
	v_rcp_f32_e32 v131, v131
	v_cvt_pk_bf16_f32 v24, v24, v25
	s_nop 0
	v_pk_mul_f32 v[22:23], v[130:131], v[22:23]
	s_nop 0
	v_cvt_pk_bf16_f32 v25, v22, v23
	global_store_dwordx2 v[46:47], v[24:25], off offset:128
	s_waitcnt vmcnt(9)
	v_lshlrev_b32_e32 v130, 16, v50
	v_and_b32_e32 v131, 0xffff0000, v50
	v_lshlrev_b32_e32 v132, 16, v51
	v_and_b32_e32 v133, 0xffff0000, v51
	v_pk_fma_f32 v[20:21], v[232:233], v[20:21], v[236:237]
	v_pk_fma_f32 v[18:19], v[234:235], v[18:19], v[238:239]
	v_mul_f32_e32 v50, 0xbfb8aa3b, v130
	v_mul_f32_e32 v51, 0xbfb8aa3b, v131
	v_exp_f32_e32 v50, v50
	v_exp_f32_e32 v51, v51
	v_pk_mul_f32 v[20:21], v[20:21], v[130:131]
	v_mul_f32_e32 v130, 0xbfb8aa3b, v132
	v_mul_f32_e32 v131, 0xbfb8aa3b, v133
	v_add_f32_e32 v50, 1.0, v50
	v_add_f32_e32 v51, 1.0, v51
	v_rcp_f32_e32 v50, v50
	v_rcp_f32_e32 v51, v51
	v_exp_f32_e32 v130, v130
	v_exp_f32_e32 v131, v131
	v_pk_mul_f32 v[18:19], v[18:19], v[132:133]
	v_pk_mul_f32 v[20:21], v[50:51], v[20:21]
	v_add_f32_e32 v130, 1.0, v130
	v_add_f32_e32 v131, 1.0, v131
	v_rcp_f32_e32 v130, v130
	v_rcp_f32_e32 v131, v131
	v_cvt_pk_bf16_f32 v20, v20, v21
	s_nop 0
	v_pk_mul_f32 v[18:19], v[130:131], v[18:19]
	s_nop 0
	v_cvt_pk_bf16_f32 v21, v18, v19
	global_store_dwordx2 v[46:47], v[20:21], off offset:160
	s_waitcnt vmcnt(8)
	v_lshlrev_b32_e32 v130, 16, v52
	v_and_b32_e32 v131, 0xffff0000, v52
	v_lshlrev_b32_e32 v132, 16, v53
	v_and_b32_e32 v133, 0xffff0000, v53
	v_pk_fma_f32 v[16:17], v[240:241], v[16:17], v[248:249]
	v_pk_fma_f32 v[14:15], v[242:243], v[14:15], v[250:251]
	v_mul_f32_e32 v52, 0xbfb8aa3b, v130
	v_mul_f32_e32 v53, 0xbfb8aa3b, v131
	v_exp_f32_e32 v52, v52
	v_exp_f32_e32 v53, v53
	v_pk_mul_f32 v[16:17], v[16:17], v[130:131]
	v_mul_f32_e32 v130, 0xbfb8aa3b, v132
	v_mul_f32_e32 v131, 0xbfb8aa3b, v133
	v_add_f32_e32 v52, 1.0, v52
	v_add_f32_e32 v53, 1.0, v53
	v_rcp_f32_e32 v52, v52
	v_rcp_f32_e32 v53, v53
	v_exp_f32_e32 v130, v130
	v_exp_f32_e32 v131, v131
	v_pk_mul_f32 v[14:15], v[14:15], v[132:133]
	v_pk_mul_f32 v[16:17], v[52:53], v[16:17]
	v_add_f32_e32 v130, 1.0, v130
	v_add_f32_e32 v131, 1.0, v131
	v_rcp_f32_e32 v130, v130
	v_rcp_f32_e32 v131, v131
	v_cvt_pk_bf16_f32 v16, v16, v17
	s_nop 0
	v_pk_mul_f32 v[14:15], v[130:131], v[14:15]
	s_nop 0
	v_cvt_pk_bf16_f32 v17, v14, v15
	global_store_dwordx2 v[46:47], v[16:17], off offset:192
	s_waitcnt vmcnt(7)
	v_lshlrev_b32_e32 v130, 16, v54
	v_and_b32_e32 v131, 0xffff0000, v54
	v_lshlrev_b32_e32 v132, 16, v55
	v_and_b32_e32 v133, 0xffff0000, v55
	v_pk_fma_f32 v[10:11], v[56:57], v[10:11], v[60:61]
	v_pk_fma_f32 v[8:9], v[58:59], v[8:9], v[62:63]
	v_mul_f32_e32 v54, 0xbfb8aa3b, v130
	v_mul_f32_e32 v55, 0xbfb8aa3b, v131
	v_exp_f32_e32 v54, v54
	v_exp_f32_e32 v55, v55
	v_pk_mul_f32 v[10:11], v[10:11], v[130:131]
	v_mul_f32_e32 v130, 0xbfb8aa3b, v132
	v_mul_f32_e32 v131, 0xbfb8aa3b, v133
	v_add_f32_e32 v54, 1.0, v54
	v_add_f32_e32 v55, 1.0, v55
	v_rcp_f32_e32 v54, v54
	v_rcp_f32_e32 v55, v55
	v_exp_f32_e32 v130, v130
	v_exp_f32_e32 v131, v131
	v_pk_mul_f32 v[8:9], v[8:9], v[132:133]
	v_pk_mul_f32 v[10:11], v[54:55], v[10:11]
	v_add_f32_e32 v130, 1.0, v130
	v_add_f32_e32 v131, 1.0, v131
	v_rcp_f32_e32 v130, v130
	v_rcp_f32_e32 v131, v131
	v_cvt_pk_bf16_f32 v10, v10, v11
	s_nop 0
	v_pk_mul_f32 v[8:9], v[130:131], v[8:9]
	s_nop 0
	v_cvt_pk_bf16_f32 v11, v8, v9
	global_store_dwordx2 v[46:47], v[10:11], off offset:224
	s_barrier
	s_cbranch_scc1 .LBB0_438
	v_readlane_b32 s82, v255, 40
	v_readlane_b32 s4, v255, 38
	v_readlane_b32 s80, v255, 42
	v_readlane_b32 s83, v255, 41
	v_readlane_b32 s5, v255, 39
	v_readlane_b32 s2, v255, 58
	v_readlane_b32 s81, v255, 43

; __global__ void __launch_bounds__(512, 2) fwd_mega(Args a) {
;     ...
;     const bool panel_mode = (G == 256);
;     pg8::Unit myu; { pg8::StaticOrder S; S.init(M, D, G, bid); if (!S.next(0, myu)) { myu.pm = 0; myu.pn = 0; } }
;     unsigned* pbar = (unsigned*)(ws + WS_CTL + 327680) + 64 * myu.pm;
.LBB0_494:
	s_and_b32 s4, s2, 63
	s_mov_b32 s5, 0
	s_lshl_b32 s4, s4, 2
	v_writelane_b32 v255, s5, 59
	s_add_i32 s4, s4, 0x8000
	v_mov_b32_e32 v236, s4
	global_load_dword v232, v236, s[84:85] sc1
	global_load_dword v233, v236, s[84:85] offset:256 sc1
	global_load_dword v234, v236, s[84:85] offset:512 sc1
	global_load_dword v235, v236, s[84:85] offset:768 sc1
	s_cmpk_lt_i32 s2, 0x100
	s_mov_b32 s12, 0
	s_cselect_b64 s[4:5], -1, 0
	s_cmpk_gt_i32 s2, 0xff
	s_mov_b32 s33, 0
	s_cbranch_scc1 .LBB0_500
	s_ashr_i32 s3, s2, 31
	s_lshr_b32 s3, s3, 29
	s_add_i32 s3, s2, s3
	s_and_b32 s6, s3, -8
	s_sub_i32 s8, s2, s6
	s_cmp_gt_i32 s8, -1
	s_cbranch_scc0 .LBB0_497
	s_lshl_b32 s9, s8, 5
	s_cbranch_execz .LBB0_498
	s_branch .LBB0_499

; __device__ __forceinline__ unsigned cvt_pk_bf16(float lo, float hi) { f32x2_t v = {lo, hi}; bf16x2_t b = __builtin_convertvector(v, bf16x2_t); return __builtin_bit_cast(unsigned, b); }
;     __device__ __forceinline__ void operator()(const f32x4 (&acc)[2][2][4][2], const Unit& u, int wr, int wc, int fr, int fq) const {
;         const int col0 = u.pn * BM + wc * 32 + 8 * fq;
;         const __amdgpu_buffer_rsrc_t rsrc = __builtin_amdgcn_make_buffer_rsrc((void*)xb, (short)0, 16384 * 1024 * 2, 0x00020000);
; #pragma unroll
;         for (int ai = 0; ai < 2; ++ai)
; #pragma unroll
;             for (int m = 0; m < 4; ++m) { const int row = u.pm * BM + ai * HALF + wr * 64 + m * 16 + fr; const size_t off = (size_t)row * ldc + col0; float ss = 0.f;
; #pragma unroll
;                 for (int bj = 0; bj < 2; ++bj) { const size_t o2 = off + bj * HALF; f32x4 b0, b1;
;                     if (MODE == 0) { b0 = *(const f32x4*)(basef + o2); b1 = *(const f32x4*)(basef + o2 + 4); }
;                     else { const u32x4 w = *(const u32x4*)(xb + o2);
;                         b0 = (f32x4){__uint_as_float(w.x << 16), __uint_as_float(w.x & 0xffff0000u), __uint_as_float(w.y << 16), __uint_as_float(w.y & 0xffff0000u)};
;                         b1 = (f32x4){__uint_as_float(w.z << 16), __uint_as_float(w.z & 0xffff0000u), __uint_as_float(w.w << 16), __uint_as_float(w.w & 0xffff0000u)}; }
;                     const f32x4 v0 = b0 + acc[ai][bj][m][0], v1 = b1 + acc[ai][bj][m][1];
;                     if (MODE == 2) { *(f32x4*)(outf + o2) = v0; *(f32x4*)(outf + o2 + 4) = v1; }
;                     else { ss += (v0[0] * v0[0] + v0[1] * v0[1]) + (v0[2] * v0[2] + v0[3] * v0[3]) + (v1[0] * v1[0] + v1[1] * v1[1]) + (v1[2] * v1[2] + v1[3] * v1[3]);
;                         u32x4 w; w.x = cvt_pk_bf16(v0[0], v0[1]); w.y = cvt_pk_bf16(v0[2], v0[3]); w.z = cvt_pk_bf16(v1[0], v1[1]); w.w = cvt_pk_bf16(v1[2], v1[3]);
;                         __builtin_amdgcn_raw_buffer_store_b128(w, rsrc, (unsigned)(o2 * 2), 0, 16); } }
;                 if (MODE != 2) { ss += __shfl_xor(ss, 16); ss += __shfl_xor(ss, 32); if (fq == 0) atomicAdd(rowsq + row, ss); } }
.LBB0_523:
	s_waitcnt vmcnt(8)
	v_xor_b32_e32 v236, v232, v233
	v_xor_b32_e32 v237, v232, v234
	v_xor_b32_e32 v238, v232, v235
	v_add_u32_e32 v239, -1, v232
	v_or3_b32 v236, v236, v237, v238
	v_and_b32_e32 v239, 0xfffffff0, v239
	v_or_b32_e32 v236, v236, v239
	v_cmp_eq_u32_e32 vcc, 0, v236
	s_nop 1
	v_writelane_b32 v255, vcc_lo, 59
	s_cbranch_vccnz .Lpp5_plain
	v_lshl_add_u32 v156, s40, 8, v129
	v_lshl_or_b32 v157, s42, 8, v151
	v_lshl_add_u32 v156, v156, 10, v157
	v_lshlrev_b32_e32 v156, 1, v156
	v_add_u32_e32 v157, 0x8000, v156
	v_add_u32_e32 v158, 0x10000, v156
	v_add_u32_e32 v159, 0x18000, v156
	v_add_u32_e32 v146, 0x40000, v156
	v_add_u32_e32 v147, 0x48000, v156
	v_add_u32_e32 v148, 0x50000, v156
	v_add_u32_e32 v149, 0x58000, v156
	global_load_dwordx4 v[160:163], v156, s[96:97]
	global_load_dwordx4 v[164:167], v156, s[96:97] offset:256
	global_load_dwordx4 v[168:171], v157, s[96:97]
	global_load_dwordx4 v[172:175], v157, s[96:97] offset:256
	global_load_dwordx4 v[176:179], v158, s[96:97]
	global_load_dwordx4 v[180:183], v158, s[96:97] offset:256
	global_load_dwordx4 v[184:187], v159, s[96:97]
	global_load_dwordx4 v[188:191], v159, s[96:97] offset:256
	global_load_dwordx4 v[192:195], v146, s[96:97]
	global_load_dwordx4 v[196:199], v146, s[96:97] offset:256
	global_load_dwordx4 v[200:203], v147, s[96:97]
	global_load_dwordx4 v[204:207], v147, s[96:97] offset:256
	global_load_dwordx4 v[208:211], v148, s[96:97]
	global_load_dwordx4 v[212:215], v148, s[96:97] offset:256
	global_load_dwordx4 v[216:219], v149, s[96:97]
	global_load_dwordx4 v[220:223], v149, s[96:97] offset:256
	v_xor_b32_e32 v248, 16, v155
	v_xor_b32_e32 v249, 32, v155
	v_lshlrev_b32_e32 v248, 2, v248
	v_lshlrev_b32_e32 v249, 2, v249
	s_waitcnt vmcnt(14)
	v_lshlrev_b32_e32 v224, 16, v160
	v_and_b32_e32 v225, 0xffff0000, v160
	v_lshlrev_b32_e32 v226, 16, v161
	v_and_b32_e32 v227, 0xffff0000, v161
	v_lshlrev_b32_e32 v228, 16, v162
	v_and_b32_e32 v229, 0xffff0000, v162
	v_lshlrev_b32_e32 v230, 16, v163
	v_and_b32_e32 v231, 0xffff0000, v163
	v_pk_add_f32 v[124:125], v[124:125], v[224:225]
	v_pk_add_f32 v[126:127], v[126:127], v[226:227]
	v_pk_add_f32 v[120:121], v[120:121], v[228:229]
	v_pk_add_f32 v[122:123], v[122:123], v[230:231]
	v_mul_f32_e32 v232, v124, v124
	v_fmac_f32_e32 v232, v125, v125
	v_fmac_f32_e32 v232, v126, v126
	v_fmac_f32_e32 v232, v127, v127
	v_fmac_f32_e32 v232, v120, v120
	v_fmac_f32_e32 v232, v121, v121
	v_fmac_f32_e32 v232, v122, v122
	v_fmac_f32_e32 v232, v123, v123
	v_cvt_pk_bf16_f32 v124, v124, v125
	v_cvt_pk_bf16_f32 v125, v126, v127
	v_cvt_pk_bf16_f32 v126, v120, v121
	v_cvt_pk_bf16_f32 v127, v122, v123
	buffer_store_dwordx4 v[124:127], v156, s[8:11], 0 offen sc1
	v_lshlrev_b32_e32 v224, 16, v164
	v_and_b32_e32 v225, 0xffff0000, v164
	v_lshlrev_b32_e32 v226, 16, v165
	v_and_b32_e32 v227, 0xffff0000, v165
	v_lshlrev_b32_e32 v228, 16, v166
	v_and_b32_e32 v229, 0xffff0000, v166
	v_lshlrev_b32_e32 v230, 16, v167
	v_and_b32_e32 v231, 0xffff0000, v167
	v_pk_add_f32 v[116:117], v[116:117], v[224:225]
	v_pk_add_f32 v[118:119], v[118:119], v[226:227]
	v_pk_add_f32 v[112:113], v[112:113], v[228:229]
	v_pk_add_f32 v[114:115], v[114:115], v[230:231]
	v_fmac_f32_e32 v232, v116, v116
	v_fmac_f32_e32 v232, v117, v117
	v_fmac_f32_e32 v232, v118, v118
	v_fmac_f32_e32 v232, v119, v119
	v_fmac_f32_e32 v232, v112, v112
	v_fmac_f32_e32 v232, v113, v113
	v_fmac_f32_e32 v232, v114, v114
	v_fmac_f32_e32 v232, v115, v115
	v_cvt_pk_bf16_f32 v116, v116, v117
	v_cvt_pk_bf16_f32 v117, v118, v119
	v_cvt_pk_bf16_f32 v118, v112, v113
	v_cvt_pk_bf16_f32 v119, v114, v115
	buffer_store_dwordx4 v[116:119], v156, s[8:11], 0 offen offset:256 sc1
	s_waitcnt vmcnt(14)
	v_lshlrev_b32_e32 v224, 16, v168
	v_and_b32_e32 v225, 0xffff0000, v168
	v_lshlrev_b32_e32 v226, 16, v169
	v_and_b32_e32 v227, 0xffff0000, v169
	v_lshlrev_b32_e32 v228, 16, v170
	v_and_b32_e32 v229, 0xffff0000, v170
	v_lshlrev_b32_e32 v230, 16, v171
	v_and_b32_e32 v231, 0xffff0000, v171
	v_pk_add_f32 v[108:109], v[108:109], v[224:225]
	v_pk_add_f32 v[110:111], v[110:111], v[226:227]
	v_pk_add_f32 v[104:105], v[104:105], v[228:229]
	v_pk_add_f32 v[106:107], v[106:107], v[230:231]
	v_mul_f32_e32 v233, v108, v108
	v_fmac_f32_e32 v233, v109, v109
	v_fmac_f32_e32 v233, v110, v110
	v_fmac_f32_e32 v233, v111, v111
	v_fmac_f32_e32 v233, v104, v104
	v_fmac_f32_e32 v233, v105, v105
	v_fmac_f32_e32 v233, v106, v106
	v_fmac_f32_e32 v233, v107, v107
	v_cvt_pk_bf16_f32 v108, v108, v109
	v_cvt_pk_bf16_f32 v109, v110, v111
	v_cvt_pk_bf16_f32 v110, v104, v105
	v_cvt_pk_bf16_f32 v111, v106, v107
	buffer_store_dwordx4 v[108:111], v157, s[8:11], 0 offen sc1
	v_lshlrev_b32_e32 v224, 16, v172
	v_and_b32_e32 v225, 0xffff0000, v172
	v_lshlrev_b32_e32 v226, 16, v173
	v_and_b32_e32 v227, 0xffff0000, v173
	v_lshlrev_b32_e32 v228, 16, v174
	v_and_b32_e32 v229, 0xffff0000, v174
	v_lshlrev_b32_e32 v230, 16, v175
	v_and_b32_e32 v231, 0xffff0000, v175
	v_pk_add_f32 v[100:101], v[100:101], v[224:225]
	v_pk_add_f32 v[102:103], v[102:103], v[226:227]
	v_pk_add_f32 v[96:97], v[96:97], v[228:229]
	v_pk_add_f32 v[98:99], v[98:99], v[230:231]
	v_fmac_f32_e32 v233, v100, v100
	v_fmac_f32_e32 v233, v101, v101
	v_fmac_f32_e32 v233, v102, v102
	v_fmac_f32_e32 v233, v103, v103
	v_fmac_f32_e32 v233, v96, v96
	v_fmac_f32_e32 v233, v97, v97
	v_fmac_f32_e32 v233, v98, v98
	v_fmac_f32_e32 v233, v99, v99
	v_cvt_pk_bf16_f32 v100, v100, v101
	v_cvt_pk_bf16_f32 v101, v102, v103
	v_cvt_pk_bf16_f32 v102, v96, v97
	v_cvt_pk_bf16_f32 v103, v98, v99
	buffer_store_dwordx4 v[100:103], v157, s[8:11], 0 offen offset:256 sc1
	s_waitcnt vmcnt(14)
; __device__ __forceinline__ unsigned cvt_pk_bf16(float lo, float hi) { f32x2_t v = {lo, hi}; bf16x2_t b = __builtin_convertvector(v, bf16x2_t); return __builtin_bit_cast(unsigned, b); }
;     __device__ __forceinline__ void operator()(const f32x4 (&acc)[2][2][4][2], const Unit& u, int wr, int wc, int fr, int fq) const {
;     ...
;             for (int m = 0; m < 4; ++m) { const int row = u.pm * BM + ai * HALF + wr * 64 + m * 16 + fr; const size_t off = (size_t)row * ldc + col0; float ss = 0.f;
; #pragma unroll
;                 for (int bj = 0; bj < 2; ++bj) { const size_t o2 = off + bj * HALF; f32x4 b0, b1;
;                     if (MODE == 0) { b0 = *(const f32x4*)(basef + o2); b1 = *(const f32x4*)(basef + o2 + 4); }
;                     else { const u32x4 w = *(const u32x4*)(xb + o2);
;                         b0 = (f32x4){__uint_as_float(w.x << 16), __uint_as_float(w.x & 0xffff0000u), __uint_as_float(w.y << 16), __uint_as_float(w.y & 0xffff0000u)};
;                         b1 = (f32x4){__uint_as_float(w.z << 16), __uint_as_float(w.z & 0xffff0000u), __uint_as_float(w.w << 16), __uint_as_float(w.w & 0xffff0000u)}; }
;                     const f32x4 v0 = b0 + acc[ai][bj][m][0], v1 = b1 + acc[ai][bj][m][1];
;                     if (MODE == 2) { *(f32x4*)(outf + o2) = v0; *(f32x4*)(outf + o2 + 4) = v1; }
;                     else { ss += (v0[0] * v0[0] + v0[1] * v0[1]) + (v0[2] * v0[2] + v0[3] * v0[3]) + (v1[0] * v1[0] + v1[1] * v1[1]) + (v1[2] * v1[2] + v1[3] * v1[3]);
;                         u32x4 w; w.x = cvt_pk_bf16(v0[0], v0[1]); w.y = cvt_pk_bf16(v0[2], v0[3]); w.z = cvt_pk_bf16(v1[0], v1[1]); w.w = cvt_pk_bf16(v1[2], v1[3]);
;                         __builtin_amdgcn_raw_buffer_store_b128(w, rsrc, (unsigned)(o2 * 2), 0, 16); } }
;                 if (MODE != 2) { ss += __shfl_xor(ss, 16); ss += __shfl_xor(ss, 32); if (fq == 0) atomicAdd(rowsq + row, ss); } }
	v_lshlrev_b32_e32 v224, 16, v176
	v_and_b32_e32 v225, 0xffff0000, v176
	v_lshlrev_b32_e32 v226, 16, v177
	v_and_b32_e32 v227, 0xffff0000, v177
	v_lshlrev_b32_e32 v228, 16, v178
	v_and_b32_e32 v229, 0xffff0000, v178
	v_lshlrev_b32_e32 v230, 16, v179
	v_and_b32_e32 v231, 0xffff0000, v179
	v_pk_add_f32 v[92:93], v[92:93], v[224:225]
	v_pk_add_f32 v[94:95], v[94:95], v[226:227]
	v_pk_add_f32 v[88:89], v[88:89], v[228:229]
	v_pk_add_f32 v[90:91], v[90:91], v[230:231]
	v_mul_f32_e32 v234, v92, v92
	v_fmac_f32_e32 v234, v93, v93
	v_fmac_f32_e32 v234, v94, v94
	v_fmac_f32_e32 v234, v95, v95
	v_fmac_f32_e32 v234, v88, v88
	v_fmac_f32_e32 v234, v89, v89
	v_fmac_f32_e32 v234, v90, v90
	v_fmac_f32_e32 v234, v91, v91
	v_cvt_pk_bf16_f32 v92, v92, v93
	v_cvt_pk_bf16_f32 v93, v94, v95
	v_cvt_pk_bf16_f32 v94, v88, v89
	v_cvt_pk_bf16_f32 v95, v90, v91
	buffer_store_dwordx4 v[92:95], v158, s[8:11], 0 offen sc1
	v_lshlrev_b32_e32 v224, 16, v180
	v_and_b32_e32 v225, 0xffff0000, v180
	v_lshlrev_b32_e32 v226, 16, v181
	v_and_b32_e32 v227, 0xffff0000, v181
	v_lshlrev_b32_e32 v228, 16, v182
	v_and_b32_e32 v229, 0xffff0000, v182
	v_lshlrev_b32_e32 v230, 16, v183
	v_and_b32_e32 v231, 0xffff0000, v183
	v_pk_add_f32 v[84:85], v[84:85], v[224:225]
	v_pk_add_f32 v[86:87], v[86:87], v[226:227]
	v_pk_add_f32 v[80:81], v[80:81], v[228:229]
	v_pk_add_f32 v[82:83], v[82:83], v[230:231]
	v_fmac_f32_e32 v234, v84, v84
	v_fmac_f32_e32 v234, v85, v85
	v_fmac_f32_e32 v234, v86, v86
	v_fmac_f32_e32 v234, v87, v87
	v_fmac_f32_e32 v234, v80, v80
	v_fmac_f32_e32 v234, v81, v81
	v_fmac_f32_e32 v234, v82, v82
	v_fmac_f32_e32 v234, v83, v83
	v_cvt_pk_bf16_f32 v84, v84, v85
	v_cvt_pk_bf16_f32 v85, v86, v87
	v_cvt_pk_bf16_f32 v86, v80, v81
	v_cvt_pk_bf16_f32 v87, v82, v83
	buffer_store_dwordx4 v[84:87], v158, s[8:11], 0 offen offset:256 sc1
	s_waitcnt vmcnt(14)
	v_lshlrev_b32_e32 v224, 16, v184
	v_and_b32_e32 v225, 0xffff0000, v184
	v_lshlrev_b32_e32 v226, 16, v185
	v_and_b32_e32 v227, 0xffff0000, v185
	v_lshlrev_b32_e32 v228, 16, v186
	v_and_b32_e32 v229, 0xffff0000, v186
	v_lshlrev_b32_e32 v230, 16, v187
	v_and_b32_e32 v231, 0xffff0000, v187
	v_pk_add_f32 v[76:77], v[76:77], v[224:225]
	v_pk_add_f32 v[78:79], v[78:79], v[226:227]
	v_pk_add_f32 v[72:73], v[72:73], v[228:229]
	v_pk_add_f32 v[74:75], v[74:75], v[230:231]
	v_mul_f32_e32 v235, v76, v76
	v_fmac_f32_e32 v235, v77, v77
	v_fmac_f32_e32 v235, v78, v78
	v_fmac_f32_e32 v235, v79, v79
	v_fmac_f32_e32 v235, v72, v72
	v_fmac_f32_e32 v235, v73, v73
	v_fmac_f32_e32 v235, v74, v74
	v_fmac_f32_e32 v235, v75, v75
	v_cvt_pk_bf16_f32 v76, v76, v77
	v_cvt_pk_bf16_f32 v77, v78, v79
	v_cvt_pk_bf16_f32 v78, v72, v73
	v_cvt_pk_bf16_f32 v79, v74, v75
	buffer_store_dwordx4 v[76:79], v159, s[8:11], 0 offen sc1
	v_lshlrev_b32_e32 v224, 16, v188
	v_and_b32_e32 v225, 0xffff0000, v188
	v_lshlrev_b32_e32 v226, 16, v189
	v_and_b32_e32 v227, 0xffff0000, v189
	v_lshlrev_b32_e32 v228, 16, v190
	v_and_b32_e32 v229, 0xffff0000, v190
	v_lshlrev_b32_e32 v230, 16, v191
	v_and_b32_e32 v231, 0xffff0000, v191
	v_pk_add_f32 v[68:69], v[68:69], v[224:225]
	v_pk_add_f32 v[70:71], v[70:71], v[226:227]
	v_pk_add_f32 v[64:65], v[64:65], v[228:229]
	v_pk_add_f32 v[66:67], v[66:67], v[230:231]
	v_fmac_f32_e32 v235, v68, v68
	v_fmac_f32_e32 v235, v69, v69
	v_fmac_f32_e32 v235, v70, v70
	v_fmac_f32_e32 v235, v71, v71
	v_fmac_f32_e32 v235, v64, v64
	v_fmac_f32_e32 v235, v65, v65
	v_fmac_f32_e32 v235, v66, v66
	v_fmac_f32_e32 v235, v67, v67
	v_cvt_pk_bf16_f32 v68, v68, v69
	v_cvt_pk_bf16_f32 v69, v70, v71
	v_cvt_pk_bf16_f32 v70, v64, v65
	v_cvt_pk_bf16_f32 v71, v66, v67
	buffer_store_dwordx4 v[68:71], v159, s[8:11], 0 offen offset:256 sc1
	s_waitcnt vmcnt(14)
	v_lshlrev_b32_e32 v224, 16, v192
	v_and_b32_e32 v225, 0xffff0000, v192
	v_lshlrev_b32_e32 v226, 16, v193
	v_and_b32_e32 v227, 0xffff0000, v193
	v_lshlrev_b32_e32 v228, 16, v194
	v_and_b32_e32 v229, 0xffff0000, v194
	v_lshlrev_b32_e32 v230, 16, v195
	v_and_b32_e32 v231, 0xffff0000, v195
	v_pk_add_f32 v[60:61], v[60:61], v[224:225]
	v_pk_add_f32 v[62:63], v[62:63], v[226:227]
	v_pk_add_f32 v[56:57], v[56:57], v[228:229]
	v_pk_add_f32 v[58:59], v[58:59], v[230:231]
	v_mul_f32_e32 v236, v60, v60
	v_fmac_f32_e32 v236, v61, v61
	v_fmac_f32_e32 v236, v62, v62
	v_fmac_f32_e32 v236, v63, v63
	v_fmac_f32_e32 v236, v56, v56
	v_fmac_f32_e32 v236, v57, v57
	v_fmac_f32_e32 v236, v58, v58
	v_fmac_f32_e32 v236, v59, v59
	v_cvt_pk_bf16_f32 v60, v60, v61
	v_cvt_pk_bf16_f32 v61, v62, v63
	v_cvt_pk_bf16_f32 v62, v56, v57
	v_cvt_pk_bf16_f32 v63, v58, v59
	buffer_store_dwordx4 v[60:63], v146, s[8:11], 0 offen sc1
	v_lshlrev_b32_e32 v224, 16, v196
	v_and_b32_e32 v225, 0xffff0000, v196
	v_lshlrev_b32_e32 v226, 16, v197
	v_and_b32_e32 v227, 0xffff0000, v197
	v_lshlrev_b32_e32 v228, 16, v198
	v_and_b32_e32 v229, 0xffff0000, v198
	v_lshlrev_b32_e32 v230, 16, v199
	v_and_b32_e32 v231, 0xffff0000, v199
	v_pk_add_f32 v[52:53], v[52:53], v[224:225]
	v_pk_add_f32 v[54:55], v[54:55], v[226:227]
	v_pk_add_f32 v[48:49], v[48:49], v[228:229]
	v_pk_add_f32 v[50:51], v[50:51], v[230:231]
	v_fmac_f32_e32 v236, v52, v52
	v_fmac_f32_e32 v236, v53, v53
	v_fmac_f32_e32 v236, v54, v54
	v_fmac_f32_e32 v236, v55, v55
	v_fmac_f32_e32 v236, v48, v48
	v_fmac_f32_e32 v236, v49, v49
	v_fmac_f32_e32 v236, v50, v50
	v_fmac_f32_e32 v236, v51, v51
	v_cvt_pk_bf16_f32 v52, v52, v53
	v_cvt_pk_bf16_f32 v53, v54, v55
	v_cvt_pk_bf16_f32 v54, v48, v49
	v_cvt_pk_bf16_f32 v55, v50, v51
	buffer_store_dwordx4 v[52:55], v146, s[8:11], 0 offen offset:256 sc1
	s_waitcnt vmcnt(14)
; __device__ __forceinline__ unsigned cvt_pk_bf16(float lo, float hi) { f32x2_t v = {lo, hi}; bf16x2_t b = __builtin_convertvector(v, bf16x2_t); return __builtin_bit_cast(unsigned, b); }
;     __device__ __forceinline__ void operator()(const f32x4 (&acc)[2][2][4][2], const Unit& u, int wr, int wc, int fr, int fq) const {
;     ...
;             for (int m = 0; m < 4; ++m) { const int row = u.pm * BM + ai * HALF + wr * 64 + m * 16 + fr; const size_t off = (size_t)row * ldc + col0; float ss = 0.f;
; #pragma unroll
;                 for (int bj = 0; bj < 2; ++bj) { const size_t o2 = off + bj * HALF; f32x4 b0, b1;
;                     if (MODE == 0) { b0 = *(const f32x4*)(basef + o2); b1 = *(const f32x4*)(basef + o2 + 4); }
;                     else { const u32x4 w = *(const u32x4*)(xb + o2);
;                         b0 = (f32x4){__uint_as_float(w.x << 16), __uint_as_float(w.x & 0xffff0000u), __uint_as_float(w.y << 16), __uint_as_float(w.y & 0xffff0000u)};
;                         b1 = (f32x4){__uint_as_float(w.z << 16), __uint_as_float(w.z & 0xffff0000u), __uint_as_float(w.w << 16), __uint_as_float(w.w & 0xffff0000u)}; }
;                     const f32x4 v0 = b0 + acc[ai][bj][m][0], v1 = b1 + acc[ai][bj][m][1];
;                     if (MODE == 2) { *(f32x4*)(outf + o2) = v0; *(f32x4*)(outf + o2 + 4) = v1; }
;                     else { ss += (v0[0] * v0[0] + v0[1] * v0[1]) + (v0[2] * v0[2] + v0[3] * v0[3]) + (v1[0] * v1[0] + v1[1] * v1[1]) + (v1[2] * v1[2] + v1[3] * v1[3]);
;                         u32x4 w; w.x = cvt_pk_bf16(v0[0], v0[1]); w.y = cvt_pk_bf16(v0[2], v0[3]); w.z = cvt_pk_bf16(v1[0], v1[1]); w.w = cvt_pk_bf16(v1[2], v1[3]);
;                         __builtin_amdgcn_raw_buffer_store_b128(w, rsrc, (unsigned)(o2 * 2), 0, 16); } }
;                 if (MODE != 2) { ss += __shfl_xor(ss, 16); ss += __shfl_xor(ss, 32); if (fq == 0) atomicAdd(rowsq + row, ss); } }
	v_lshlrev_b32_e32 v224, 16, v200
	v_and_b32_e32 v225, 0xffff0000, v200
	v_lshlrev_b32_e32 v226, 16, v201
	v_and_b32_e32 v227, 0xffff0000, v201
	v_lshlrev_b32_e32 v228, 16, v202
	v_and_b32_e32 v229, 0xffff0000, v202
	v_lshlrev_b32_e32 v230, 16, v203
	v_and_b32_e32 v231, 0xffff0000, v203
	v_pk_add_f32 v[44:45], v[44:45], v[224:225]
	v_pk_add_f32 v[46:47], v[46:47], v[226:227]
	v_pk_add_f32 v[40:41], v[40:41], v[228:229]
	v_pk_add_f32 v[42:43], v[42:43], v[230:231]
	v_mul_f32_e32 v237, v44, v44
	v_fmac_f32_e32 v237, v45, v45
	v_fmac_f32_e32 v237, v46, v46
	v_fmac_f32_e32 v237, v47, v47
	v_fmac_f32_e32 v237, v40, v40
	v_fmac_f32_e32 v237, v41, v41
	v_fmac_f32_e32 v237, v42, v42
	v_fmac_f32_e32 v237, v43, v43
	v_cvt_pk_bf16_f32 v44, v44, v45
	v_cvt_pk_bf16_f32 v45, v46, v47
	v_cvt_pk_bf16_f32 v46, v40, v41
	v_cvt_pk_bf16_f32 v47, v42, v43
	buffer_store_dwordx4 v[44:47], v147, s[8:11], 0 offen sc1
	v_lshlrev_b32_e32 v224, 16, v204
	v_and_b32_e32 v225, 0xffff0000, v204
	v_lshlrev_b32_e32 v226, 16, v205
	v_and_b32_e32 v227, 0xffff0000, v205
	v_lshlrev_b32_e32 v228, 16, v206
	v_and_b32_e32 v229, 0xffff0000, v206
	v_lshlrev_b32_e32 v230, 16, v207
	v_and_b32_e32 v231, 0xffff0000, v207
	v_pk_add_f32 v[36:37], v[36:37], v[224:225]
	v_pk_add_f32 v[38:39], v[38:39], v[226:227]
	v_pk_add_f32 v[32:33], v[32:33], v[228:229]
	v_pk_add_f32 v[34:35], v[34:35], v[230:231]
	v_fmac_f32_e32 v237, v36, v36
	v_fmac_f32_e32 v237, v37, v37
	v_fmac_f32_e32 v237, v38, v38
	v_fmac_f32_e32 v237, v39, v39
	v_fmac_f32_e32 v237, v32, v32
	v_fmac_f32_e32 v237, v33, v33
	v_fmac_f32_e32 v237, v34, v34
	v_fmac_f32_e32 v237, v35, v35
	v_cvt_pk_bf16_f32 v36, v36, v37
	v_cvt_pk_bf16_f32 v37, v38, v39
	v_cvt_pk_bf16_f32 v38, v32, v33
	v_cvt_pk_bf16_f32 v39, v34, v35
	buffer_store_dwordx4 v[36:39], v147, s[8:11], 0 offen offset:256 sc1
	s_waitcnt vmcnt(14)
	v_lshlrev_b32_e32 v224, 16, v208
	v_and_b32_e32 v225, 0xffff0000, v208
	v_lshlrev_b32_e32 v226, 16, v209
	v_and_b32_e32 v227, 0xffff0000, v209
	v_lshlrev_b32_e32 v228, 16, v210
	v_and_b32_e32 v229, 0xffff0000, v210
	v_lshlrev_b32_e32 v230, 16, v211
	v_and_b32_e32 v231, 0xffff0000, v211
	v_pk_add_f32 v[28:29], v[28:29], v[224:225]
	v_pk_add_f32 v[30:31], v[30:31], v[226:227]
	v_pk_add_f32 v[24:25], v[24:25], v[228:229]
	v_pk_add_f32 v[26:27], v[26:27], v[230:231]
	v_mul_f32_e32 v238, v28, v28
	v_fmac_f32_e32 v238, v29, v29
	v_fmac_f32_e32 v238, v30, v30
	v_fmac_f32_e32 v238, v31, v31
	v_fmac_f32_e32 v238, v24, v24
	v_fmac_f32_e32 v238, v25, v25
	v_fmac_f32_e32 v238, v26, v26
	v_fmac_f32_e32 v238, v27, v27
	v_cvt_pk_bf16_f32 v28, v28, v29
	v_cvt_pk_bf16_f32 v29, v30, v31
	v_cvt_pk_bf16_f32 v30, v24, v25
	v_cvt_pk_bf16_f32 v31, v26, v27
	buffer_store_dwordx4 v[28:31], v148, s[8:11], 0 offen sc1
	v_lshlrev_b32_e32 v224, 16, v212
	v_and_b32_e32 v225, 0xffff0000, v212
	v_lshlrev_b32_e32 v226, 16, v213
	v_and_b32_e32 v227, 0xffff0000, v213
	v_lshlrev_b32_e32 v228, 16, v214
	v_and_b32_e32 v229, 0xffff0000, v214
	v_lshlrev_b32_e32 v230, 16, v215
	v_and_b32_e32 v231, 0xffff0000, v215
	v_pk_add_f32 v[20:21], v[20:21], v[224:225]
	v_pk_add_f32 v[22:23], v[22:23], v[226:227]
	v_pk_add_f32 v[16:17], v[16:17], v[228:229]
	v_pk_add_f32 v[18:19], v[18:19], v[230:231]
	v_fmac_f32_e32 v238, v20, v20
	v_fmac_f32_e32 v238, v21, v21
	v_fmac_f32_e32 v238, v22, v22
	v_fmac_f32_e32 v238, v23, v23
	v_fmac_f32_e32 v238, v16, v16
	v_fmac_f32_e32 v238, v17, v17
	v_fmac_f32_e32 v238, v18, v18
	v_fmac_f32_e32 v238, v19, v19
	v_cvt_pk_bf16_f32 v20, v20, v21
	v_cvt_pk_bf16_f32 v21, v22, v23
	v_cvt_pk_bf16_f32 v22, v16, v17
	v_cvt_pk_bf16_f32 v23, v18, v19
	buffer_store_dwordx4 v[20:23], v148, s[8:11], 0 offen offset:256 sc1
	s_waitcnt vmcnt(14)
	v_lshlrev_b32_e32 v224, 16, v216
	v_and_b32_e32 v225, 0xffff0000, v216
	v_lshlrev_b32_e32 v226, 16, v217
	v_and_b32_e32 v227, 0xffff0000, v217
	v_lshlrev_b32_e32 v228, 16, v218
	v_and_b32_e32 v229, 0xffff0000, v218
	v_lshlrev_b32_e32 v230, 16, v219
	v_and_b32_e32 v231, 0xffff0000, v219
	v_pk_add_f32 v[12:13], v[12:13], v[224:225]
	v_pk_add_f32 v[14:15], v[14:15], v[226:227]
	v_pk_add_f32 v[8:9], v[8:9], v[228:229]
	v_pk_add_f32 v[10:11], v[10:11], v[230:231]
	v_mul_f32_e32 v239, v12, v12
	v_fmac_f32_e32 v239, v13, v13
	v_fmac_f32_e32 v239, v14, v14
	v_fmac_f32_e32 v239, v15, v15
	v_fmac_f32_e32 v239, v8, v8
	v_fmac_f32_e32 v239, v9, v9
	v_fmac_f32_e32 v239, v10, v10
	v_fmac_f32_e32 v239, v11, v11
	v_cvt_pk_bf16_f32 v12, v12, v13
	v_cvt_pk_bf16_f32 v13, v14, v15
	v_cvt_pk_bf16_f32 v14, v8, v9
	v_cvt_pk_bf16_f32 v15, v10, v11
	buffer_store_dwordx4 v[12:15], v149, s[8:11], 0 offen sc1
	v_lshlrev_b32_e32 v224, 16, v220
	v_and_b32_e32 v225, 0xffff0000, v220
	v_lshlrev_b32_e32 v226, 16, v221
	v_and_b32_e32 v227, 0xffff0000, v221
	v_lshlrev_b32_e32 v228, 16, v222
	v_and_b32_e32 v229, 0xffff0000, v222
	v_lshlrev_b32_e32 v230, 16, v223
	v_and_b32_e32 v231, 0xffff0000, v223
	v_pk_add_f32 v[4:5], v[4:5], v[224:225]
	v_pk_add_f32 v[6:7], v[6:7], v[226:227]
	v_pk_add_f32 v[0:1], v[0:1], v[228:229]
	v_pk_add_f32 v[2:3], v[2:3], v[230:231]
	v_fmac_f32_e32 v239, v4, v4
	v_fmac_f32_e32 v239, v5, v5
	v_fmac_f32_e32 v239, v6, v6
	v_fmac_f32_e32 v239, v7, v7
	v_fmac_f32_e32 v239, v0, v0
	v_fmac_f32_e32 v239, v1, v1
	v_fmac_f32_e32 v239, v2, v2
	v_fmac_f32_e32 v239, v3, v3
	v_cvt_pk_bf16_f32 v4, v4, v5
	v_cvt_pk_bf16_f32 v5, v6, v7
	v_cvt_pk_bf16_f32 v6, v0, v1
	v_cvt_pk_bf16_f32 v7, v2, v3
	buffer_store_dwordx4 v[4:7], v149, s[8:11], 0 offen offset:256 sc1
	ds_bpermute_b32 v240, v248, v232
	ds_bpermute_b32 v241, v248, v233
	ds_bpermute_b32 v242, v248, v234
	ds_bpermute_b32 v243, v248, v235
	ds_bpermute_b32 v244, v248, v236
	ds_bpermute_b32 v245, v248, v237
	ds_bpermute_b32 v246, v248, v238
	ds_bpermute_b32 v247, v248, v239
	s_waitcnt lgkmcnt(0)
; __device__ __forceinline__ unsigned cvt_pk_bf16(float lo, float hi) { f32x2_t v = {lo, hi}; bf16x2_t b = __builtin_convertvector(v, bf16x2_t); return __builtin_bit_cast(unsigned, b); }
;     __device__ __forceinline__ void operator()(const f32x4 (&acc)[2][2][4][2], const Unit& u, int wr, int wc, int fr, int fq) const {
;     ...
;             for (int m = 0; m < 4; ++m) { const int row = u.pm * BM + ai * HALF + wr * 64 + m * 16 + fr; const size_t off = (size_t)row * ldc + col0; float ss = 0.f;
; #pragma unroll
;                 for (int bj = 0; bj < 2; ++bj) { const size_t o2 = off + bj * HALF; f32x4 b0, b1;
;                     if (MODE == 0) { b0 = *(const f32x4*)(basef + o2); b1 = *(const f32x4*)(basef + o2 + 4); }
;                     else { const u32x4 w = *(const u32x4*)(xb + o2);
;                         b0 = (f32x4){__uint_as_float(w.x << 16), __uint_as_float(w.x & 0xffff0000u), __uint_as_float(w.y << 16), __uint_as_float(w.y & 0xffff0000u)};
;                         b1 = (f32x4){__uint_as_float(w.z << 16), __uint_as_float(w.z & 0xffff0000u), __uint_as_float(w.w << 16), __uint_as_float(w.w & 0xffff0000u)}; }
;                     const f32x4 v0 = b0 + acc[ai][bj][m][0], v1 = b1 + acc[ai][bj][m][1];
;                     if (MODE == 2) { *(f32x4*)(outf + o2) = v0; *(f32x4*)(outf + o2 + 4) = v1; }
;                     else { ss += (v0[0] * v0[0] + v0[1] * v0[1]) + (v0[2] * v0[2] + v0[3] * v0[3]) + (v1[0] * v1[0] + v1[1] * v1[1]) + (v1[2] * v1[2] + v1[3] * v1[3]);
;                         u32x4 w; w.x = cvt_pk_bf16(v0[0], v0[1]); w.y = cvt_pk_bf16(v0[2], v0[3]); w.z = cvt_pk_bf16(v1[0], v1[1]); w.w = cvt_pk_bf16(v1[2], v1[3]);
;                         __builtin_amdgcn_raw_buffer_store_b128(w, rsrc, (unsigned)(o2 * 2), 0, 16); } }
;                 if (MODE != 2) { ss += __shfl_xor(ss, 16); ss += __shfl_xor(ss, 32); if (fq == 0) atomicAdd(rowsq + row, ss); } }
	v_add_f32_e32 v232, v232, v240
	v_add_f32_e32 v233, v233, v241
	v_add_f32_e32 v234, v234, v242
	v_add_f32_e32 v235, v235, v243
	v_add_f32_e32 v236, v236, v244
	v_add_f32_e32 v237, v237, v245
	v_add_f32_e32 v238, v238, v246
	v_add_f32_e32 v239, v239, v247
	ds_bpermute_b32 v240, v249, v232
	ds_bpermute_b32 v241, v249, v233
	ds_bpermute_b32 v242, v249, v234
	ds_bpermute_b32 v243, v249, v235
	ds_bpermute_b32 v244, v249, v236
	ds_bpermute_b32 v245, v249, v237
	ds_bpermute_b32 v246, v249, v238
	ds_bpermute_b32 v247, v249, v239
	v_lshl_add_u32 v224, s40, 8, v129
	v_ashrrev_i32_e32 v225, 31, v224
	v_lshl_add_u64 v[224:225], v[224:225], 2, s[22:23]
	s_waitcnt lgkmcnt(0)
	v_add_f32_e32 v232, v232, v240
	v_add_f32_e32 v233, v233, v241
	v_add_f32_e32 v234, v234, v242
	v_add_f32_e32 v235, v235, v243
	v_add_f32_e32 v236, v236, v244
	v_add_f32_e32 v237, v237, v245
	v_add_f32_e32 v238, v238, v246
	v_add_f32_e32 v239, v239, v247
	s_and_saveexec_b64 s[40:41], s[4:5]
	global_atomic_add_f32 v[224:225], v232, off
	global_atomic_add_f32 v[224:225], v233, off offset:64
	global_atomic_add_f32 v[224:225], v234, off offset:128
	global_atomic_add_f32 v[224:225], v235, off offset:192
	global_atomic_add_f32 v[224:225], v236, off offset:512
	global_atomic_add_f32 v[224:225], v237, off offset:576
	global_atomic_add_f32 v[224:225], v238, off offset:640
	global_atomic_add_f32 v[224:225], v239, off offset:704
	s_or_b64 exec, exec, s[40:41]
	s_branch .Lpp5_done
.Lpp5_plain:
	v_lshl_add_u32 v156, s40, 8, v129
	v_lshl_or_b32 v157, s42, 8, v151
	v_lshl_add_u32 v156, v156, 10, v157
	v_lshlrev_b32_e32 v156, 1, v156
	v_add_u32_e32 v157, 0x8000, v156
	v_add_u32_e32 v158, 0x10000, v156
	v_add_u32_e32 v159, 0x18000, v156
	v_add_u32_e32 v146, 0x40000, v156
	v_add_u32_e32 v147, 0x48000, v156
	v_add_u32_e32 v148, 0x50000, v156
	v_add_u32_e32 v149, 0x58000, v156
	global_load_dwordx4 v[160:163], v156, s[96:97]
	global_load_dwordx4 v[164:167], v156, s[96:97] offset:256
	global_load_dwordx4 v[168:171], v157, s[96:97]
	global_load_dwordx4 v[172:175], v157, s[96:97] offset:256
	global_load_dwordx4 v[176:179], v158, s[96:97]
	global_load_dwordx4 v[180:183], v158, s[96:97] offset:256
	global_load_dwordx4 v[184:187], v159, s[96:97]
	global_load_dwordx4 v[188:191], v159, s[96:97] offset:256
	global_load_dwordx4 v[192:195], v146, s[96:97]
	global_load_dwordx4 v[196:199], v146, s[96:97] offset:256
	global_load_dwordx4 v[200:203], v147, s[96:97]
	global_load_dwordx4 v[204:207], v147, s[96:97] offset:256
	global_load_dwordx4 v[208:211], v148, s[96:97]
	global_load_dwordx4 v[212:215], v148, s[96:97] offset:256
	global_load_dwordx4 v[216:219], v149, s[96:97]
	global_load_dwordx4 v[220:223], v149, s[96:97] offset:256
	v_xor_b32_e32 v248, 16, v155
	v_xor_b32_e32 v249, 32, v155
	v_lshlrev_b32_e32 v248, 2, v248
	v_lshlrev_b32_e32 v249, 2, v249
	s_waitcnt vmcnt(14)
	v_lshlrev_b32_e32 v224, 16, v160
	v_and_b32_e32 v225, 0xffff0000, v160
	v_lshlrev_b32_e32 v226, 16, v161
	v_and_b32_e32 v227, 0xffff0000, v161
	v_lshlrev_b32_e32 v228, 16, v162
	v_and_b32_e32 v229, 0xffff0000, v162
	v_lshlrev_b32_e32 v230, 16, v163
	v_and_b32_e32 v231, 0xffff0000, v163
	v_pk_add_f32 v[124:125], v[124:125], v[224:225]
	v_pk_add_f32 v[126:127], v[126:127], v[226:227]
	v_pk_add_f32 v[120:121], v[120:121], v[228:229]
	v_pk_add_f32 v[122:123], v[122:123], v[230:231]
	v_mul_f32_e32 v232, v124, v124
	v_fmac_f32_e32 v232, v125, v125
	v_fmac_f32_e32 v232, v126, v126
	v_fmac_f32_e32 v232, v127, v127
	v_fmac_f32_e32 v232, v120, v120
	v_fmac_f32_e32 v232, v121, v121
	v_fmac_f32_e32 v232, v122, v122
	v_fmac_f32_e32 v232, v123, v123
	v_cvt_pk_bf16_f32 v124, v124, v125
	v_cvt_pk_bf16_f32 v125, v126, v127
	v_cvt_pk_bf16_f32 v126, v120, v121
	v_cvt_pk_bf16_f32 v127, v122, v123
	buffer_store_dwordx4 v[124:127], v156, s[8:11], 0 offen
	v_lshlrev_b32_e32 v224, 16, v164
	v_and_b32_e32 v225, 0xffff0000, v164
	v_lshlrev_b32_e32 v226, 16, v165
	v_and_b32_e32 v227, 0xffff0000, v165
	v_lshlrev_b32_e32 v228, 16, v166
	v_and_b32_e32 v229, 0xffff0000, v166
	v_lshlrev_b32_e32 v230, 16, v167
	v_and_b32_e32 v231, 0xffff0000, v167
	v_pk_add_f32 v[116:117], v[116:117], v[224:225]
	v_pk_add_f32 v[118:119], v[118:119], v[226:227]
	v_pk_add_f32 v[112:113], v[112:113], v[228:229]
	v_pk_add_f32 v[114:115], v[114:115], v[230:231]
	v_fmac_f32_e32 v232, v116, v116
	v_fmac_f32_e32 v232, v117, v117
	v_fmac_f32_e32 v232, v118, v118
	v_fmac_f32_e32 v232, v119, v119
	v_fmac_f32_e32 v232, v112, v112
	v_fmac_f32_e32 v232, v113, v113
	v_fmac_f32_e32 v232, v114, v114
	v_fmac_f32_e32 v232, v115, v115
	v_cvt_pk_bf16_f32 v116, v116, v117
	v_cvt_pk_bf16_f32 v117, v118, v119
	v_cvt_pk_bf16_f32 v118, v112, v113
	v_cvt_pk_bf16_f32 v119, v114, v115
	buffer_store_dwordx4 v[116:119], v156, s[8:11], 0 offen offset:256
	s_waitcnt vmcnt(14)
; __device__ __forceinline__ unsigned cvt_pk_bf16(float lo, float hi) { f32x2_t v = {lo, hi}; bf16x2_t b = __builtin_convertvector(v, bf16x2_t); return __builtin_bit_cast(unsigned, b); }
;     __device__ __forceinline__ void operator()(const f32x4 (&acc)[2][2][4][2], const Unit& u, int wr, int wc, int fr, int fq) const {
;     ...
;             for (int m = 0; m < 4; ++m) { const int row = u.pm * BM + ai * HALF + wr * 64 + m * 16 + fr; const size_t off = (size_t)row * ldc + col0; float ss = 0.f;
; #pragma unroll
;                 for (int bj = 0; bj < 2; ++bj) { const size_t o2 = off + bj * HALF; f32x4 b0, b1;
;                     if (MODE == 0) { b0 = *(const f32x4*)(basef + o2); b1 = *(const f32x4*)(basef + o2 + 4); }
;                     else { const u32x4 w = *(const u32x4*)(xb + o2);
;                         b0 = (f32x4){__uint_as_float(w.x << 16), __uint_as_float(w.x & 0xffff0000u), __uint_as_float(w.y << 16), __uint_as_float(w.y & 0xffff0000u)};
;                         b1 = (f32x4){__uint_as_float(w.z << 16), __uint_as_float(w.z & 0xffff0000u), __uint_as_float(w.w << 16), __uint_as_float(w.w & 0xffff0000u)}; }
;                     const f32x4 v0 = b0 + acc[ai][bj][m][0], v1 = b1 + acc[ai][bj][m][1];
;                     if (MODE == 2) { *(f32x4*)(outf + o2) = v0; *(f32x4*)(outf + o2 + 4) = v1; }
;                     else { ss += (v0[0] * v0[0] + v0[1] * v0[1]) + (v0[2] * v0[2] + v0[3] * v0[3]) + (v1[0] * v1[0] + v1[1] * v1[1]) + (v1[2] * v1[2] + v1[3] * v1[3]);
;                         u32x4 w; w.x = cvt_pk_bf16(v0[0], v0[1]); w.y = cvt_pk_bf16(v0[2], v0[3]); w.z = cvt_pk_bf16(v1[0], v1[1]); w.w = cvt_pk_bf16(v1[2], v1[3]);
;                         __builtin_amdgcn_raw_buffer_store_b128(w, rsrc, (unsigned)(o2 * 2), 0, 16); } }
;                 if (MODE != 2) { ss += __shfl_xor(ss, 16); ss += __shfl_xor(ss, 32); if (fq == 0) atomicAdd(rowsq + row, ss); } }
	v_lshlrev_b32_e32 v224, 16, v168
	v_and_b32_e32 v225, 0xffff0000, v168
	v_lshlrev_b32_e32 v226, 16, v169
	v_and_b32_e32 v227, 0xffff0000, v169
	v_lshlrev_b32_e32 v228, 16, v170
	v_and_b32_e32 v229, 0xffff0000, v170
	v_lshlrev_b32_e32 v230, 16, v171
	v_and_b32_e32 v231, 0xffff0000, v171
	v_pk_add_f32 v[108:109], v[108:109], v[224:225]
	v_pk_add_f32 v[110:111], v[110:111], v[226:227]
	v_pk_add_f32 v[104:105], v[104:105], v[228:229]
	v_pk_add_f32 v[106:107], v[106:107], v[230:231]
	v_mul_f32_e32 v233, v108, v108
	v_fmac_f32_e32 v233, v109, v109
	v_fmac_f32_e32 v233, v110, v110
	v_fmac_f32_e32 v233, v111, v111
	v_fmac_f32_e32 v233, v104, v104
	v_fmac_f32_e32 v233, v105, v105
	v_fmac_f32_e32 v233, v106, v106
	v_fmac_f32_e32 v233, v107, v107
	v_cvt_pk_bf16_f32 v108, v108, v109
	v_cvt_pk_bf16_f32 v109, v110, v111
	v_cvt_pk_bf16_f32 v110, v104, v105
	v_cvt_pk_bf16_f32 v111, v106, v107
	buffer_store_dwordx4 v[108:111], v157, s[8:11], 0 offen
	v_lshlrev_b32_e32 v224, 16, v172
	v_and_b32_e32 v225, 0xffff0000, v172
	v_lshlrev_b32_e32 v226, 16, v173
	v_and_b32_e32 v227, 0xffff0000, v173
	v_lshlrev_b32_e32 v228, 16, v174
	v_and_b32_e32 v229, 0xffff0000, v174
	v_lshlrev_b32_e32 v230, 16, v175
	v_and_b32_e32 v231, 0xffff0000, v175
	v_pk_add_f32 v[100:101], v[100:101], v[224:225]
	v_pk_add_f32 v[102:103], v[102:103], v[226:227]
	v_pk_add_f32 v[96:97], v[96:97], v[228:229]
	v_pk_add_f32 v[98:99], v[98:99], v[230:231]
	v_fmac_f32_e32 v233, v100, v100
	v_fmac_f32_e32 v233, v101, v101
	v_fmac_f32_e32 v233, v102, v102
	v_fmac_f32_e32 v233, v103, v103
	v_fmac_f32_e32 v233, v96, v96
	v_fmac_f32_e32 v233, v97, v97
	v_fmac_f32_e32 v233, v98, v98
	v_fmac_f32_e32 v233, v99, v99
	v_cvt_pk_bf16_f32 v100, v100, v101
	v_cvt_pk_bf16_f32 v101, v102, v103
	v_cvt_pk_bf16_f32 v102, v96, v97
	v_cvt_pk_bf16_f32 v103, v98, v99
	buffer_store_dwordx4 v[100:103], v157, s[8:11], 0 offen offset:256
	s_waitcnt vmcnt(14)
	v_lshlrev_b32_e32 v224, 16, v176
	v_and_b32_e32 v225, 0xffff0000, v176
	v_lshlrev_b32_e32 v226, 16, v177
	v_and_b32_e32 v227, 0xffff0000, v177
	v_lshlrev_b32_e32 v228, 16, v178
	v_and_b32_e32 v229, 0xffff0000, v178
	v_lshlrev_b32_e32 v230, 16, v179
	v_and_b32_e32 v231, 0xffff0000, v179
	v_pk_add_f32 v[92:93], v[92:93], v[224:225]
	v_pk_add_f32 v[94:95], v[94:95], v[226:227]
	v_pk_add_f32 v[88:89], v[88:89], v[228:229]
	v_pk_add_f32 v[90:91], v[90:91], v[230:231]
	v_mul_f32_e32 v234, v92, v92
	v_fmac_f32_e32 v234, v93, v93
	v_fmac_f32_e32 v234, v94, v94
	v_fmac_f32_e32 v234, v95, v95
	v_fmac_f32_e32 v234, v88, v88
	v_fmac_f32_e32 v234, v89, v89
	v_fmac_f32_e32 v234, v90, v90
	v_fmac_f32_e32 v234, v91, v91
	v_cvt_pk_bf16_f32 v92, v92, v93
	v_cvt_pk_bf16_f32 v93, v94, v95
	v_cvt_pk_bf16_f32 v94, v88, v89
	v_cvt_pk_bf16_f32 v95, v90, v91
	buffer_store_dwordx4 v[92:95], v158, s[8:11], 0 offen
	v_lshlrev_b32_e32 v224, 16, v180
	v_and_b32_e32 v225, 0xffff0000, v180
	v_lshlrev_b32_e32 v226, 16, v181
	v_and_b32_e32 v227, 0xffff0000, v181
	v_lshlrev_b32_e32 v228, 16, v182
	v_and_b32_e32 v229, 0xffff0000, v182
	v_lshlrev_b32_e32 v230, 16, v183
	v_and_b32_e32 v231, 0xffff0000, v183
	v_pk_add_f32 v[84:85], v[84:85], v[224:225]
	v_pk_add_f32 v[86:87], v[86:87], v[226:227]
	v_pk_add_f32 v[80:81], v[80:81], v[228:229]
	v_pk_add_f32 v[82:83], v[82:83], v[230:231]
	v_fmac_f32_e32 v234, v84, v84
	v_fmac_f32_e32 v234, v85, v85
	v_fmac_f32_e32 v234, v86, v86
	v_fmac_f32_e32 v234, v87, v87
	v_fmac_f32_e32 v234, v80, v80
	v_fmac_f32_e32 v234, v81, v81
	v_fmac_f32_e32 v234, v82, v82
	v_fmac_f32_e32 v234, v83, v83
	v_cvt_pk_bf16_f32 v84, v84, v85
	v_cvt_pk_bf16_f32 v85, v86, v87
	v_cvt_pk_bf16_f32 v86, v80, v81
	v_cvt_pk_bf16_f32 v87, v82, v83
	buffer_store_dwordx4 v[84:87], v158, s[8:11], 0 offen offset:256
	s_waitcnt vmcnt(14)
	v_lshlrev_b32_e32 v224, 16, v184
	v_and_b32_e32 v225, 0xffff0000, v184
	v_lshlrev_b32_e32 v226, 16, v185
	v_and_b32_e32 v227, 0xffff0000, v185
	v_lshlrev_b32_e32 v228, 16, v186
	v_and_b32_e32 v229, 0xffff0000, v186
	v_lshlrev_b32_e32 v230, 16, v187
	v_and_b32_e32 v231, 0xffff0000, v187
	v_pk_add_f32 v[76:77], v[76:77], v[224:225]
	v_pk_add_f32 v[78:79], v[78:79], v[226:227]
	v_pk_add_f32 v[72:73], v[72:73], v[228:229]
	v_pk_add_f32 v[74:75], v[74:75], v[230:231]
	v_mul_f32_e32 v235, v76, v76
	v_fmac_f32_e32 v235, v77, v77
	v_fmac_f32_e32 v235, v78, v78
	v_fmac_f32_e32 v235, v79, v79
	v_fmac_f32_e32 v235, v72, v72
	v_fmac_f32_e32 v235, v73, v73
	v_fmac_f32_e32 v235, v74, v74
	v_fmac_f32_e32 v235, v75, v75
	v_cvt_pk_bf16_f32 v76, v76, v77
	v_cvt_pk_bf16_f32 v77, v78, v79
	v_cvt_pk_bf16_f32 v78, v72, v73
	v_cvt_pk_bf16_f32 v79, v74, v75
	buffer_store_dwordx4 v[76:79], v159, s[8:11], 0 offen
	v_lshlrev_b32_e32 v224, 16, v188
	v_and_b32_e32 v225, 0xffff0000, v188
	v_lshlrev_b32_e32 v226, 16, v189
	v_and_b32_e32 v227, 0xffff0000, v189
	v_lshlrev_b32_e32 v228, 16, v190
	v_and_b32_e32 v229, 0xffff0000, v190
	v_lshlrev_b32_e32 v230, 16, v191
	v_and_b32_e32 v231, 0xffff0000, v191
	v_pk_add_f32 v[68:69], v[68:69], v[224:225]
	v_pk_add_f32 v[70:71], v[70:71], v[226:227]
	v_pk_add_f32 v[64:65], v[64:65], v[228:229]
	v_pk_add_f32 v[66:67], v[66:67], v[230:231]
	v_fmac_f32_e32 v235, v68, v68
	v_fmac_f32_e32 v235, v69, v69
	v_fmac_f32_e32 v235, v70, v70
	v_fmac_f32_e32 v235, v71, v71
	v_fmac_f32_e32 v235, v64, v64
	v_fmac_f32_e32 v235, v65, v65
	v_fmac_f32_e32 v235, v66, v66
	v_fmac_f32_e32 v235, v67, v67
	v_cvt_pk_bf16_f32 v68, v68, v69
	v_cvt_pk_bf16_f32 v69, v70, v71
	v_cvt_pk_bf16_f32 v70, v64, v65
	v_cvt_pk_bf16_f32 v71, v66, v67
	buffer_store_dwordx4 v[68:71], v159, s[8:11], 0 offen offset:256
	s_waitcnt vmcnt(14)
; __device__ __forceinline__ unsigned cvt_pk_bf16(float lo, float hi) { f32x2_t v = {lo, hi}; bf16x2_t b = __builtin_convertvector(v, bf16x2_t); return __builtin_bit_cast(unsigned, b); }
;     __device__ __forceinline__ void operator()(const f32x4 (&acc)[2][2][4][2], const Unit& u, int wr, int wc, int fr, int fq) const {
;     ...
;             for (int m = 0; m < 4; ++m) { const int row = u.pm * BM + ai * HALF + wr * 64 + m * 16 + fr; const size_t off = (size_t)row * ldc + col0; float ss = 0.f;
; #pragma unroll
;                 for (int bj = 0; bj < 2; ++bj) { const size_t o2 = off + bj * HALF; f32x4 b0, b1;
;                     if (MODE == 0) { b0 = *(const f32x4*)(basef + o2); b1 = *(const f32x4*)(basef + o2 + 4); }
;                     else { const u32x4 w = *(const u32x4*)(xb + o2);
;                         b0 = (f32x4){__uint_as_float(w.x << 16), __uint_as_float(w.x & 0xffff0000u), __uint_as_float(w.y << 16), __uint_as_float(w.y & 0xffff0000u)};
;                         b1 = (f32x4){__uint_as_float(w.z << 16), __uint_as_float(w.z & 0xffff0000u), __uint_as_float(w.w << 16), __uint_as_float(w.w & 0xffff0000u)}; }
;                     const f32x4 v0 = b0 + acc[ai][bj][m][0], v1 = b1 + acc[ai][bj][m][1];
;                     if (MODE == 2) { *(f32x4*)(outf + o2) = v0; *(f32x4*)(outf + o2 + 4) = v1; }
;                     else { ss += (v0[0] * v0[0] + v0[1] * v0[1]) + (v0[2] * v0[2] + v0[3] * v0[3]) + (v1[0] * v1[0] + v1[1] * v1[1]) + (v1[2] * v1[2] + v1[3] * v1[3]);
;                         u32x4 w; w.x = cvt_pk_bf16(v0[0], v0[1]); w.y = cvt_pk_bf16(v0[2], v0[3]); w.z = cvt_pk_bf16(v1[0], v1[1]); w.w = cvt_pk_bf16(v1[2], v1[3]);
;                         __builtin_amdgcn_raw_buffer_store_b128(w, rsrc, (unsigned)(o2 * 2), 0, 16); } }
;                 if (MODE != 2) { ss += __shfl_xor(ss, 16); ss += __shfl_xor(ss, 32); if (fq == 0) atomicAdd(rowsq + row, ss); } }
	v_lshlrev_b32_e32 v224, 16, v192
	v_and_b32_e32 v225, 0xffff0000, v192
	v_lshlrev_b32_e32 v226, 16, v193
	v_and_b32_e32 v227, 0xffff0000, v193
	v_lshlrev_b32_e32 v228, 16, v194
	v_and_b32_e32 v229, 0xffff0000, v194
	v_lshlrev_b32_e32 v230, 16, v195
	v_and_b32_e32 v231, 0xffff0000, v195
	v_pk_add_f32 v[60:61], v[60:61], v[224:225]
	v_pk_add_f32 v[62:63], v[62:63], v[226:227]
	v_pk_add_f32 v[56:57], v[56:57], v[228:229]
	v_pk_add_f32 v[58:59], v[58:59], v[230:231]
	v_mul_f32_e32 v236, v60, v60
	v_fmac_f32_e32 v236, v61, v61
	v_fmac_f32_e32 v236, v62, v62
	v_fmac_f32_e32 v236, v63, v63
	v_fmac_f32_e32 v236, v56, v56
	v_fmac_f32_e32 v236, v57, v57
	v_fmac_f32_e32 v236, v58, v58
	v_fmac_f32_e32 v236, v59, v59
	v_cvt_pk_bf16_f32 v60, v60, v61
	v_cvt_pk_bf16_f32 v61, v62, v63
	v_cvt_pk_bf16_f32 v62, v56, v57
	v_cvt_pk_bf16_f32 v63, v58, v59
	buffer_store_dwordx4 v[60:63], v146, s[8:11], 0 offen
	v_lshlrev_b32_e32 v224, 16, v196
	v_and_b32_e32 v225, 0xffff0000, v196
	v_lshlrev_b32_e32 v226, 16, v197
	v_and_b32_e32 v227, 0xffff0000, v197
	v_lshlrev_b32_e32 v228, 16, v198
	v_and_b32_e32 v229, 0xffff0000, v198
	v_lshlrev_b32_e32 v230, 16, v199
	v_and_b32_e32 v231, 0xffff0000, v199
	v_pk_add_f32 v[52:53], v[52:53], v[224:225]
	v_pk_add_f32 v[54:55], v[54:55], v[226:227]
	v_pk_add_f32 v[48:49], v[48:49], v[228:229]
	v_pk_add_f32 v[50:51], v[50:51], v[230:231]
	v_fmac_f32_e32 v236, v52, v52
	v_fmac_f32_e32 v236, v53, v53
	v_fmac_f32_e32 v236, v54, v54
	v_fmac_f32_e32 v236, v55, v55
	v_fmac_f32_e32 v236, v48, v48
	v_fmac_f32_e32 v236, v49, v49
	v_fmac_f32_e32 v236, v50, v50
	v_fmac_f32_e32 v236, v51, v51
	v_cvt_pk_bf16_f32 v52, v52, v53
	v_cvt_pk_bf16_f32 v53, v54, v55
	v_cvt_pk_bf16_f32 v54, v48, v49
	v_cvt_pk_bf16_f32 v55, v50, v51
	buffer_store_dwordx4 v[52:55], v146, s[8:11], 0 offen offset:256
	s_waitcnt vmcnt(14)
	v_lshlrev_b32_e32 v224, 16, v200
	v_and_b32_e32 v225, 0xffff0000, v200
	v_lshlrev_b32_e32 v226, 16, v201
	v_and_b32_e32 v227, 0xffff0000, v201
	v_lshlrev_b32_e32 v228, 16, v202
	v_and_b32_e32 v229, 0xffff0000, v202
	v_lshlrev_b32_e32 v230, 16, v203
	v_and_b32_e32 v231, 0xffff0000, v203
	v_pk_add_f32 v[44:45], v[44:45], v[224:225]
	v_pk_add_f32 v[46:47], v[46:47], v[226:227]
	v_pk_add_f32 v[40:41], v[40:41], v[228:229]
	v_pk_add_f32 v[42:43], v[42:43], v[230:231]
	v_mul_f32_e32 v237, v44, v44
	v_fmac_f32_e32 v237, v45, v45
	v_fmac_f32_e32 v237, v46, v46
	v_fmac_f32_e32 v237, v47, v47
	v_fmac_f32_e32 v237, v40, v40
	v_fmac_f32_e32 v237, v41, v41
	v_fmac_f32_e32 v237, v42, v42
	v_fmac_f32_e32 v237, v43, v43
	v_cvt_pk_bf16_f32 v44, v44, v45
	v_cvt_pk_bf16_f32 v45, v46, v47
	v_cvt_pk_bf16_f32 v46, v40, v41
	v_cvt_pk_bf16_f32 v47, v42, v43
	buffer_store_dwordx4 v[44:47], v147, s[8:11], 0 offen
	v_lshlrev_b32_e32 v224, 16, v204
	v_and_b32_e32 v225, 0xffff0000, v204
	v_lshlrev_b32_e32 v226, 16, v205
	v_and_b32_e32 v227, 0xffff0000, v205
	v_lshlrev_b32_e32 v228, 16, v206
	v_and_b32_e32 v229, 0xffff0000, v206
	v_lshlrev_b32_e32 v230, 16, v207
	v_and_b32_e32 v231, 0xffff0000, v207
	v_pk_add_f32 v[36:37], v[36:37], v[224:225]
	v_pk_add_f32 v[38:39], v[38:39], v[226:227]
	v_pk_add_f32 v[32:33], v[32:33], v[228:229]
	v_pk_add_f32 v[34:35], v[34:35], v[230:231]
	v_fmac_f32_e32 v237, v36, v36
	v_fmac_f32_e32 v237, v37, v37
	v_fmac_f32_e32 v237, v38, v38
	v_fmac_f32_e32 v237, v39, v39
	v_fmac_f32_e32 v237, v32, v32
	v_fmac_f32_e32 v237, v33, v33
	v_fmac_f32_e32 v237, v34, v34
	v_fmac_f32_e32 v237, v35, v35
	v_cvt_pk_bf16_f32 v36, v36, v37
	v_cvt_pk_bf16_f32 v37, v38, v39
	v_cvt_pk_bf16_f32 v38, v32, v33
	v_cvt_pk_bf16_f32 v39, v34, v35
	buffer_store_dwordx4 v[36:39], v147, s[8:11], 0 offen offset:256
	s_waitcnt vmcnt(14)
; __device__ __forceinline__ unsigned cvt_pk_bf16(float lo, float hi) { f32x2_t v = {lo, hi}; bf16x2_t b = __builtin_convertvector(v, bf16x2_t); return __builtin_bit_cast(unsigned, b); }
;     __device__ __forceinline__ void operator()(const f32x4 (&acc)[2][2][4][2], const Unit& u, int wr, int wc, int fr, int fq) const {
;     ...
;             for (int m = 0; m < 4; ++m) { const int row = u.pm * BM + ai * HALF + wr * 64 + m * 16 + fr; const size_t off = (size_t)row * ldc + col0; float ss = 0.f;
; #pragma unroll
;                 for (int bj = 0; bj < 2; ++bj) { const size_t o2 = off + bj * HALF; f32x4 b0, b1;
;                     if (MODE == 0) { b0 = *(const f32x4*)(basef + o2); b1 = *(const f32x4*)(basef + o2 + 4); }
;                     else { const u32x4 w = *(const u32x4*)(xb + o2);
;                         b0 = (f32x4){__uint_as_float(w.x << 16), __uint_as_float(w.x & 0xffff0000u), __uint_as_float(w.y << 16), __uint_as_float(w.y & 0xffff0000u)};
;                         b1 = (f32x4){__uint_as_float(w.z << 16), __uint_as_float(w.z & 0xffff0000u), __uint_as_float(w.w << 16), __uint_as_float(w.w & 0xffff0000u)}; }
;                     const f32x4 v0 = b0 + acc[ai][bj][m][0], v1 = b1 + acc[ai][bj][m][1];
;                     if (MODE == 2) { *(f32x4*)(outf + o2) = v0; *(f32x4*)(outf + o2 + 4) = v1; }
;                     else { ss += (v0[0] * v0[0] + v0[1] * v0[1]) + (v0[2] * v0[2] + v0[3] * v0[3]) + (v1[0] * v1[0] + v1[1] * v1[1]) + (v1[2] * v1[2] + v1[3] * v1[3]);
;                         u32x4 w; w.x = cvt_pk_bf16(v0[0], v0[1]); w.y = cvt_pk_bf16(v0[2], v0[3]); w.z = cvt_pk_bf16(v1[0], v1[1]); w.w = cvt_pk_bf16(v1[2], v1[3]);
;                         __builtin_amdgcn_raw_buffer_store_b128(w, rsrc, (unsigned)(o2 * 2), 0, 16); } }
;                 if (MODE != 2) { ss += __shfl_xor(ss, 16); ss += __shfl_xor(ss, 32); if (fq == 0) atomicAdd(rowsq + row, ss); } }
	v_lshlrev_b32_e32 v224, 16, v208
	v_and_b32_e32 v225, 0xffff0000, v208
	v_lshlrev_b32_e32 v226, 16, v209
	v_and_b32_e32 v227, 0xffff0000, v209
	v_lshlrev_b32_e32 v228, 16, v210
	v_and_b32_e32 v229, 0xffff0000, v210
	v_lshlrev_b32_e32 v230, 16, v211
	v_and_b32_e32 v231, 0xffff0000, v211
	v_pk_add_f32 v[28:29], v[28:29], v[224:225]
	v_pk_add_f32 v[30:31], v[30:31], v[226:227]
	v_pk_add_f32 v[24:25], v[24:25], v[228:229]
	v_pk_add_f32 v[26:27], v[26:27], v[230:231]
	v_mul_f32_e32 v238, v28, v28
	v_fmac_f32_e32 v238, v29, v29
	v_fmac_f32_e32 v238, v30, v30
	v_fmac_f32_e32 v238, v31, v31
	v_fmac_f32_e32 v238, v24, v24
	v_fmac_f32_e32 v238, v25, v25
	v_fmac_f32_e32 v238, v26, v26
	v_fmac_f32_e32 v238, v27, v27
	v_cvt_pk_bf16_f32 v28, v28, v29
	v_cvt_pk_bf16_f32 v29, v30, v31
	v_cvt_pk_bf16_f32 v30, v24, v25
	v_cvt_pk_bf16_f32 v31, v26, v27
	buffer_store_dwordx4 v[28:31], v148, s[8:11], 0 offen
	v_lshlrev_b32_e32 v224, 16, v212
	v_and_b32_e32 v225, 0xffff0000, v212
	v_lshlrev_b32_e32 v226, 16, v213
	v_and_b32_e32 v227, 0xffff0000, v213
	v_lshlrev_b32_e32 v228, 16, v214
	v_and_b32_e32 v229, 0xffff0000, v214
	v_lshlrev_b32_e32 v230, 16, v215
	v_and_b32_e32 v231, 0xffff0000, v215
	v_pk_add_f32 v[20:21], v[20:21], v[224:225]
	v_pk_add_f32 v[22:23], v[22:23], v[226:227]
	v_pk_add_f32 v[16:17], v[16:17], v[228:229]
	v_pk_add_f32 v[18:19], v[18:19], v[230:231]
	v_fmac_f32_e32 v238, v20, v20
	v_fmac_f32_e32 v238, v21, v21
	v_fmac_f32_e32 v238, v22, v22
	v_fmac_f32_e32 v238, v23, v23
	v_fmac_f32_e32 v238, v16, v16
	v_fmac_f32_e32 v238, v17, v17
	v_fmac_f32_e32 v238, v18, v18
	v_fmac_f32_e32 v238, v19, v19
	v_cvt_pk_bf16_f32 v20, v20, v21
	v_cvt_pk_bf16_f32 v21, v22, v23
	v_cvt_pk_bf16_f32 v22, v16, v17
	v_cvt_pk_bf16_f32 v23, v18, v19
	buffer_store_dwordx4 v[20:23], v148, s[8:11], 0 offen offset:256
	s_waitcnt vmcnt(14)
	v_lshlrev_b32_e32 v224, 16, v216
	v_and_b32_e32 v225, 0xffff0000, v216
	v_lshlrev_b32_e32 v226, 16, v217
	v_and_b32_e32 v227, 0xffff0000, v217
	v_lshlrev_b32_e32 v228, 16, v218
	v_and_b32_e32 v229, 0xffff0000, v218
	v_lshlrev_b32_e32 v230, 16, v219
	v_and_b32_e32 v231, 0xffff0000, v219
	v_pk_add_f32 v[12:13], v[12:13], v[224:225]
	v_pk_add_f32 v[14:15], v[14:15], v[226:227]
	v_pk_add_f32 v[8:9], v[8:9], v[228:229]
	v_pk_add_f32 v[10:11], v[10:11], v[230:231]
	v_mul_f32_e32 v239, v12, v12
	v_fmac_f32_e32 v239, v13, v13
	v_fmac_f32_e32 v239, v14, v14
	v_fmac_f32_e32 v239, v15, v15
	v_fmac_f32_e32 v239, v8, v8
	v_fmac_f32_e32 v239, v9, v9
	v_fmac_f32_e32 v239, v10, v10
	v_fmac_f32_e32 v239, v11, v11
	v_cvt_pk_bf16_f32 v12, v12, v13
	v_cvt_pk_bf16_f32 v13, v14, v15
	v_cvt_pk_bf16_f32 v14, v8, v9
	v_cvt_pk_bf16_f32 v15, v10, v11
	buffer_store_dwordx4 v[12:15], v149, s[8:11], 0 offen
	v_lshlrev_b32_e32 v224, 16, v220
	v_and_b32_e32 v225, 0xffff0000, v220
	v_lshlrev_b32_e32 v226, 16, v221
	v_and_b32_e32 v227, 0xffff0000, v221
	v_lshlrev_b32_e32 v228, 16, v222
	v_and_b32_e32 v229, 0xffff0000, v222
	v_lshlrev_b32_e32 v230, 16, v223
	v_and_b32_e32 v231, 0xffff0000, v223
	v_pk_add_f32 v[4:5], v[4:5], v[224:225]
	v_pk_add_f32 v[6:7], v[6:7], v[226:227]
	v_pk_add_f32 v[0:1], v[0:1], v[228:229]
	v_pk_add_f32 v[2:3], v[2:3], v[230:231]
	v_fmac_f32_e32 v239, v4, v4
	v_fmac_f32_e32 v239, v5, v5
	v_fmac_f32_e32 v239, v6, v6
	v_fmac_f32_e32 v239, v7, v7
	v_fmac_f32_e32 v239, v0, v0
	v_fmac_f32_e32 v239, v1, v1
	v_fmac_f32_e32 v239, v2, v2
	v_fmac_f32_e32 v239, v3, v3
	v_cvt_pk_bf16_f32 v4, v4, v5
	v_cvt_pk_bf16_f32 v5, v6, v7
	v_cvt_pk_bf16_f32 v6, v0, v1
	v_cvt_pk_bf16_f32 v7, v2, v3
	buffer_store_dwordx4 v[4:7], v149, s[8:11], 0 offen offset:256
	ds_bpermute_b32 v240, v248, v232
	ds_bpermute_b32 v241, v248, v233
	ds_bpermute_b32 v242, v248, v234
	ds_bpermute_b32 v243, v248, v235
	ds_bpermute_b32 v244, v248, v236
	ds_bpermute_b32 v245, v248, v237
	ds_bpermute_b32 v246, v248, v238
	ds_bpermute_b32 v247, v248, v239
	s_waitcnt lgkmcnt(0)
	v_add_f32_e32 v232, v232, v240
	v_add_f32_e32 v233, v233, v241
	v_add_f32_e32 v234, v234, v242
	v_add_f32_e32 v235, v235, v243
	v_add_f32_e32 v236, v236, v244
	v_add_f32_e32 v237, v237, v245
	v_add_f32_e32 v238, v238, v246
	v_add_f32_e32 v239, v239, v247
	ds_bpermute_b32 v240, v249, v232
	ds_bpermute_b32 v241, v249, v233
	ds_bpermute_b32 v242, v249, v234
	ds_bpermute_b32 v243, v249, v235
	ds_bpermute_b32 v244, v249, v236
	ds_bpermute_b32 v245, v249, v237
	ds_bpermute_b32 v246, v249, v238
	ds_bpermute_b32 v247, v249, v239
	v_lshl_add_u32 v224, s40, 8, v129
	v_ashrrev_i32_e32 v225, 31, v224
	v_lshl_add_u64 v[224:225], v[224:225], 2, s[22:23]
	s_waitcnt lgkmcnt(0)
	v_add_f32_e32 v232, v232, v240
	v_add_f32_e32 v233, v233, v241
	v_add_f32_e32 v234, v234, v242
	v_add_f32_e32 v235, v235, v243
	v_add_f32_e32 v236, v236, v244
	v_add_f32_e32 v237, v237, v245
	v_add_f32_e32 v238, v238, v246
	v_add_f32_e32 v239, v239, v247
	s_and_saveexec_b64 s[40:41], s[4:5]
	global_atomic_add_f32 v[224:225], v232, off
	global_atomic_add_f32 v[224:225], v233, off offset:64
	global_atomic_add_f32 v[224:225], v234, off offset:128
	global_atomic_add_f32 v[224:225], v235, off offset:192
	global_atomic_add_f32 v[224:225], v236, off offset:512
	global_atomic_add_f32 v[224:225], v237, off offset:576
	global_atomic_add_f32 v[224:225], v238, off offset:640
	global_atomic_add_f32 v[224:225], v239, off offset:704
	s_or_b64 exec, exec, s[40:41]

; __device__ __forceinline__ unsigned cvt_pk_bf16(float lo, float hi) { f32x2_t v = {lo, hi}; bf16x2_t b = __builtin_convertvector(v, bf16x2_t); return __builtin_bit_cast(unsigned, b); }
;     __device__ __forceinline__ void operator()(const f32x4 (&acc)[2][2][4][2], const Unit& u, int wr, int wc, int fr, int fq) const {
;         const int col0 = u.pn * BM + wc * 32 + 8 * fq;
;         const __amdgpu_buffer_rsrc_t rsrc = __builtin_amdgcn_make_buffer_rsrc((void*)xb, (short)0, 16384 * 1024 * 2, 0x00020000);
; #pragma unroll
;         for (int ai = 0; ai < 2; ++ai)
; #pragma unroll
;             for (int m = 0; m < 4; ++m) { const int row = u.pm * BM + ai * HALF + wr * 64 + m * 16 + fr; const size_t off = (size_t)row * ldc + col0; float ss = 0.f;
; #pragma unroll
;                 for (int bj = 0; bj < 2; ++bj) { const size_t o2 = off + bj * HALF; f32x4 b0, b1;
;                     if (MODE == 0) { b0 = *(const f32x4*)(basef + o2); b1 = *(const f32x4*)(basef + o2 + 4); }
;                     else { const u32x4 w = *(const u32x4*)(xb + o2);
;                         b0 = (f32x4){__uint_as_float(w.x << 16), __uint_as_float(w.x & 0xffff0000u), __uint_as_float(w.y << 16), __uint_as_float(w.y & 0xffff0000u)};
;                         b1 = (f32x4){__uint_as_float(w.z << 16), __uint_as_float(w.z & 0xffff0000u), __uint_as_float(w.w << 16), __uint_as_float(w.w & 0xffff0000u)}; }
;                     const f32x4 v0 = b0 + acc[ai][bj][m][0], v1 = b1 + acc[ai][bj][m][1];
;                     if (MODE == 2) { *(f32x4*)(outf + o2) = v0; *(f32x4*)(outf + o2 + 4) = v1; }
;                     else { ss += (v0[0] * v0[0] + v0[1] * v0[1]) + (v0[2] * v0[2] + v0[3] * v0[3]) + (v1[0] * v1[0] + v1[1] * v1[1]) + (v1[2] * v1[2] + v1[3] * v1[3]);
;                         u32x4 w; w.x = cvt_pk_bf16(v0[0], v0[1]); w.y = cvt_pk_bf16(v0[2], v0[3]); w.z = cvt_pk_bf16(v1[0], v1[1]); w.w = cvt_pk_bf16(v1[2], v1[3]);
;                         __builtin_amdgcn_raw_buffer_store_b128(w, rsrc, (unsigned)(o2 * 2), 0, 16); } }
;                 if (MODE != 2) { ss += __shfl_xor(ss, 16); ss += __shfl_xor(ss, 32); if (fq == 0) atomicAdd(rowsq + row, ss); } }
.LBB0_801:
	v_readlane_b32 vcc_lo, v255, 59
	s_mov_b32 vcc_hi, 0
	s_nop 1
	s_mov_b64 vcc, vcc
	s_nop 1
	s_cbranch_vccnz .Lpp9_plain
	v_lshl_add_u32 v156, s40, 8, v129
	v_lshl_or_b32 v157, s42, 8, v151
	v_lshl_add_u32 v156, v156, 10, v157
	v_lshlrev_b32_e32 v156, 1, v156
	v_add_u32_e32 v157, 0x8000, v156
	v_add_u32_e32 v158, 0x10000, v156
	v_add_u32_e32 v159, 0x18000, v156
	v_add_u32_e32 v146, 0x40000, v156
	v_add_u32_e32 v147, 0x48000, v156
	v_add_u32_e32 v148, 0x50000, v156
	v_add_u32_e32 v149, 0x58000, v156
	global_load_dwordx4 v[160:163], v156, s[96:97]
	global_load_dwordx4 v[164:167], v156, s[96:97] offset:256
	global_load_dwordx4 v[168:171], v157, s[96:97]
	global_load_dwordx4 v[172:175], v157, s[96:97] offset:256
	global_load_dwordx4 v[176:179], v158, s[96:97]
	global_load_dwordx4 v[180:183], v158, s[96:97] offset:256
	global_load_dwordx4 v[184:187], v159, s[96:97]
	global_load_dwordx4 v[188:191], v159, s[96:97] offset:256
	global_load_dwordx4 v[192:195], v146, s[96:97]
	global_load_dwordx4 v[196:199], v146, s[96:97] offset:256
	global_load_dwordx4 v[200:203], v147, s[96:97]
	global_load_dwordx4 v[204:207], v147, s[96:97] offset:256
	global_load_dwordx4 v[208:211], v148, s[96:97]
	global_load_dwordx4 v[212:215], v148, s[96:97] offset:256
	global_load_dwordx4 v[216:219], v149, s[96:97]
	global_load_dwordx4 v[220:223], v149, s[96:97] offset:256
	v_xor_b32_e32 v248, 16, v155
	v_xor_b32_e32 v249, 32, v155
	v_lshlrev_b32_e32 v248, 2, v248
	v_lshlrev_b32_e32 v249, 2, v249
	s_waitcnt vmcnt(14)
	v_lshlrev_b32_e32 v224, 16, v160
	v_and_b32_e32 v225, 0xffff0000, v160
	v_lshlrev_b32_e32 v226, 16, v161
	v_and_b32_e32 v227, 0xffff0000, v161
	v_lshlrev_b32_e32 v228, 16, v162
	v_and_b32_e32 v229, 0xffff0000, v162
	v_lshlrev_b32_e32 v230, 16, v163
	v_and_b32_e32 v231, 0xffff0000, v163
	v_pk_add_f32 v[124:125], v[124:125], v[224:225]
	v_pk_add_f32 v[126:127], v[126:127], v[226:227]
	v_pk_add_f32 v[120:121], v[120:121], v[228:229]
	v_pk_add_f32 v[122:123], v[122:123], v[230:231]
	v_mul_f32_e32 v232, v124, v124
	v_fmac_f32_e32 v232, v125, v125
	v_fmac_f32_e32 v232, v126, v126
	v_fmac_f32_e32 v232, v127, v127
	v_fmac_f32_e32 v232, v120, v120
	v_fmac_f32_e32 v232, v121, v121
	v_fmac_f32_e32 v232, v122, v122
	v_fmac_f32_e32 v232, v123, v123
	v_cvt_pk_bf16_f32 v124, v124, v125
	v_cvt_pk_bf16_f32 v125, v126, v127
	v_cvt_pk_bf16_f32 v126, v120, v121
	v_cvt_pk_bf16_f32 v127, v122, v123
	buffer_store_dwordx4 v[124:127], v156, s[12:15], 0 offen sc1
	v_lshlrev_b32_e32 v224, 16, v164
	v_and_b32_e32 v225, 0xffff0000, v164
	v_lshlrev_b32_e32 v226, 16, v165
	v_and_b32_e32 v227, 0xffff0000, v165
	v_lshlrev_b32_e32 v228, 16, v166
	v_and_b32_e32 v229, 0xffff0000, v166
	v_lshlrev_b32_e32 v230, 16, v167
	v_and_b32_e32 v231, 0xffff0000, v167
	v_pk_add_f32 v[116:117], v[116:117], v[224:225]
	v_pk_add_f32 v[118:119], v[118:119], v[226:227]
	v_pk_add_f32 v[112:113], v[112:113], v[228:229]
	v_pk_add_f32 v[114:115], v[114:115], v[230:231]
	v_fmac_f32_e32 v232, v116, v116
	v_fmac_f32_e32 v232, v117, v117
	v_fmac_f32_e32 v232, v118, v118
	v_fmac_f32_e32 v232, v119, v119
	v_fmac_f32_e32 v232, v112, v112
	v_fmac_f32_e32 v232, v113, v113
	v_fmac_f32_e32 v232, v114, v114
	v_fmac_f32_e32 v232, v115, v115
	v_cvt_pk_bf16_f32 v116, v116, v117
	v_cvt_pk_bf16_f32 v117, v118, v119
	v_cvt_pk_bf16_f32 v118, v112, v113
	v_cvt_pk_bf16_f32 v119, v114, v115
	buffer_store_dwordx4 v[116:119], v156, s[12:15], 0 offen offset:256 sc1
	s_waitcnt vmcnt(14)
	v_lshlrev_b32_e32 v224, 16, v168
	v_and_b32_e32 v225, 0xffff0000, v168
	v_lshlrev_b32_e32 v226, 16, v169
	v_and_b32_e32 v227, 0xffff0000, v169
	v_lshlrev_b32_e32 v228, 16, v170
	v_and_b32_e32 v229, 0xffff0000, v170
	v_lshlrev_b32_e32 v230, 16, v171
	v_and_b32_e32 v231, 0xffff0000, v171
	v_pk_add_f32 v[108:109], v[108:109], v[224:225]
	v_pk_add_f32 v[110:111], v[110:111], v[226:227]
	v_pk_add_f32 v[104:105], v[104:105], v[228:229]
	v_pk_add_f32 v[106:107], v[106:107], v[230:231]
	v_mul_f32_e32 v233, v108, v108
	v_fmac_f32_e32 v233, v109, v109
	v_fmac_f32_e32 v233, v110, v110
	v_fmac_f32_e32 v233, v111, v111
	v_fmac_f32_e32 v233, v104, v104
	v_fmac_f32_e32 v233, v105, v105
	v_fmac_f32_e32 v233, v106, v106
	v_fmac_f32_e32 v233, v107, v107
	v_cvt_pk_bf16_f32 v108, v108, v109
	v_cvt_pk_bf16_f32 v109, v110, v111
	v_cvt_pk_bf16_f32 v110, v104, v105
	v_cvt_pk_bf16_f32 v111, v106, v107
	buffer_store_dwordx4 v[108:111], v157, s[12:15], 0 offen sc1
	v_lshlrev_b32_e32 v224, 16, v172
	v_and_b32_e32 v225, 0xffff0000, v172
	v_lshlrev_b32_e32 v226, 16, v173
	v_and_b32_e32 v227, 0xffff0000, v173
	v_lshlrev_b32_e32 v228, 16, v174
	v_and_b32_e32 v229, 0xffff0000, v174
	v_lshlrev_b32_e32 v230, 16, v175
	v_and_b32_e32 v231, 0xffff0000, v175
	v_pk_add_f32 v[100:101], v[100:101], v[224:225]
	v_pk_add_f32 v[102:103], v[102:103], v[226:227]
	v_pk_add_f32 v[96:97], v[96:97], v[228:229]
	v_pk_add_f32 v[98:99], v[98:99], v[230:231]
	v_fmac_f32_e32 v233, v100, v100
	v_fmac_f32_e32 v233, v101, v101
	v_fmac_f32_e32 v233, v102, v102
	v_fmac_f32_e32 v233, v103, v103
	v_fmac_f32_e32 v233, v96, v96
	v_fmac_f32_e32 v233, v97, v97
	v_fmac_f32_e32 v233, v98, v98
	v_fmac_f32_e32 v233, v99, v99
	v_cvt_pk_bf16_f32 v100, v100, v101
	v_cvt_pk_bf16_f32 v101, v102, v103
	v_cvt_pk_bf16_f32 v102, v96, v97
	v_cvt_pk_bf16_f32 v103, v98, v99
	buffer_store_dwordx4 v[100:103], v157, s[12:15], 0 offen offset:256 sc1
	s_waitcnt vmcnt(14)
; __device__ __forceinline__ unsigned cvt_pk_bf16(float lo, float hi) { f32x2_t v = {lo, hi}; bf16x2_t b = __builtin_convertvector(v, bf16x2_t); return __builtin_bit_cast(unsigned, b); }
;     __device__ __forceinline__ void operator()(const f32x4 (&acc)[2][2][4][2], const Unit& u, int wr, int wc, int fr, int fq) const {
;     ...
;             for (int m = 0; m < 4; ++m) { const int row = u.pm * BM + ai * HALF + wr * 64 + m * 16 + fr; const size_t off = (size_t)row * ldc + col0; float ss = 0.f;
; #pragma unroll
;                 for (int bj = 0; bj < 2; ++bj) { const size_t o2 = off + bj * HALF; f32x4 b0, b1;
;                     if (MODE == 0) { b0 = *(const f32x4*)(basef + o2); b1 = *(const f32x4*)(basef + o2 + 4); }
;                     else { const u32x4 w = *(const u32x4*)(xb + o2);
;                         b0 = (f32x4){__uint_as_float(w.x << 16), __uint_as_float(w.x & 0xffff0000u), __uint_as_float(w.y << 16), __uint_as_float(w.y & 0xffff0000u)};
;                         b1 = (f32x4){__uint_as_float(w.z << 16), __uint_as_float(w.z & 0xffff0000u), __uint_as_float(w.w << 16), __uint_as_float(w.w & 0xffff0000u)}; }
;                     const f32x4 v0 = b0 + acc[ai][bj][m][0], v1 = b1 + acc[ai][bj][m][1];
;                     if (MODE == 2) { *(f32x4*)(outf + o2) = v0; *(f32x4*)(outf + o2 + 4) = v1; }
;                     else { ss += (v0[0] * v0[0] + v0[1] * v0[1]) + (v0[2] * v0[2] + v0[3] * v0[3]) + (v1[0] * v1[0] + v1[1] * v1[1]) + (v1[2] * v1[2] + v1[3] * v1[3]);
;                         u32x4 w; w.x = cvt_pk_bf16(v0[0], v0[1]); w.y = cvt_pk_bf16(v0[2], v0[3]); w.z = cvt_pk_bf16(v1[0], v1[1]); w.w = cvt_pk_bf16(v1[2], v1[3]);
;                         __builtin_amdgcn_raw_buffer_store_b128(w, rsrc, (unsigned)(o2 * 2), 0, 16); } }
;                 if (MODE != 2) { ss += __shfl_xor(ss, 16); ss += __shfl_xor(ss, 32); if (fq == 0) atomicAdd(rowsq + row, ss); } }
	v_lshlrev_b32_e32 v224, 16, v176
	v_and_b32_e32 v225, 0xffff0000, v176
	v_lshlrev_b32_e32 v226, 16, v177
	v_and_b32_e32 v227, 0xffff0000, v177
	v_lshlrev_b32_e32 v228, 16, v178
	v_and_b32_e32 v229, 0xffff0000, v178
	v_lshlrev_b32_e32 v230, 16, v179
	v_and_b32_e32 v231, 0xffff0000, v179
	v_pk_add_f32 v[92:93], v[92:93], v[224:225]
	v_pk_add_f32 v[94:95], v[94:95], v[226:227]
	v_pk_add_f32 v[88:89], v[88:89], v[228:229]
	v_pk_add_f32 v[90:91], v[90:91], v[230:231]
	v_mul_f32_e32 v234, v92, v92
	v_fmac_f32_e32 v234, v93, v93
	v_fmac_f32_e32 v234, v94, v94
	v_fmac_f32_e32 v234, v95, v95
	v_fmac_f32_e32 v234, v88, v88
	v_fmac_f32_e32 v234, v89, v89
	v_fmac_f32_e32 v234, v90, v90
	v_fmac_f32_e32 v234, v91, v91
	v_cvt_pk_bf16_f32 v92, v92, v93
	v_cvt_pk_bf16_f32 v93, v94, v95
	v_cvt_pk_bf16_f32 v94, v88, v89
	v_cvt_pk_bf16_f32 v95, v90, v91
	buffer_store_dwordx4 v[92:95], v158, s[12:15], 0 offen sc1
	v_lshlrev_b32_e32 v224, 16, v180
	v_and_b32_e32 v225, 0xffff0000, v180
	v_lshlrev_b32_e32 v226, 16, v181
	v_and_b32_e32 v227, 0xffff0000, v181
	v_lshlrev_b32_e32 v228, 16, v182
	v_and_b32_e32 v229, 0xffff0000, v182
	v_lshlrev_b32_e32 v230, 16, v183
	v_and_b32_e32 v231, 0xffff0000, v183
	v_pk_add_f32 v[84:85], v[84:85], v[224:225]
	v_pk_add_f32 v[86:87], v[86:87], v[226:227]
	v_pk_add_f32 v[80:81], v[80:81], v[228:229]
	v_pk_add_f32 v[82:83], v[82:83], v[230:231]
	v_fmac_f32_e32 v234, v84, v84
	v_fmac_f32_e32 v234, v85, v85
	v_fmac_f32_e32 v234, v86, v86
	v_fmac_f32_e32 v234, v87, v87
	v_fmac_f32_e32 v234, v80, v80
	v_fmac_f32_e32 v234, v81, v81
	v_fmac_f32_e32 v234, v82, v82
	v_fmac_f32_e32 v234, v83, v83
	v_cvt_pk_bf16_f32 v84, v84, v85
	v_cvt_pk_bf16_f32 v85, v86, v87
	v_cvt_pk_bf16_f32 v86, v80, v81
	v_cvt_pk_bf16_f32 v87, v82, v83
	buffer_store_dwordx4 v[84:87], v158, s[12:15], 0 offen offset:256 sc1
	s_waitcnt vmcnt(14)
	v_lshlrev_b32_e32 v224, 16, v184
	v_and_b32_e32 v225, 0xffff0000, v184
	v_lshlrev_b32_e32 v226, 16, v185
	v_and_b32_e32 v227, 0xffff0000, v185
	v_lshlrev_b32_e32 v228, 16, v186
	v_and_b32_e32 v229, 0xffff0000, v186
	v_lshlrev_b32_e32 v230, 16, v187
	v_and_b32_e32 v231, 0xffff0000, v187
	v_pk_add_f32 v[76:77], v[76:77], v[224:225]
	v_pk_add_f32 v[78:79], v[78:79], v[226:227]
	v_pk_add_f32 v[72:73], v[72:73], v[228:229]
	v_pk_add_f32 v[74:75], v[74:75], v[230:231]
	v_mul_f32_e32 v235, v76, v76
	v_fmac_f32_e32 v235, v77, v77
	v_fmac_f32_e32 v235, v78, v78
	v_fmac_f32_e32 v235, v79, v79
	v_fmac_f32_e32 v235, v72, v72
	v_fmac_f32_e32 v235, v73, v73
	v_fmac_f32_e32 v235, v74, v74
	v_fmac_f32_e32 v235, v75, v75
	v_cvt_pk_bf16_f32 v76, v76, v77
	v_cvt_pk_bf16_f32 v77, v78, v79
	v_cvt_pk_bf16_f32 v78, v72, v73
	v_cvt_pk_bf16_f32 v79, v74, v75
	buffer_store_dwordx4 v[76:79], v159, s[12:15], 0 offen sc1
	v_lshlrev_b32_e32 v224, 16, v188
	v_and_b32_e32 v225, 0xffff0000, v188
	v_lshlrev_b32_e32 v226, 16, v189
	v_and_b32_e32 v227, 0xffff0000, v189
	v_lshlrev_b32_e32 v228, 16, v190
	v_and_b32_e32 v229, 0xffff0000, v190
	v_lshlrev_b32_e32 v230, 16, v191
	v_and_b32_e32 v231, 0xffff0000, v191
	v_pk_add_f32 v[68:69], v[68:69], v[224:225]
	v_pk_add_f32 v[70:71], v[70:71], v[226:227]
	v_pk_add_f32 v[64:65], v[64:65], v[228:229]
	v_pk_add_f32 v[66:67], v[66:67], v[230:231]
	v_fmac_f32_e32 v235, v68, v68
	v_fmac_f32_e32 v235, v69, v69
	v_fmac_f32_e32 v235, v70, v70
	v_fmac_f32_e32 v235, v71, v71
	v_fmac_f32_e32 v235, v64, v64
	v_fmac_f32_e32 v235, v65, v65
	v_fmac_f32_e32 v235, v66, v66
	v_fmac_f32_e32 v235, v67, v67
	v_cvt_pk_bf16_f32 v68, v68, v69
	v_cvt_pk_bf16_f32 v69, v70, v71
	v_cvt_pk_bf16_f32 v70, v64, v65
	v_cvt_pk_bf16_f32 v71, v66, v67
	buffer_store_dwordx4 v[68:71], v159, s[12:15], 0 offen offset:256 sc1
	s_waitcnt vmcnt(14)
	v_lshlrev_b32_e32 v224, 16, v192
	v_and_b32_e32 v225, 0xffff0000, v192
	v_lshlrev_b32_e32 v226, 16, v193
	v_and_b32_e32 v227, 0xffff0000, v193
	v_lshlrev_b32_e32 v228, 16, v194
	v_and_b32_e32 v229, 0xffff0000, v194
	v_lshlrev_b32_e32 v230, 16, v195
	v_and_b32_e32 v231, 0xffff0000, v195
	v_pk_add_f32 v[60:61], v[60:61], v[224:225]
	v_pk_add_f32 v[62:63], v[62:63], v[226:227]
	v_pk_add_f32 v[56:57], v[56:57], v[228:229]
	v_pk_add_f32 v[58:59], v[58:59], v[230:231]
	v_mul_f32_e32 v236, v60, v60
	v_fmac_f32_e32 v236, v61, v61
	v_fmac_f32_e32 v236, v62, v62
	v_fmac_f32_e32 v236, v63, v63
	v_fmac_f32_e32 v236, v56, v56
	v_fmac_f32_e32 v236, v57, v57
	v_fmac_f32_e32 v236, v58, v58
	v_fmac_f32_e32 v236, v59, v59
	v_cvt_pk_bf16_f32 v60, v60, v61
	v_cvt_pk_bf16_f32 v61, v62, v63
	v_cvt_pk_bf16_f32 v62, v56, v57
	v_cvt_pk_bf16_f32 v63, v58, v59
	buffer_store_dwordx4 v[60:63], v146, s[12:15], 0 offen sc1
	v_lshlrev_b32_e32 v224, 16, v196
	v_and_b32_e32 v225, 0xffff0000, v196
	v_lshlrev_b32_e32 v226, 16, v197
	v_and_b32_e32 v227, 0xffff0000, v197
	v_lshlrev_b32_e32 v228, 16, v198
	v_and_b32_e32 v229, 0xffff0000, v198
	v_lshlrev_b32_e32 v230, 16, v199
	v_and_b32_e32 v231, 0xffff0000, v199
	v_pk_add_f32 v[52:53], v[52:53], v[224:225]
	v_pk_add_f32 v[54:55], v[54:55], v[226:227]
	v_pk_add_f32 v[48:49], v[48:49], v[228:229]
	v_pk_add_f32 v[50:51], v[50:51], v[230:231]
	v_fmac_f32_e32 v236, v52, v52
	v_fmac_f32_e32 v236, v53, v53
	v_fmac_f32_e32 v236, v54, v54
	v_fmac_f32_e32 v236, v55, v55
	v_fmac_f32_e32 v236, v48, v48
	v_fmac_f32_e32 v236, v49, v49
	v_fmac_f32_e32 v236, v50, v50
	v_fmac_f32_e32 v236, v51, v51
	v_cvt_pk_bf16_f32 v52, v52, v53
	v_cvt_pk_bf16_f32 v53, v54, v55
	v_cvt_pk_bf16_f32 v54, v48, v49
	v_cvt_pk_bf16_f32 v55, v50, v51
	buffer_store_dwordx4 v[52:55], v146, s[12:15], 0 offen offset:256 sc1
	s_waitcnt vmcnt(14)
; __device__ __forceinline__ unsigned cvt_pk_bf16(float lo, float hi) { f32x2_t v = {lo, hi}; bf16x2_t b = __builtin_convertvector(v, bf16x2_t); return __builtin_bit_cast(unsigned, b); }
;     __device__ __forceinline__ void operator()(const f32x4 (&acc)[2][2][4][2], const Unit& u, int wr, int wc, int fr, int fq) const {
;     ...
;             for (int m = 0; m < 4; ++m) { const int row = u.pm * BM + ai * HALF + wr * 64 + m * 16 + fr; const size_t off = (size_t)row * ldc + col0; float ss = 0.f;
; #pragma unroll
;                 for (int bj = 0; bj < 2; ++bj) { const size_t o2 = off + bj * HALF; f32x4 b0, b1;
;                     if (MODE == 0) { b0 = *(const f32x4*)(basef + o2); b1 = *(const f32x4*)(basef + o2 + 4); }
;                     else { const u32x4 w = *(const u32x4*)(xb + o2);
;                         b0 = (f32x4){__uint_as_float(w.x << 16), __uint_as_float(w.x & 0xffff0000u), __uint_as_float(w.y << 16), __uint_as_float(w.y & 0xffff0000u)};
;                         b1 = (f32x4){__uint_as_float(w.z << 16), __uint_as_float(w.z & 0xffff0000u), __uint_as_float(w.w << 16), __uint_as_float(w.w & 0xffff0000u)}; }
;                     const f32x4 v0 = b0 + acc[ai][bj][m][0], v1 = b1 + acc[ai][bj][m][1];
;                     if (MODE == 2) { *(f32x4*)(outf + o2) = v0; *(f32x4*)(outf + o2 + 4) = v1; }
;                     else { ss += (v0[0] * v0[0] + v0[1] * v0[1]) + (v0[2] * v0[2] + v0[3] * v0[3]) + (v1[0] * v1[0] + v1[1] * v1[1]) + (v1[2] * v1[2] + v1[3] * v1[3]);
;                         u32x4 w; w.x = cvt_pk_bf16(v0[0], v0[1]); w.y = cvt_pk_bf16(v0[2], v0[3]); w.z = cvt_pk_bf16(v1[0], v1[1]); w.w = cvt_pk_bf16(v1[2], v1[3]);
;                         __builtin_amdgcn_raw_buffer_store_b128(w, rsrc, (unsigned)(o2 * 2), 0, 16); } }
;                 if (MODE != 2) { ss += __shfl_xor(ss, 16); ss += __shfl_xor(ss, 32); if (fq == 0) atomicAdd(rowsq + row, ss); } }
	v_lshlrev_b32_e32 v224, 16, v200
	v_and_b32_e32 v225, 0xffff0000, v200
	v_lshlrev_b32_e32 v226, 16, v201
	v_and_b32_e32 v227, 0xffff0000, v201
	v_lshlrev_b32_e32 v228, 16, v202
	v_and_b32_e32 v229, 0xffff0000, v202
	v_lshlrev_b32_e32 v230, 16, v203
	v_and_b32_e32 v231, 0xffff0000, v203
	v_pk_add_f32 v[44:45], v[44:45], v[224:225]
	v_pk_add_f32 v[46:47], v[46:47], v[226:227]
	v_pk_add_f32 v[40:41], v[40:41], v[228:229]
	v_pk_add_f32 v[42:43], v[42:43], v[230:231]
	v_mul_f32_e32 v237, v44, v44
	v_fmac_f32_e32 v237, v45, v45
	v_fmac_f32_e32 v237, v46, v46
	v_fmac_f32_e32 v237, v47, v47
	v_fmac_f32_e32 v237, v40, v40
	v_fmac_f32_e32 v237, v41, v41
	v_fmac_f32_e32 v237, v42, v42
	v_fmac_f32_e32 v237, v43, v43
	v_cvt_pk_bf16_f32 v44, v44, v45
	v_cvt_pk_bf16_f32 v45, v46, v47
	v_cvt_pk_bf16_f32 v46, v40, v41
	v_cvt_pk_bf16_f32 v47, v42, v43
	buffer_store_dwordx4 v[44:47], v147, s[12:15], 0 offen sc1
	v_lshlrev_b32_e32 v224, 16, v204
	v_and_b32_e32 v225, 0xffff0000, v204
	v_lshlrev_b32_e32 v226, 16, v205
	v_and_b32_e32 v227, 0xffff0000, v205
	v_lshlrev_b32_e32 v228, 16, v206
	v_and_b32_e32 v229, 0xffff0000, v206
	v_lshlrev_b32_e32 v230, 16, v207
	v_and_b32_e32 v231, 0xffff0000, v207
	v_pk_add_f32 v[36:37], v[36:37], v[224:225]
	v_pk_add_f32 v[38:39], v[38:39], v[226:227]
	v_pk_add_f32 v[32:33], v[32:33], v[228:229]
	v_pk_add_f32 v[34:35], v[34:35], v[230:231]
	v_fmac_f32_e32 v237, v36, v36
	v_fmac_f32_e32 v237, v37, v37
	v_fmac_f32_e32 v237, v38, v38
	v_fmac_f32_e32 v237, v39, v39
	v_fmac_f32_e32 v237, v32, v32
	v_fmac_f32_e32 v237, v33, v33
	v_fmac_f32_e32 v237, v34, v34
	v_fmac_f32_e32 v237, v35, v35
	v_cvt_pk_bf16_f32 v36, v36, v37
	v_cvt_pk_bf16_f32 v37, v38, v39
	v_cvt_pk_bf16_f32 v38, v32, v33
	v_cvt_pk_bf16_f32 v39, v34, v35
	buffer_store_dwordx4 v[36:39], v147, s[12:15], 0 offen offset:256 sc1
	s_waitcnt vmcnt(14)
	v_lshlrev_b32_e32 v224, 16, v208
	v_and_b32_e32 v225, 0xffff0000, v208
	v_lshlrev_b32_e32 v226, 16, v209
	v_and_b32_e32 v227, 0xffff0000, v209
	v_lshlrev_b32_e32 v228, 16, v210
	v_and_b32_e32 v229, 0xffff0000, v210
	v_lshlrev_b32_e32 v230, 16, v211
	v_and_b32_e32 v231, 0xffff0000, v211
	v_pk_add_f32 v[28:29], v[28:29], v[224:225]
	v_pk_add_f32 v[30:31], v[30:31], v[226:227]
	v_pk_add_f32 v[24:25], v[24:25], v[228:229]
	v_pk_add_f32 v[26:27], v[26:27], v[230:231]
	v_mul_f32_e32 v238, v28, v28
	v_fmac_f32_e32 v238, v29, v29
	v_fmac_f32_e32 v238, v30, v30
	v_fmac_f32_e32 v238, v31, v31
	v_fmac_f32_e32 v238, v24, v24
	v_fmac_f32_e32 v238, v25, v25
	v_fmac_f32_e32 v238, v26, v26
	v_fmac_f32_e32 v238, v27, v27
	v_cvt_pk_bf16_f32 v28, v28, v29
	v_cvt_pk_bf16_f32 v29, v30, v31
	v_cvt_pk_bf16_f32 v30, v24, v25
	v_cvt_pk_bf16_f32 v31, v26, v27
	buffer_store_dwordx4 v[28:31], v148, s[12:15], 0 offen sc1
	v_lshlrev_b32_e32 v224, 16, v212
	v_and_b32_e32 v225, 0xffff0000, v212
	v_lshlrev_b32_e32 v226, 16, v213
	v_and_b32_e32 v227, 0xffff0000, v213
	v_lshlrev_b32_e32 v228, 16, v214
	v_and_b32_e32 v229, 0xffff0000, v214
	v_lshlrev_b32_e32 v230, 16, v215
	v_and_b32_e32 v231, 0xffff0000, v215
	v_pk_add_f32 v[20:21], v[20:21], v[224:225]
	v_pk_add_f32 v[22:23], v[22:23], v[226:227]
	v_pk_add_f32 v[16:17], v[16:17], v[228:229]
	v_pk_add_f32 v[18:19], v[18:19], v[230:231]
	v_fmac_f32_e32 v238, v20, v20
	v_fmac_f32_e32 v238, v21, v21
	v_fmac_f32_e32 v238, v22, v22
	v_fmac_f32_e32 v238, v23, v23
	v_fmac_f32_e32 v238, v16, v16
	v_fmac_f32_e32 v238, v17, v17
	v_fmac_f32_e32 v238, v18, v18
	v_fmac_f32_e32 v238, v19, v19
	v_cvt_pk_bf16_f32 v20, v20, v21
	v_cvt_pk_bf16_f32 v21, v22, v23
	v_cvt_pk_bf16_f32 v22, v16, v17
	v_cvt_pk_bf16_f32 v23, v18, v19
	buffer_store_dwordx4 v[20:23], v148, s[12:15], 0 offen offset:256 sc1
	s_waitcnt vmcnt(14)
	v_lshlrev_b32_e32 v224, 16, v216
	v_and_b32_e32 v225, 0xffff0000, v216
	v_lshlrev_b32_e32 v226, 16, v217
	v_and_b32_e32 v227, 0xffff0000, v217
	v_lshlrev_b32_e32 v228, 16, v218
	v_and_b32_e32 v229, 0xffff0000, v218
	v_lshlrev_b32_e32 v230, 16, v219
	v_and_b32_e32 v231, 0xffff0000, v219
	v_pk_add_f32 v[12:13], v[12:13], v[224:225]
	v_pk_add_f32 v[14:15], v[14:15], v[226:227]
	v_pk_add_f32 v[8:9], v[8:9], v[228:229]
	v_pk_add_f32 v[10:11], v[10:11], v[230:231]
	v_mul_f32_e32 v239, v12, v12
	v_fmac_f32_e32 v239, v13, v13
	v_fmac_f32_e32 v239, v14, v14
	v_fmac_f32_e32 v239, v15, v15
	v_fmac_f32_e32 v239, v8, v8
	v_fmac_f32_e32 v239, v9, v9
	v_fmac_f32_e32 v239, v10, v10
	v_fmac_f32_e32 v239, v11, v11
	v_cvt_pk_bf16_f32 v12, v12, v13
	v_cvt_pk_bf16_f32 v13, v14, v15
	v_cvt_pk_bf16_f32 v14, v8, v9
	v_cvt_pk_bf16_f32 v15, v10, v11
	buffer_store_dwordx4 v[12:15], v149, s[12:15], 0 offen sc1
	v_lshlrev_b32_e32 v224, 16, v220
	v_and_b32_e32 v225, 0xffff0000, v220
	v_lshlrev_b32_e32 v226, 16, v221
	v_and_b32_e32 v227, 0xffff0000, v221
	v_lshlrev_b32_e32 v228, 16, v222
	v_and_b32_e32 v229, 0xffff0000, v222
	v_lshlrev_b32_e32 v230, 16, v223
	v_and_b32_e32 v231, 0xffff0000, v223
	v_pk_add_f32 v[4:5], v[4:5], v[224:225]
	v_pk_add_f32 v[6:7], v[6:7], v[226:227]
	v_pk_add_f32 v[0:1], v[0:1], v[228:229]
	v_pk_add_f32 v[2:3], v[2:3], v[230:231]
	v_fmac_f32_e32 v239, v4, v4
	v_fmac_f32_e32 v239, v5, v5
	v_fmac_f32_e32 v239, v6, v6
	v_fmac_f32_e32 v239, v7, v7
	v_fmac_f32_e32 v239, v0, v0
	v_fmac_f32_e32 v239, v1, v1
	v_fmac_f32_e32 v239, v2, v2
	v_fmac_f32_e32 v239, v3, v3
	v_cvt_pk_bf16_f32 v4, v4, v5
	v_cvt_pk_bf16_f32 v5, v6, v7
	v_cvt_pk_bf16_f32 v6, v0, v1
	v_cvt_pk_bf16_f32 v7, v2, v3
	buffer_store_dwordx4 v[4:7], v149, s[12:15], 0 offen offset:256 sc1
	ds_bpermute_b32 v240, v248, v232
	ds_bpermute_b32 v241, v248, v233
	ds_bpermute_b32 v242, v248, v234
	ds_bpermute_b32 v243, v248, v235
	ds_bpermute_b32 v244, v248, v236
	ds_bpermute_b32 v245, v248, v237
	ds_bpermute_b32 v246, v248, v238
	ds_bpermute_b32 v247, v248, v239
	s_waitcnt lgkmcnt(0)
; __device__ __forceinline__ unsigned cvt_pk_bf16(float lo, float hi) { f32x2_t v = {lo, hi}; bf16x2_t b = __builtin_convertvector(v, bf16x2_t); return __builtin_bit_cast(unsigned, b); }
;     __device__ __forceinline__ void operator()(const f32x4 (&acc)[2][2][4][2], const Unit& u, int wr, int wc, int fr, int fq) const {
;     ...
;             for (int m = 0; m < 4; ++m) { const int row = u.pm * BM + ai * HALF + wr * 64 + m * 16 + fr; const size_t off = (size_t)row * ldc + col0; float ss = 0.f;
; #pragma unroll
;                 for (int bj = 0; bj < 2; ++bj) { const size_t o2 = off + bj * HALF; f32x4 b0, b1;
;                     if (MODE == 0) { b0 = *(const f32x4*)(basef + o2); b1 = *(const f32x4*)(basef + o2 + 4); }
;                     else { const u32x4 w = *(const u32x4*)(xb + o2);
;                         b0 = (f32x4){__uint_as_float(w.x << 16), __uint_as_float(w.x & 0xffff0000u), __uint_as_float(w.y << 16), __uint_as_float(w.y & 0xffff0000u)};
;                         b1 = (f32x4){__uint_as_float(w.z << 16), __uint_as_float(w.z & 0xffff0000u), __uint_as_float(w.w << 16), __uint_as_float(w.w & 0xffff0000u)}; }
;                     const f32x4 v0 = b0 + acc[ai][bj][m][0], v1 = b1 + acc[ai][bj][m][1];
;                     if (MODE == 2) { *(f32x4*)(outf + o2) = v0; *(f32x4*)(outf + o2 + 4) = v1; }
;                     else { ss += (v0[0] * v0[0] + v0[1] * v0[1]) + (v0[2] * v0[2] + v0[3] * v0[3]) + (v1[0] * v1[0] + v1[1] * v1[1]) + (v1[2] * v1[2] + v1[3] * v1[3]);
;                         u32x4 w; w.x = cvt_pk_bf16(v0[0], v0[1]); w.y = cvt_pk_bf16(v0[2], v0[3]); w.z = cvt_pk_bf16(v1[0], v1[1]); w.w = cvt_pk_bf16(v1[2], v1[3]);
;                         __builtin_amdgcn_raw_buffer_store_b128(w, rsrc, (unsigned)(o2 * 2), 0, 16); } }
;                 if (MODE != 2) { ss += __shfl_xor(ss, 16); ss += __shfl_xor(ss, 32); if (fq == 0) atomicAdd(rowsq + row, ss); } }
	v_add_f32_e32 v232, v232, v240
	v_add_f32_e32 v233, v233, v241
	v_add_f32_e32 v234, v234, v242
	v_add_f32_e32 v235, v235, v243
	v_add_f32_e32 v236, v236, v244
	v_add_f32_e32 v237, v237, v245
	v_add_f32_e32 v238, v238, v246
	v_add_f32_e32 v239, v239, v247
	ds_bpermute_b32 v240, v249, v232
	ds_bpermute_b32 v241, v249, v233
	ds_bpermute_b32 v242, v249, v234
	ds_bpermute_b32 v243, v249, v235
	ds_bpermute_b32 v244, v249, v236
	ds_bpermute_b32 v245, v249, v237
	ds_bpermute_b32 v246, v249, v238
	ds_bpermute_b32 v247, v249, v239
	v_lshl_add_u32 v224, s40, 8, v129
	v_ashrrev_i32_e32 v225, 31, v224
	v_lshl_add_u64 v[224:225], v[224:225], 2, s[10:11]
	s_waitcnt lgkmcnt(0)
	v_add_f32_e32 v232, v232, v240
	v_add_f32_e32 v233, v233, v241
	v_add_f32_e32 v234, v234, v242
	v_add_f32_e32 v235, v235, v243
	v_add_f32_e32 v236, v236, v244
	v_add_f32_e32 v237, v237, v245
	v_add_f32_e32 v238, v238, v246
	v_add_f32_e32 v239, v239, v247
	s_and_saveexec_b64 s[40:41], s[6:7]
	global_atomic_add_f32 v[224:225], v232, off
	global_atomic_add_f32 v[224:225], v233, off offset:64
	global_atomic_add_f32 v[224:225], v234, off offset:128
	global_atomic_add_f32 v[224:225], v235, off offset:192
	global_atomic_add_f32 v[224:225], v236, off offset:512
	global_atomic_add_f32 v[224:225], v237, off offset:576
	global_atomic_add_f32 v[224:225], v238, off offset:640
	global_atomic_add_f32 v[224:225], v239, off offset:704
	s_or_b64 exec, exec, s[40:41]
	s_branch .Lpp9_done
.Lpp9_plain:
	v_lshl_add_u32 v156, s40, 8, v129
	v_lshl_or_b32 v157, s42, 8, v151
	v_lshl_add_u32 v156, v156, 10, v157
	v_lshlrev_b32_e32 v156, 1, v156
	v_add_u32_e32 v157, 0x8000, v156
	v_add_u32_e32 v158, 0x10000, v156
	v_add_u32_e32 v159, 0x18000, v156
	v_add_u32_e32 v146, 0x40000, v156
	v_add_u32_e32 v147, 0x48000, v156
	v_add_u32_e32 v148, 0x50000, v156
	v_add_u32_e32 v149, 0x58000, v156
	global_load_dwordx4 v[160:163], v156, s[96:97]
	global_load_dwordx4 v[164:167], v156, s[96:97] offset:256
	global_load_dwordx4 v[168:171], v157, s[96:97]
	global_load_dwordx4 v[172:175], v157, s[96:97] offset:256
	global_load_dwordx4 v[176:179], v158, s[96:97]
	global_load_dwordx4 v[180:183], v158, s[96:97] offset:256
	global_load_dwordx4 v[184:187], v159, s[96:97]
	global_load_dwordx4 v[188:191], v159, s[96:97] offset:256
	global_load_dwordx4 v[192:195], v146, s[96:97]
	global_load_dwordx4 v[196:199], v146, s[96:97] offset:256
	global_load_dwordx4 v[200:203], v147, s[96:97]
	global_load_dwordx4 v[204:207], v147, s[96:97] offset:256
	global_load_dwordx4 v[208:211], v148, s[96:97]
	global_load_dwordx4 v[212:215], v148, s[96:97] offset:256
	global_load_dwordx4 v[216:219], v149, s[96:97]
	global_load_dwordx4 v[220:223], v149, s[96:97] offset:256
	v_xor_b32_e32 v248, 16, v155
	v_xor_b32_e32 v249, 32, v155
	v_lshlrev_b32_e32 v248, 2, v248
	v_lshlrev_b32_e32 v249, 2, v249
	s_waitcnt vmcnt(14)
	v_lshlrev_b32_e32 v224, 16, v160
	v_and_b32_e32 v225, 0xffff0000, v160
	v_lshlrev_b32_e32 v226, 16, v161
	v_and_b32_e32 v227, 0xffff0000, v161
	v_lshlrev_b32_e32 v228, 16, v162
	v_and_b32_e32 v229, 0xffff0000, v162
	v_lshlrev_b32_e32 v230, 16, v163
	v_and_b32_e32 v231, 0xffff0000, v163
	v_pk_add_f32 v[124:125], v[124:125], v[224:225]
	v_pk_add_f32 v[126:127], v[126:127], v[226:227]
	v_pk_add_f32 v[120:121], v[120:121], v[228:229]
	v_pk_add_f32 v[122:123], v[122:123], v[230:231]
	v_mul_f32_e32 v232, v124, v124
	v_fmac_f32_e32 v232, v125, v125
	v_fmac_f32_e32 v232, v126, v126
	v_fmac_f32_e32 v232, v127, v127
	v_fmac_f32_e32 v232, v120, v120
	v_fmac_f32_e32 v232, v121, v121
	v_fmac_f32_e32 v232, v122, v122
	v_fmac_f32_e32 v232, v123, v123
	v_cvt_pk_bf16_f32 v124, v124, v125
	v_cvt_pk_bf16_f32 v125, v126, v127
	v_cvt_pk_bf16_f32 v126, v120, v121
	v_cvt_pk_bf16_f32 v127, v122, v123
	buffer_store_dwordx4 v[124:127], v156, s[12:15], 0 offen
	v_lshlrev_b32_e32 v224, 16, v164
	v_and_b32_e32 v225, 0xffff0000, v164
	v_lshlrev_b32_e32 v226, 16, v165
	v_and_b32_e32 v227, 0xffff0000, v165
	v_lshlrev_b32_e32 v228, 16, v166
	v_and_b32_e32 v229, 0xffff0000, v166
	v_lshlrev_b32_e32 v230, 16, v167
	v_and_b32_e32 v231, 0xffff0000, v167
	v_pk_add_f32 v[116:117], v[116:117], v[224:225]
	v_pk_add_f32 v[118:119], v[118:119], v[226:227]
	v_pk_add_f32 v[112:113], v[112:113], v[228:229]
	v_pk_add_f32 v[114:115], v[114:115], v[230:231]
	v_fmac_f32_e32 v232, v116, v116
	v_fmac_f32_e32 v232, v117, v117
	v_fmac_f32_e32 v232, v118, v118
	v_fmac_f32_e32 v232, v119, v119
	v_fmac_f32_e32 v232, v112, v112
	v_fmac_f32_e32 v232, v113, v113
	v_fmac_f32_e32 v232, v114, v114
	v_fmac_f32_e32 v232, v115, v115
	v_cvt_pk_bf16_f32 v116, v116, v117
	v_cvt_pk_bf16_f32 v117, v118, v119
	v_cvt_pk_bf16_f32 v118, v112, v113
	v_cvt_pk_bf16_f32 v119, v114, v115
	buffer_store_dwordx4 v[116:119], v156, s[12:15], 0 offen offset:256
	s_waitcnt vmcnt(14)
; __device__ __forceinline__ unsigned cvt_pk_bf16(float lo, float hi) { f32x2_t v = {lo, hi}; bf16x2_t b = __builtin_convertvector(v, bf16x2_t); return __builtin_bit_cast(unsigned, b); }
;     __device__ __forceinline__ void operator()(const f32x4 (&acc)[2][2][4][2], const Unit& u, int wr, int wc, int fr, int fq) const {
;     ...
;             for (int m = 0; m < 4; ++m) { const int row = u.pm * BM + ai * HALF + wr * 64 + m * 16 + fr; const size_t off = (size_t)row * ldc + col0; float ss = 0.f;
; #pragma unroll
;                 for (int bj = 0; bj < 2; ++bj) { const size_t o2 = off + bj * HALF; f32x4 b0, b1;
;                     if (MODE == 0) { b0 = *(const f32x4*)(basef + o2); b1 = *(const f32x4*)(basef + o2 + 4); }
;                     else { const u32x4 w = *(const u32x4*)(xb + o2);
;                         b0 = (f32x4){__uint_as_float(w.x << 16), __uint_as_float(w.x & 0xffff0000u), __uint_as_float(w.y << 16), __uint_as_float(w.y & 0xffff0000u)};
;                         b1 = (f32x4){__uint_as_float(w.z << 16), __uint_as_float(w.z & 0xffff0000u), __uint_as_float(w.w << 16), __uint_as_float(w.w & 0xffff0000u)}; }
;                     const f32x4 v0 = b0 + acc[ai][bj][m][0], v1 = b1 + acc[ai][bj][m][1];
;                     if (MODE == 2) { *(f32x4*)(outf + o2) = v0; *(f32x4*)(outf + o2 + 4) = v1; }
;                     else { ss += (v0[0] * v0[0] + v0[1] * v0[1]) + (v0[2] * v0[2] + v0[3] * v0[3]) + (v1[0] * v1[0] + v1[1] * v1[1]) + (v1[2] * v1[2] + v1[3] * v1[3]);
;                         u32x4 w; w.x = cvt_pk_bf16(v0[0], v0[1]); w.y = cvt_pk_bf16(v0[2], v0[3]); w.z = cvt_pk_bf16(v1[0], v1[1]); w.w = cvt_pk_bf16(v1[2], v1[3]);
;                         __builtin_amdgcn_raw_buffer_store_b128(w, rsrc, (unsigned)(o2 * 2), 0, 16); } }
;                 if (MODE != 2) { ss += __shfl_xor(ss, 16); ss += __shfl_xor(ss, 32); if (fq == 0) atomicAdd(rowsq + row, ss); } }
	v_lshlrev_b32_e32 v224, 16, v168
	v_and_b32_e32 v225, 0xffff0000, v168
	v_lshlrev_b32_e32 v226, 16, v169
	v_and_b32_e32 v227, 0xffff0000, v169
	v_lshlrev_b32_e32 v228, 16, v170
	v_and_b32_e32 v229, 0xffff0000, v170
	v_lshlrev_b32_e32 v230, 16, v171
	v_and_b32_e32 v231, 0xffff0000, v171
	v_pk_add_f32 v[108:109], v[108:109], v[224:225]
	v_pk_add_f32 v[110:111], v[110:111], v[226:227]
	v_pk_add_f32 v[104:105], v[104:105], v[228:229]
	v_pk_add_f32 v[106:107], v[106:107], v[230:231]
	v_mul_f32_e32 v233, v108, v108
	v_fmac_f32_e32 v233, v109, v109
	v_fmac_f32_e32 v233, v110, v110
	v_fmac_f32_e32 v233, v111, v111
	v_fmac_f32_e32 v233, v104, v104
	v_fmac_f32_e32 v233, v105, v105
	v_fmac_f32_e32 v233, v106, v106
	v_fmac_f32_e32 v233, v107, v107
	v_cvt_pk_bf16_f32 v108, v108, v109
	v_cvt_pk_bf16_f32 v109, v110, v111
	v_cvt_pk_bf16_f32 v110, v104, v105
	v_cvt_pk_bf16_f32 v111, v106, v107
	buffer_store_dwordx4 v[108:111], v157, s[12:15], 0 offen
	v_lshlrev_b32_e32 v224, 16, v172
	v_and_b32_e32 v225, 0xffff0000, v172
	v_lshlrev_b32_e32 v226, 16, v173
	v_and_b32_e32 v227, 0xffff0000, v173
	v_lshlrev_b32_e32 v228, 16, v174
	v_and_b32_e32 v229, 0xffff0000, v174
	v_lshlrev_b32_e32 v230, 16, v175
	v_and_b32_e32 v231, 0xffff0000, v175
	v_pk_add_f32 v[100:101], v[100:101], v[224:225]
	v_pk_add_f32 v[102:103], v[102:103], v[226:227]
	v_pk_add_f32 v[96:97], v[96:97], v[228:229]
	v_pk_add_f32 v[98:99], v[98:99], v[230:231]
	v_fmac_f32_e32 v233, v100, v100
	v_fmac_f32_e32 v233, v101, v101
	v_fmac_f32_e32 v233, v102, v102
	v_fmac_f32_e32 v233, v103, v103
	v_fmac_f32_e32 v233, v96, v96
	v_fmac_f32_e32 v233, v97, v97
	v_fmac_f32_e32 v233, v98, v98
	v_fmac_f32_e32 v233, v99, v99
	v_cvt_pk_bf16_f32 v100, v100, v101
	v_cvt_pk_bf16_f32 v101, v102, v103
	v_cvt_pk_bf16_f32 v102, v96, v97
	v_cvt_pk_bf16_f32 v103, v98, v99
	buffer_store_dwordx4 v[100:103], v157, s[12:15], 0 offen offset:256
	s_waitcnt vmcnt(14)
	v_lshlrev_b32_e32 v224, 16, v176
	v_and_b32_e32 v225, 0xffff0000, v176
	v_lshlrev_b32_e32 v226, 16, v177
	v_and_b32_e32 v227, 0xffff0000, v177
	v_lshlrev_b32_e32 v228, 16, v178
	v_and_b32_e32 v229, 0xffff0000, v178
	v_lshlrev_b32_e32 v230, 16, v179
	v_and_b32_e32 v231, 0xffff0000, v179
	v_pk_add_f32 v[92:93], v[92:93], v[224:225]
	v_pk_add_f32 v[94:95], v[94:95], v[226:227]
	v_pk_add_f32 v[88:89], v[88:89], v[228:229]
	v_pk_add_f32 v[90:91], v[90:91], v[230:231]
	v_mul_f32_e32 v234, v92, v92
	v_fmac_f32_e32 v234, v93, v93
	v_fmac_f32_e32 v234, v94, v94
	v_fmac_f32_e32 v234, v95, v95
	v_fmac_f32_e32 v234, v88, v88
	v_fmac_f32_e32 v234, v89, v89
	v_fmac_f32_e32 v234, v90, v90
	v_fmac_f32_e32 v234, v91, v91
	v_cvt_pk_bf16_f32 v92, v92, v93
	v_cvt_pk_bf16_f32 v93, v94, v95
	v_cvt_pk_bf16_f32 v94, v88, v89
	v_cvt_pk_bf16_f32 v95, v90, v91
	buffer_store_dwordx4 v[92:95], v158, s[12:15], 0 offen
	v_lshlrev_b32_e32 v224, 16, v180
	v_and_b32_e32 v225, 0xffff0000, v180
	v_lshlrev_b32_e32 v226, 16, v181
	v_and_b32_e32 v227, 0xffff0000, v181
	v_lshlrev_b32_e32 v228, 16, v182
	v_and_b32_e32 v229, 0xffff0000, v182
	v_lshlrev_b32_e32 v230, 16, v183
	v_and_b32_e32 v231, 0xffff0000, v183
	v_pk_add_f32 v[84:85], v[84:85], v[224:225]
	v_pk_add_f32 v[86:87], v[86:87], v[226:227]
	v_pk_add_f32 v[80:81], v[80:81], v[228:229]
	v_pk_add_f32 v[82:83], v[82:83], v[230:231]
	v_fmac_f32_e32 v234, v84, v84
	v_fmac_f32_e32 v234, v85, v85
	v_fmac_f32_e32 v234, v86, v86
	v_fmac_f32_e32 v234, v87, v87
	v_fmac_f32_e32 v234, v80, v80
	v_fmac_f32_e32 v234, v81, v81
	v_fmac_f32_e32 v234, v82, v82
	v_fmac_f32_e32 v234, v83, v83
	v_cvt_pk_bf16_f32 v84, v84, v85
	v_cvt_pk_bf16_f32 v85, v86, v87
	v_cvt_pk_bf16_f32 v86, v80, v81
	v_cvt_pk_bf16_f32 v87, v82, v83
	buffer_store_dwordx4 v[84:87], v158, s[12:15], 0 offen offset:256
	s_waitcnt vmcnt(14)
	v_lshlrev_b32_e32 v224, 16, v184
	v_and_b32_e32 v225, 0xffff0000, v184
	v_lshlrev_b32_e32 v226, 16, v185
	v_and_b32_e32 v227, 0xffff0000, v185
	v_lshlrev_b32_e32 v228, 16, v186
	v_and_b32_e32 v229, 0xffff0000, v186
	v_lshlrev_b32_e32 v230, 16, v187
	v_and_b32_e32 v231, 0xffff0000, v187
	v_pk_add_f32 v[76:77], v[76:77], v[224:225]
	v_pk_add_f32 v[78:79], v[78:79], v[226:227]
	v_pk_add_f32 v[72:73], v[72:73], v[228:229]
	v_pk_add_f32 v[74:75], v[74:75], v[230:231]
	v_mul_f32_e32 v235, v76, v76
	v_fmac_f32_e32 v235, v77, v77
	v_fmac_f32_e32 v235, v78, v78
	v_fmac_f32_e32 v235, v79, v79
	v_fmac_f32_e32 v235, v72, v72
	v_fmac_f32_e32 v235, v73, v73
	v_fmac_f32_e32 v235, v74, v74
	v_fmac_f32_e32 v235, v75, v75
	v_cvt_pk_bf16_f32 v76, v76, v77
	v_cvt_pk_bf16_f32 v77, v78, v79
	v_cvt_pk_bf16_f32 v78, v72, v73
	v_cvt_pk_bf16_f32 v79, v74, v75
	buffer_store_dwordx4 v[76:79], v159, s[12:15], 0 offen
	v_lshlrev_b32_e32 v224, 16, v188
	v_and_b32_e32 v225, 0xffff0000, v188
	v_lshlrev_b32_e32 v226, 16, v189
	v_and_b32_e32 v227, 0xffff0000, v189
	v_lshlrev_b32_e32 v228, 16, v190
	v_and_b32_e32 v229, 0xffff0000, v190
	v_lshlrev_b32_e32 v230, 16, v191
	v_and_b32_e32 v231, 0xffff0000, v191
	v_pk_add_f32 v[68:69], v[68:69], v[224:225]
	v_pk_add_f32 v[70:71], v[70:71], v[226:227]
	v_pk_add_f32 v[64:65], v[64:65], v[228:229]
	v_pk_add_f32 v[66:67], v[66:67], v[230:231]
	v_fmac_f32_e32 v235, v68, v68
	v_fmac_f32_e32 v235, v69, v69
	v_fmac_f32_e32 v235, v70, v70
	v_fmac_f32_e32 v235, v71, v71
	v_fmac_f32_e32 v235, v64, v64
	v_fmac_f32_e32 v235, v65, v65
	v_fmac_f32_e32 v235, v66, v66
	v_fmac_f32_e32 v235, v67, v67
	v_cvt_pk_bf16_f32 v68, v68, v69
	v_cvt_pk_bf16_f32 v69, v70, v71
	v_cvt_pk_bf16_f32 v70, v64, v65
	v_cvt_pk_bf16_f32 v71, v66, v67
	buffer_store_dwordx4 v[68:71], v159, s[12:15], 0 offen offset:256
	s_waitcnt vmcnt(14)
; __device__ __forceinline__ unsigned cvt_pk_bf16(float lo, float hi) { f32x2_t v = {lo, hi}; bf16x2_t b = __builtin_convertvector(v, bf16x2_t); return __builtin_bit_cast(unsigned, b); }
;     __device__ __forceinline__ void operator()(const f32x4 (&acc)[2][2][4][2], const Unit& u, int wr, int wc, int fr, int fq) const {
;     ...
;             for (int m = 0; m < 4; ++m) { const int row = u.pm * BM + ai * HALF + wr * 64 + m * 16 + fr; const size_t off = (size_t)row * ldc + col0; float ss = 0.f;
; #pragma unroll
;                 for (int bj = 0; bj < 2; ++bj) { const size_t o2 = off + bj * HALF; f32x4 b0, b1;
;                     if (MODE == 0) { b0 = *(const f32x4*)(basef + o2); b1 = *(const f32x4*)(basef + o2 + 4); }
;                     else { const u32x4 w = *(const u32x4*)(xb + o2);
;                         b0 = (f32x4){__uint_as_float(w.x << 16), __uint_as_float(w.x & 0xffff0000u), __uint_as_float(w.y << 16), __uint_as_float(w.y & 0xffff0000u)};
;                         b1 = (f32x4){__uint_as_float(w.z << 16), __uint_as_float(w.z & 0xffff0000u), __uint_as_float(w.w << 16), __uint_as_float(w.w & 0xffff0000u)}; }
;                     const f32x4 v0 = b0 + acc[ai][bj][m][0], v1 = b1 + acc[ai][bj][m][1];
;                     if (MODE == 2) { *(f32x4*)(outf + o2) = v0; *(f32x4*)(outf + o2 + 4) = v1; }
;                     else { ss += (v0[0] * v0[0] + v0[1] * v0[1]) + (v0[2] * v0[2] + v0[3] * v0[3]) + (v1[0] * v1[0] + v1[1] * v1[1]) + (v1[2] * v1[2] + v1[3] * v1[3]);
;                         u32x4 w; w.x = cvt_pk_bf16(v0[0], v0[1]); w.y = cvt_pk_bf16(v0[2], v0[3]); w.z = cvt_pk_bf16(v1[0], v1[1]); w.w = cvt_pk_bf16(v1[2], v1[3]);
;                         __builtin_amdgcn_raw_buffer_store_b128(w, rsrc, (unsigned)(o2 * 2), 0, 16); } }
;                 if (MODE != 2) { ss += __shfl_xor(ss, 16); ss += __shfl_xor(ss, 32); if (fq == 0) atomicAdd(rowsq + row, ss); } }
	v_lshlrev_b32_e32 v224, 16, v192
	v_and_b32_e32 v225, 0xffff0000, v192
	v_lshlrev_b32_e32 v226, 16, v193
	v_and_b32_e32 v227, 0xffff0000, v193
	v_lshlrev_b32_e32 v228, 16, v194
	v_and_b32_e32 v229, 0xffff0000, v194
	v_lshlrev_b32_e32 v230, 16, v195
	v_and_b32_e32 v231, 0xffff0000, v195
	v_pk_add_f32 v[60:61], v[60:61], v[224:225]
	v_pk_add_f32 v[62:63], v[62:63], v[226:227]
	v_pk_add_f32 v[56:57], v[56:57], v[228:229]
	v_pk_add_f32 v[58:59], v[58:59], v[230:231]
	v_mul_f32_e32 v236, v60, v60
	v_fmac_f32_e32 v236, v61, v61
	v_fmac_f32_e32 v236, v62, v62
	v_fmac_f32_e32 v236, v63, v63
	v_fmac_f32_e32 v236, v56, v56
	v_fmac_f32_e32 v236, v57, v57
	v_fmac_f32_e32 v236, v58, v58
	v_fmac_f32_e32 v236, v59, v59
	v_cvt_pk_bf16_f32 v60, v60, v61
	v_cvt_pk_bf16_f32 v61, v62, v63
	v_cvt_pk_bf16_f32 v62, v56, v57
	v_cvt_pk_bf16_f32 v63, v58, v59
	buffer_store_dwordx4 v[60:63], v146, s[12:15], 0 offen
	v_lshlrev_b32_e32 v224, 16, v196
	v_and_b32_e32 v225, 0xffff0000, v196
	v_lshlrev_b32_e32 v226, 16, v197
	v_and_b32_e32 v227, 0xffff0000, v197
	v_lshlrev_b32_e32 v228, 16, v198
	v_and_b32_e32 v229, 0xffff0000, v198
	v_lshlrev_b32_e32 v230, 16, v199
	v_and_b32_e32 v231, 0xffff0000, v199
	v_pk_add_f32 v[52:53], v[52:53], v[224:225]
	v_pk_add_f32 v[54:55], v[54:55], v[226:227]
	v_pk_add_f32 v[48:49], v[48:49], v[228:229]
	v_pk_add_f32 v[50:51], v[50:51], v[230:231]
	v_fmac_f32_e32 v236, v52, v52
	v_fmac_f32_e32 v236, v53, v53
	v_fmac_f32_e32 v236, v54, v54
	v_fmac_f32_e32 v236, v55, v55
	v_fmac_f32_e32 v236, v48, v48
	v_fmac_f32_e32 v236, v49, v49
	v_fmac_f32_e32 v236, v50, v50
	v_fmac_f32_e32 v236, v51, v51
	v_cvt_pk_bf16_f32 v52, v52, v53
	v_cvt_pk_bf16_f32 v53, v54, v55
	v_cvt_pk_bf16_f32 v54, v48, v49
	v_cvt_pk_bf16_f32 v55, v50, v51
	buffer_store_dwordx4 v[52:55], v146, s[12:15], 0 offen offset:256
	s_waitcnt vmcnt(14)
	v_lshlrev_b32_e32 v224, 16, v200
	v_and_b32_e32 v225, 0xffff0000, v200
	v_lshlrev_b32_e32 v226, 16, v201
	v_and_b32_e32 v227, 0xffff0000, v201
	v_lshlrev_b32_e32 v228, 16, v202
	v_and_b32_e32 v229, 0xffff0000, v202
	v_lshlrev_b32_e32 v230, 16, v203
	v_and_b32_e32 v231, 0xffff0000, v203
	v_pk_add_f32 v[44:45], v[44:45], v[224:225]
	v_pk_add_f32 v[46:47], v[46:47], v[226:227]
	v_pk_add_f32 v[40:41], v[40:41], v[228:229]
	v_pk_add_f32 v[42:43], v[42:43], v[230:231]
	v_mul_f32_e32 v237, v44, v44
	v_fmac_f32_e32 v237, v45, v45
	v_fmac_f32_e32 v237, v46, v46
	v_fmac_f32_e32 v237, v47, v47
	v_fmac_f32_e32 v237, v40, v40
	v_fmac_f32_e32 v237, v41, v41
	v_fmac_f32_e32 v237, v42, v42
	v_fmac_f32_e32 v237, v43, v43
	v_cvt_pk_bf16_f32 v44, v44, v45
	v_cvt_pk_bf16_f32 v45, v46, v47
	v_cvt_pk_bf16_f32 v46, v40, v41
	v_cvt_pk_bf16_f32 v47, v42, v43
	buffer_store_dwordx4 v[44:47], v147, s[12:15], 0 offen
	v_lshlrev_b32_e32 v224, 16, v204
	v_and_b32_e32 v225, 0xffff0000, v204
	v_lshlrev_b32_e32 v226, 16, v205
	v_and_b32_e32 v227, 0xffff0000, v205
	v_lshlrev_b32_e32 v228, 16, v206
	v_and_b32_e32 v229, 0xffff0000, v206
	v_lshlrev_b32_e32 v230, 16, v207
	v_and_b32_e32 v231, 0xffff0000, v207
	v_pk_add_f32 v[36:37], v[36:37], v[224:225]
	v_pk_add_f32 v[38:39], v[38:39], v[226:227]
	v_pk_add_f32 v[32:33], v[32:33], v[228:229]
	v_pk_add_f32 v[34:35], v[34:35], v[230:231]
	v_fmac_f32_e32 v237, v36, v36
	v_fmac_f32_e32 v237, v37, v37
	v_fmac_f32_e32 v237, v38, v38
	v_fmac_f32_e32 v237, v39, v39
	v_fmac_f32_e32 v237, v32, v32
	v_fmac_f32_e32 v237, v33, v33
	v_fmac_f32_e32 v237, v34, v34
	v_fmac_f32_e32 v237, v35, v35
	v_cvt_pk_bf16_f32 v36, v36, v37
	v_cvt_pk_bf16_f32 v37, v38, v39
	v_cvt_pk_bf16_f32 v38, v32, v33
	v_cvt_pk_bf16_f32 v39, v34, v35
	buffer_store_dwordx4 v[36:39], v147, s[12:15], 0 offen offset:256
	s_waitcnt vmcnt(14)
; __device__ __forceinline__ unsigned cvt_pk_bf16(float lo, float hi) { f32x2_t v = {lo, hi}; bf16x2_t b = __builtin_convertvector(v, bf16x2_t); return __builtin_bit_cast(unsigned, b); }
;     __device__ __forceinline__ void operator()(const f32x4 (&acc)[2][2][4][2], const Unit& u, int wr, int wc, int fr, int fq) const {
;     ...
;             for (int m = 0; m < 4; ++m) { const int row = u.pm * BM + ai * HALF + wr * 64 + m * 16 + fr; const size_t off = (size_t)row * ldc + col0; float ss = 0.f;
; #pragma unroll
;                 for (int bj = 0; bj < 2; ++bj) { const size_t o2 = off + bj * HALF; f32x4 b0, b1;
;                     if (MODE == 0) { b0 = *(const f32x4*)(basef + o2); b1 = *(const f32x4*)(basef + o2 + 4); }
;                     else { const u32x4 w = *(const u32x4*)(xb + o2);
;                         b0 = (f32x4){__uint_as_float(w.x << 16), __uint_as_float(w.x & 0xffff0000u), __uint_as_float(w.y << 16), __uint_as_float(w.y & 0xffff0000u)};
;                         b1 = (f32x4){__uint_as_float(w.z << 16), __uint_as_float(w.z & 0xffff0000u), __uint_as_float(w.w << 16), __uint_as_float(w.w & 0xffff0000u)}; }
;                     const f32x4 v0 = b0 + acc[ai][bj][m][0], v1 = b1 + acc[ai][bj][m][1];
;                     if (MODE == 2) { *(f32x4*)(outf + o2) = v0; *(f32x4*)(outf + o2 + 4) = v1; }
;                     else { ss += (v0[0] * v0[0] + v0[1] * v0[1]) + (v0[2] * v0[2] + v0[3] * v0[3]) + (v1[0] * v1[0] + v1[1] * v1[1]) + (v1[2] * v1[2] + v1[3] * v1[3]);
;                         u32x4 w; w.x = cvt_pk_bf16(v0[0], v0[1]); w.y = cvt_pk_bf16(v0[2], v0[3]); w.z = cvt_pk_bf16(v1[0], v1[1]); w.w = cvt_pk_bf16(v1[2], v1[3]);
;                         __builtin_amdgcn_raw_buffer_store_b128(w, rsrc, (unsigned)(o2 * 2), 0, 16); } }
;                 if (MODE != 2) { ss += __shfl_xor(ss, 16); ss += __shfl_xor(ss, 32); if (fq == 0) atomicAdd(rowsq + row, ss); } }
	v_lshlrev_b32_e32 v224, 16, v208
	v_and_b32_e32 v225, 0xffff0000, v208
	v_lshlrev_b32_e32 v226, 16, v209
	v_and_b32_e32 v227, 0xffff0000, v209
	v_lshlrev_b32_e32 v228, 16, v210
	v_and_b32_e32 v229, 0xffff0000, v210
	v_lshlrev_b32_e32 v230, 16, v211
	v_and_b32_e32 v231, 0xffff0000, v211
	v_pk_add_f32 v[28:29], v[28:29], v[224:225]
	v_pk_add_f32 v[30:31], v[30:31], v[226:227]
	v_pk_add_f32 v[24:25], v[24:25], v[228:229]
	v_pk_add_f32 v[26:27], v[26:27], v[230:231]
	v_mul_f32_e32 v238, v28, v28
	v_fmac_f32_e32 v238, v29, v29
	v_fmac_f32_e32 v238, v30, v30
	v_fmac_f32_e32 v238, v31, v31
	v_fmac_f32_e32 v238, v24, v24
	v_fmac_f32_e32 v238, v25, v25
	v_fmac_f32_e32 v238, v26, v26
	v_fmac_f32_e32 v238, v27, v27
	v_cvt_pk_bf16_f32 v28, v28, v29
	v_cvt_pk_bf16_f32 v29, v30, v31
	v_cvt_pk_bf16_f32 v30, v24, v25
	v_cvt_pk_bf16_f32 v31, v26, v27
	buffer_store_dwordx4 v[28:31], v148, s[12:15], 0 offen
	v_lshlrev_b32_e32 v224, 16, v212
	v_and_b32_e32 v225, 0xffff0000, v212
	v_lshlrev_b32_e32 v226, 16, v213
	v_and_b32_e32 v227, 0xffff0000, v213
	v_lshlrev_b32_e32 v228, 16, v214
	v_and_b32_e32 v229, 0xffff0000, v214
	v_lshlrev_b32_e32 v230, 16, v215
	v_and_b32_e32 v231, 0xffff0000, v215
	v_pk_add_f32 v[20:21], v[20:21], v[224:225]
	v_pk_add_f32 v[22:23], v[22:23], v[226:227]
	v_pk_add_f32 v[16:17], v[16:17], v[228:229]
	v_pk_add_f32 v[18:19], v[18:19], v[230:231]
	v_fmac_f32_e32 v238, v20, v20
	v_fmac_f32_e32 v238, v21, v21
	v_fmac_f32_e32 v238, v22, v22
	v_fmac_f32_e32 v238, v23, v23
	v_fmac_f32_e32 v238, v16, v16
	v_fmac_f32_e32 v238, v17, v17
	v_fmac_f32_e32 v238, v18, v18
	v_fmac_f32_e32 v238, v19, v19
	v_cvt_pk_bf16_f32 v20, v20, v21
	v_cvt_pk_bf16_f32 v21, v22, v23
	v_cvt_pk_bf16_f32 v22, v16, v17
	v_cvt_pk_bf16_f32 v23, v18, v19
	buffer_store_dwordx4 v[20:23], v148, s[12:15], 0 offen offset:256
	s_waitcnt vmcnt(14)
	v_lshlrev_b32_e32 v224, 16, v216
	v_and_b32_e32 v225, 0xffff0000, v216
	v_lshlrev_b32_e32 v226, 16, v217
	v_and_b32_e32 v227, 0xffff0000, v217
	v_lshlrev_b32_e32 v228, 16, v218
	v_and_b32_e32 v229, 0xffff0000, v218
	v_lshlrev_b32_e32 v230, 16, v219
	v_and_b32_e32 v231, 0xffff0000, v219
	v_pk_add_f32 v[12:13], v[12:13], v[224:225]
	v_pk_add_f32 v[14:15], v[14:15], v[226:227]
	v_pk_add_f32 v[8:9], v[8:9], v[228:229]
	v_pk_add_f32 v[10:11], v[10:11], v[230:231]
	v_mul_f32_e32 v239, v12, v12
	v_fmac_f32_e32 v239, v13, v13
	v_fmac_f32_e32 v239, v14, v14
	v_fmac_f32_e32 v239, v15, v15
	v_fmac_f32_e32 v239, v8, v8
	v_fmac_f32_e32 v239, v9, v9
	v_fmac_f32_e32 v239, v10, v10
	v_fmac_f32_e32 v239, v11, v11
	v_cvt_pk_bf16_f32 v12, v12, v13
	v_cvt_pk_bf16_f32 v13, v14, v15
	v_cvt_pk_bf16_f32 v14, v8, v9
	v_cvt_pk_bf16_f32 v15, v10, v11
	buffer_store_dwordx4 v[12:15], v149, s[12:15], 0 offen
	v_lshlrev_b32_e32 v224, 16, v220
	v_and_b32_e32 v225, 0xffff0000, v220
	v_lshlrev_b32_e32 v226, 16, v221
	v_and_b32_e32 v227, 0xffff0000, v221
	v_lshlrev_b32_e32 v228, 16, v222
	v_and_b32_e32 v229, 0xffff0000, v222
	v_lshlrev_b32_e32 v230, 16, v223
	v_and_b32_e32 v231, 0xffff0000, v223
	v_pk_add_f32 v[4:5], v[4:5], v[224:225]
	v_pk_add_f32 v[6:7], v[6:7], v[226:227]
	v_pk_add_f32 v[0:1], v[0:1], v[228:229]
	v_pk_add_f32 v[2:3], v[2:3], v[230:231]
	v_fmac_f32_e32 v239, v4, v4
	v_fmac_f32_e32 v239, v5, v5
	v_fmac_f32_e32 v239, v6, v6
	v_fmac_f32_e32 v239, v7, v7
	v_fmac_f32_e32 v239, v0, v0
	v_fmac_f32_e32 v239, v1, v1
	v_fmac_f32_e32 v239, v2, v2
	v_fmac_f32_e32 v239, v3, v3
	v_cvt_pk_bf16_f32 v4, v4, v5
	v_cvt_pk_bf16_f32 v5, v6, v7
	v_cvt_pk_bf16_f32 v6, v0, v1
	v_cvt_pk_bf16_f32 v7, v2, v3
	buffer_store_dwordx4 v[4:7], v149, s[12:15], 0 offen offset:256
	ds_bpermute_b32 v240, v248, v232
	ds_bpermute_b32 v241, v248, v233
	ds_bpermute_b32 v242, v248, v234
	ds_bpermute_b32 v243, v248, v235
	ds_bpermute_b32 v244, v248, v236
	ds_bpermute_b32 v245, v248, v237
	ds_bpermute_b32 v246, v248, v238
	ds_bpermute_b32 v247, v248, v239
	s_waitcnt lgkmcnt(0)
	v_add_f32_e32 v232, v232, v240
	v_add_f32_e32 v233, v233, v241
	v_add_f32_e32 v234, v234, v242
	v_add_f32_e32 v235, v235, v243
	v_add_f32_e32 v236, v236, v244
	v_add_f32_e32 v237, v237, v245
	v_add_f32_e32 v238, v238, v246
	v_add_f32_e32 v239, v239, v247
	ds_bpermute_b32 v240, v249, v232
	ds_bpermute_b32 v241, v249, v233
	ds_bpermute_b32 v242, v249, v234
	ds_bpermute_b32 v243, v249, v235
	ds_bpermute_b32 v244, v249, v236
	ds_bpermute_b32 v245, v249, v237
	ds_bpermute_b32 v246, v249, v238
	ds_bpermute_b32 v247, v249, v239
	v_lshl_add_u32 v224, s40, 8, v129
	v_ashrrev_i32_e32 v225, 31, v224
	v_lshl_add_u64 v[224:225], v[224:225], 2, s[10:11]
	s_waitcnt lgkmcnt(0)
	v_add_f32_e32 v232, v232, v240
	v_add_f32_e32 v233, v233, v241
	v_add_f32_e32 v234, v234, v242
	v_add_f32_e32 v235, v235, v243
	v_add_f32_e32 v236, v236, v244
	v_add_f32_e32 v237, v237, v245
	v_add_f32_e32 v238, v238, v246
	v_add_f32_e32 v239, v239, v247
	s_and_saveexec_b64 s[40:41], s[6:7]
	global_atomic_add_f32 v[224:225], v232, off
	global_atomic_add_f32 v[224:225], v233, off offset:64
	global_atomic_add_f32 v[224:225], v234, off offset:128
	global_atomic_add_f32 v[224:225], v235, off offset:192
	global_atomic_add_f32 v[224:225], v236, off offset:512
	global_atomic_add_f32 v[224:225], v237, off offset:576
	global_atomic_add_f32 v[224:225], v238, off offset:640
	global_atomic_add_f32 v[224:225], v239, off offset:704
	s_or_b64 exec, exec, s[40:41]
